# scanner: v pairs of two steps fetched by one 16-byte LDS read (paired table layout), wait states that only separated plain dependent VALU ops removed
# speedup vs baseline: 1.0071x; 1.0071x over previous
;     __device__ __forceinline__ bf16* R(int i) const { return (bf16*)(ws + OFF_R0 + (size_t)i * RSZ); }
; __device__ __forceinline__ void phase_rwkv_scan(const Fr& F, int jr) {
;     ...
;     const int lane = F.lane, wave = F.wave, tid = F.tid, l15 = lane & 15, lq = lane >> 4;
;     const int bxs = (int)blockIdx.x, bxcd = (gridDim.x == 256) ? (bxs & 7) * 32 + (bxs >> 3) : bxs;
;     for (int task = bxcd; task < 256; task += gridDim.x) {
;         const int half = task & 1, h = (task >> 1) & 15, b = (task >> 5) & 3, s = task >> 7;
;         bf16* Yb = F.R(s);
;         const float* w0 = F.a->in[9] + (size_t)(jr * 2 + s) * D + h * 64; const float* a0 = F.a->in[12] + (size_t)(jr * 2 + s) * D + h * 64;
;         const float* kkw = F.a->in[15] + (size_t)jr * D + h * 64; const float* kaw = F.a->in[16] + (size_t)jr * D + h * 64;
;         f32x2 S01 = {0.f, 0.f}, S23 = {0.f, 0.f};
;         const int ks = 4 * l15, rloc = 4 * wave + lq;
;         const int pt = wave & 3, ht0 = (wave >> 2) * 2;
;         const int p1 = pt * 16 + l15;
;         const int p2 = tid >> 3, j8 = tid & 7, hk0 = 8 * j8;
.LBB0_552:
	s_or_b64 exec, exec, s[6:7]
	v_cmp_gt_i32_e32 vcc, 6, v1
	v_cmp_lt_i32_e64 s[6:7], 5, v2
	s_and_b64 s[6:7], vcc, s[6:7]
	s_and_saveexec_b64 s[12:13], s[6:7]
	s_cbranch_execz .LBB0_565
	s_and_b32 s3, s2, 7
	s_lshl_b32 s3, s3, 5
	s_lshr_b32 s6, s2, 3
	s_add_i32 s3, s3, s6
	s_lshr_b32 s6, s3, 7
	s_bfe_u32 s7, s3, 0x20005
	s_bfe_u32 s8, s3, 0x40001
	s_and_b32 s9, s3, 1
	s_cmp_gt_u32 s68, 3
	s_cbranch_scc1 .Lrw0_helper
	s_setprio 3
	v_mov_b32_e32 v206, 0
	v_mov_b32_e32 v207, 0
	v_mov_b32_e32 v208, 0
	v_mov_b32_e32 v209, 0
	v_mov_b32_e32 v210, 0
	v_mov_b32_e32 v211, 0
	v_mov_b32_e32 v212, 0
	v_mov_b32_e32 v213, 0
	v_and_b32_e32 v243, 15, v130
	v_lshlrev_b32_e32 v214, 4, v243
	v_lshrrev_b32_e32 v244, 4, v130
	v_lshrrev_b32_e32 v245, 3, v243
	v_lshl_add_u32 v245, v244, 1, v245
	s_lshl_b32 s16, s68, 3
	v_add_u32_e32 v245, s16, v245
	v_lshlrev_b32_e32 v216, 4, v245
	s_mul_i32 s16, s68, 0x2400
	s_add_i32 s16, s16, 0x19800
	s_cmp_eq_u32 s68, 3
	s_cselect_b32 s16, 0x20800, s16
	v_mul_u32_u24_e32 v218, 0x90, v130
	v_add_u32_e32 v218, s16, v218
	v_mul_u32_u24_e32 v244, 0x90, v244
	v_lshl_add_u32 v244, v243, 3, v244
	v_add_u32_e32 v217, s16, v244
	v_lshrrev_b32_e32 v219, 2, v130
	s_cmp_eq_u32 s6, 0
	s_cbranch_scc1 .Lrw0_sdir0
	v_sub_u32_e32 v219, 0, v219

; template <int CTRL> __device__ __forceinline__ float dppf(float x) { return __builtin_bit_cast(float, __builtin_amdgcn_update_dpp(0, __builtin_bit_cast(int, x), CTRL, 0xF, 0xF, false)); }
; __device__ __forceinline__ void phase_rwkv_scan(const Fr& F, int jr) {
;     ...
;                 f32x4 w4 = PW[0], k4 = PW[1024], b4 = PW[2048], d4 = PW[3072], r4 = PR[0];
;                 float vv = PV[0];
;                 for (int pg = 0; pg < 64; pg += 16) {
; #pragma unroll
;                     for (int pi = 0; pi < 16; ++pi) {
;                         const int p = pg + pi, pn = p < 63 ? p + 1 : 63;
;                         const f32x4 w4n = PW[pn * 16], k4n = PW[1024 + pn * 16], b4n = PW[2048 + pn * 16], d4n = PW[3072 + pn * 16], r4n = PR[pn * 16];
;                         const float vvn = PV[pn * 32];
;                         f32x2 t = S01 * k4.xy; t = S23 * k4.zw + t; float sa = t.x + t.y;
;                         sa += dppf<0x128>(sa);
;                         const f32x2 dv01 = d4.xy * vv, dv23 = d4.zw * vv;
;                         sa += dppf<0x124>(sa);
;                         const f32x2 e01 = S01 * w4.xy + dv01;
;                         sa += dppf<0x122>(sa);
;                         const f32x2 e23 = S23 * w4.zw + dv23;
;                         sa += dppf<0x121>(sa);
;                         S01 = e01 - b4.xy * sa; S23 = e23 - b4.zw * sa;
;                         f32x2 u = S01 * r4.xy; u = S23 * r4.zw + u;
;                         PY[pi * 64] = u.x + u.y;
;                         w4 = w4n; k4 = k4n; b4 = b4n; d4 = d4n; r4 = r4n; vv = vvn;
;                     }
.Lrw0_shc:
	v_add_u32_e32 v240, s11, v214
	v_add_u32_e32 v242, s11, v216
	ds_read_b128 v[84:87], v240 offset:8704
	ds_read_b128 v[56:59], v242 offset:43520
	ds_read_b128 v[92:95], v240 offset:26112
	ds_read_b128 v[80:83], v240 offset:0
	ds_read_b128 v[88:91], v240 offset:17408
	ds_read_b128 v[96:99], v240 offset:34816
	ds_read_b128 v[106:109], v240 offset:8976
	ds_read_b128 v[114:117], v240 offset:26384
	ds_read_b128 v[102:105], v240 offset:272
	ds_read_b128 v[110:113], v240 offset:17680
	s_lshl_b32 s17, s10, 5
	s_cmp_lt_u32 s10, 8
	s_movk_i32 s18, 0x11ff
	s_cselect_b32 s18, 0xff, s18
	s_sub_i32 s18, s18, s17
	s_cmp_eq_u32 s6, 0
	s_cselect_b32 s15, s17, s18
	s_cselect_b32 s19, 16, -16
	s_waitcnt lgkmcnt(5)
	ds_read_b128 v[4:7], v240 offset:9248
	ds_read_b128 v[60:63], v242 offset:44048
	ds_read_b128 v[12:15], v240 offset:26656
	ds_read_b128 v[0:3], v240 offset:544
	ds_read_b128 v[8:11], v240 offset:17952
	v_pk_mul_f32 v[226:227], v[206:207], v[84:85] op_sel_hi:[1,0]
	v_pk_mul_f32 v[232:233], v[56:57], v[92:93] op_sel_hi:[1,0]
	v_pk_fma_f32 v[226:227], v[208:209], v[84:85], v[226:227] op_sel:[0,1,0]
	v_pk_mul_f32 v[234:235], v[56:57], v[92:93] op_sel:[0,1]
	v_pk_fma_f32 v[226:227], v[210:211], v[86:87], v[226:227] op_sel_hi:[1,0,1]
	v_pk_mul_f32 v[236:237], v[56:57], v[94:95] op_sel_hi:[1,0]
	v_pk_fma_f32 v[226:227], v[212:213], v[86:87], v[226:227] op_sel:[0,1,0]
	v_pk_mul_f32 v[238:239], v[56:57], v[94:95] op_sel:[0,1]
	s_nop 0
	v_add_f32_dpp v230, v227, v226 row_ror:8 row_mask:0xf bank_mask:0xf
	v_pk_fma_f32 v[232:233], v[206:207], v[80:81], v[232:233] op_sel_hi:[1,0,1]
	v_pk_fma_f32 v[234:235], v[208:209], v[80:81], v[234:235] op_sel:[0,1,0]
	v_add_f32_dpp v230, v230, v230 quad_perm:[1,0,3,2] row_mask:0xf bank_mask:0xf
	v_pk_fma_f32 v[236:237], v[210:211], v[82:83], v[236:237] op_sel_hi:[1,0,1]
	v_pk_fma_f32 v[238:239], v[212:213], v[82:83], v[238:239] op_sel:[0,1,0]
	v_add_f32_dpp v230, v230, v230 quad_perm:[2,3,0,1] row_mask:0xf bank_mask:0xf
	ds_read_b128 v[222:225], v240 offset:35088
	s_nop 0
	v_add_f32_dpp v230, v230, v230 row_half_mirror row_mask:0xf bank_mask:0xf
	s_nop 1
	v_mov_b32_dpp v231, v230 row_ror:8 row_mask:0xf bank_mask:0xf
	v_pk_fma_f32 v[206:207], v[88:89], v[230:231], v[232:233] op_sel_hi:[0,1,1] neg_lo:[1,0,0] neg_hi:[1,0,0]
	v_pk_fma_f32 v[208:209], v[88:89], v[230:231], v[234:235] op_sel:[1,0,0] neg_lo:[1,0,0] neg_hi:[1,0,0]
	v_pk_fma_f32 v[210:211], v[90:91], v[230:231], v[236:237] op_sel_hi:[0,1,1] neg_lo:[1,0,0] neg_hi:[1,0,0]
	v_pk_fma_f32 v[212:213], v[90:91], v[230:231], v[238:239] op_sel:[1,0,0] neg_lo:[1,0,0] neg_hi:[1,0,0]
	s_waitcnt lgkmcnt(6)
	ds_read_b128 v[84:87], v240 offset:9520
	ds_read_b128 v[92:95], v240 offset:26928
	ds_read_b128 v[80:83], v240 offset:816
	ds_read_b128 v[88:91], v240 offset:18224
	v_pk_mul_f32 v[226:227], v[206:207], v[106:107] op_sel_hi:[1,0]
	v_pk_mul_f32 v[228:229], v[206:207], v[96:97] op_sel_hi:[1,0]
	v_pk_fma_f32 v[226:227], v[208:209], v[106:107], v[226:227] op_sel:[0,1,0]
	v_pk_fma_f32 v[228:229], v[208:209], v[96:97], v[228:229] op_sel:[0,1,0]
	v_pk_fma_f32 v[226:227], v[210:211], v[108:109], v[226:227] op_sel_hi:[1,0,1]
	v_pk_fma_f32 v[228:229], v[210:211], v[98:99], v[228:229] op_sel_hi:[1,0,1]
	v_pk_fma_f32 v[226:227], v[212:213], v[108:109], v[226:227] op_sel:[0,1,0]
	v_pk_fma_f32 v[228:229], v[212:213], v[98:99], v[228:229] op_sel:[0,1,0]
	v_pk_mul_f32 v[232:233], v[58:59], v[114:115] op_sel_hi:[1,0]
	v_add_f32_dpp v230, v227, v226 row_ror:8 row_mask:0xf bank_mask:0xf
	v_pk_mul_f32 v[234:235], v[58:59], v[114:115] op_sel:[0,1]
	v_pk_mul_f32 v[236:237], v[58:59], v[116:117] op_sel_hi:[1,0]
	v_add_f32_dpp v230, v230, v230 quad_perm:[1,0,3,2] row_mask:0xf bank_mask:0xf
	v_pk_mul_f32 v[238:239], v[58:59], v[116:117] op_sel:[0,1]
	ds_read_b128 v[96:99], v240 offset:35360
	v_add_f32_dpp v230, v230, v230 quad_perm:[2,3,0,1] row_mask:0xf bank_mask:0xf
	v_pk_fma_f32 v[232:233], v[206:207], v[102:103], v[232:233] op_sel_hi:[1,0,1]
	v_pk_fma_f32 v[234:235], v[208:209], v[102:103], v[234:235] op_sel:[0,1,0]
	v_add_f32_dpp v230, v230, v230 row_half_mirror row_mask:0xf bank_mask:0xf
	v_pk_fma_f32 v[236:237], v[210:211], v[104:105], v[236:237] op_sel_hi:[1,0,1]
	v_pk_fma_f32 v[238:239], v[212:213], v[104:105], v[238:239] op_sel:[0,1,0]
	v_mov_b32_dpp v231, v230 row_ror:8 row_mask:0xf bank_mask:0xf
	ds_write_b64 v217, v[228:229] offset:0
	v_pk_fma_f32 v[206:207], v[110:111], v[230:231], v[232:233] op_sel_hi:[0,1,1] neg_lo:[1,0,0] neg_hi:[1,0,0]
	v_pk_fma_f32 v[208:209], v[110:111], v[230:231], v[234:235] op_sel:[1,0,0] neg_lo:[1,0,0] neg_hi:[1,0,0]
	v_pk_fma_f32 v[210:211], v[112:113], v[230:231], v[236:237] op_sel_hi:[0,1,1] neg_lo:[1,0,0] neg_hi:[1,0,0]
	v_pk_fma_f32 v[212:213], v[112:113], v[230:231], v[238:239] op_sel:[1,0,0] neg_lo:[1,0,0] neg_hi:[1,0,0]
	s_waitcnt lgkmcnt(6)
; template <int CTRL> __device__ __forceinline__ float dppf(float x) { return __builtin_bit_cast(float, __builtin_amdgcn_update_dpp(0, __builtin_bit_cast(int, x), CTRL, 0xF, 0xF, false)); }
; __device__ __forceinline__ void phase_rwkv_scan(const Fr& F, int jr) {
;     ...
;                 f32x4 w4 = PW[0], k4 = PW[1024], b4 = PW[2048], d4 = PW[3072], r4 = PR[0];
;                 float vv = PV[0];
;                 for (int pg = 0; pg < 64; pg += 16) {
; #pragma unroll
;                     for (int pi = 0; pi < 16; ++pi) {
;                         const int p = pg + pi, pn = p < 63 ? p + 1 : 63;
;                         const f32x4 w4n = PW[pn * 16], k4n = PW[1024 + pn * 16], b4n = PW[2048 + pn * 16], d4n = PW[3072 + pn * 16], r4n = PR[pn * 16];
;                         const float vvn = PV[pn * 32];
;                         f32x2 t = S01 * k4.xy; t = S23 * k4.zw + t; float sa = t.x + t.y;
;                         sa += dppf<0x128>(sa);
;                         const f32x2 dv01 = d4.xy * vv, dv23 = d4.zw * vv;
;                         sa += dppf<0x124>(sa);
;                         const f32x2 e01 = S01 * w4.xy + dv01;
;                         sa += dppf<0x122>(sa);
;                         const f32x2 e23 = S23 * w4.zw + dv23;
;                         sa += dppf<0x121>(sa);
;                         S01 = e01 - b4.xy * sa; S23 = e23 - b4.zw * sa;
;                         f32x2 u = S01 * r4.xy; u = S23 * r4.zw + u;
;                         PY[pi * 64] = u.x + u.y;
;                         w4 = w4n; k4 = k4n; b4 = b4n; d4 = d4n; r4 = r4n; vv = vvn;
;                     }
	ds_read_b128 v[106:109], v240 offset:9792
	ds_read_b128 v[56:59], v242 offset:44576
	ds_read_b128 v[114:117], v240 offset:27200
	ds_read_b128 v[102:105], v240 offset:1088
	ds_read_b128 v[110:113], v240 offset:18496
	v_pk_mul_f32 v[226:227], v[206:207], v[4:5] op_sel_hi:[1,0]
	v_pk_mul_f32 v[228:229], v[206:207], v[222:223] op_sel_hi:[1,0]
	v_pk_fma_f32 v[226:227], v[208:209], v[4:5], v[226:227] op_sel:[0,1,0]
	v_pk_fma_f32 v[228:229], v[208:209], v[222:223], v[228:229] op_sel:[0,1,0]
	v_pk_fma_f32 v[226:227], v[210:211], v[6:7], v[226:227] op_sel_hi:[1,0,1]
	v_pk_fma_f32 v[228:229], v[210:211], v[224:225], v[228:229] op_sel_hi:[1,0,1]
	v_pk_fma_f32 v[226:227], v[212:213], v[6:7], v[226:227] op_sel:[0,1,0]
	v_pk_fma_f32 v[228:229], v[212:213], v[224:225], v[228:229] op_sel:[0,1,0]
	v_pk_mul_f32 v[232:233], v[60:61], v[12:13] op_sel_hi:[1,0]
	v_add_f32_dpp v230, v227, v226 row_ror:8 row_mask:0xf bank_mask:0xf
	v_pk_mul_f32 v[234:235], v[60:61], v[12:13] op_sel:[0,1]
	v_pk_mul_f32 v[236:237], v[60:61], v[14:15] op_sel_hi:[1,0]
	v_add_f32_dpp v230, v230, v230 quad_perm:[1,0,3,2] row_mask:0xf bank_mask:0xf
	v_pk_mul_f32 v[238:239], v[60:61], v[14:15] op_sel:[0,1]
	ds_read_b128 v[222:225], v240 offset:35632
	v_add_f32_dpp v230, v230, v230 quad_perm:[2,3,0,1] row_mask:0xf bank_mask:0xf
	v_pk_fma_f32 v[232:233], v[206:207], v[0:1], v[232:233] op_sel_hi:[1,0,1]
	v_pk_fma_f32 v[234:235], v[208:209], v[0:1], v[234:235] op_sel:[0,1,0]
	v_add_f32_dpp v230, v230, v230 row_half_mirror row_mask:0xf bank_mask:0xf
	v_pk_fma_f32 v[236:237], v[210:211], v[2:3], v[236:237] op_sel_hi:[1,0,1]
	v_pk_fma_f32 v[238:239], v[212:213], v[2:3], v[238:239] op_sel:[0,1,0]
	v_mov_b32_dpp v231, v230 row_ror:8 row_mask:0xf bank_mask:0xf
	ds_write_b64 v217, v[228:229] offset:576
	v_pk_fma_f32 v[206:207], v[8:9], v[230:231], v[232:233] op_sel_hi:[0,1,1] neg_lo:[1,0,0] neg_hi:[1,0,0]
	v_pk_fma_f32 v[208:209], v[8:9], v[230:231], v[234:235] op_sel:[1,0,0] neg_lo:[1,0,0] neg_hi:[1,0,0]
	v_pk_fma_f32 v[210:211], v[10:11], v[230:231], v[236:237] op_sel_hi:[0,1,1] neg_lo:[1,0,0] neg_hi:[1,0,0]
	v_pk_fma_f32 v[212:213], v[10:11], v[230:231], v[238:239] op_sel:[1,0,0] neg_lo:[1,0,0] neg_hi:[1,0,0]
	s_waitcnt lgkmcnt(8)
	ds_read_b128 v[4:7], v240 offset:10064
	ds_read_b128 v[12:15], v240 offset:27472
	ds_read_b128 v[0:3], v240 offset:1360
	ds_read_b128 v[8:11], v240 offset:18768
	v_pk_mul_f32 v[226:227], v[206:207], v[84:85] op_sel_hi:[1,0]
	v_pk_mul_f32 v[228:229], v[206:207], v[96:97] op_sel_hi:[1,0]
	v_pk_fma_f32 v[226:227], v[208:209], v[84:85], v[226:227] op_sel:[0,1,0]
	v_pk_fma_f32 v[228:229], v[208:209], v[96:97], v[228:229] op_sel:[0,1,0]
	v_pk_fma_f32 v[226:227], v[210:211], v[86:87], v[226:227] op_sel_hi:[1,0,1]
	v_pk_fma_f32 v[228:229], v[210:211], v[98:99], v[228:229] op_sel_hi:[1,0,1]
	v_pk_fma_f32 v[226:227], v[212:213], v[86:87], v[226:227] op_sel:[0,1,0]
	v_pk_fma_f32 v[228:229], v[212:213], v[98:99], v[228:229] op_sel:[0,1,0]
	v_pk_mul_f32 v[232:233], v[62:63], v[92:93] op_sel_hi:[1,0]
	v_add_f32_dpp v230, v227, v226 row_ror:8 row_mask:0xf bank_mask:0xf
	v_pk_mul_f32 v[234:235], v[62:63], v[92:93] op_sel:[0,1]
	v_pk_mul_f32 v[236:237], v[62:63], v[94:95] op_sel_hi:[1,0]
	v_add_f32_dpp v230, v230, v230 quad_perm:[1,0,3,2] row_mask:0xf bank_mask:0xf
	v_pk_mul_f32 v[238:239], v[62:63], v[94:95] op_sel:[0,1]
	ds_read_b128 v[96:99], v240 offset:35904
	v_add_f32_dpp v230, v230, v230 quad_perm:[2,3,0,1] row_mask:0xf bank_mask:0xf
	v_pk_fma_f32 v[232:233], v[206:207], v[80:81], v[232:233] op_sel_hi:[1,0,1]
	v_pk_fma_f32 v[234:235], v[208:209], v[80:81], v[234:235] op_sel:[0,1,0]
	v_add_f32_dpp v230, v230, v230 row_half_mirror row_mask:0xf bank_mask:0xf
	v_pk_fma_f32 v[236:237], v[210:211], v[82:83], v[236:237] op_sel_hi:[1,0,1]
	v_pk_fma_f32 v[238:239], v[212:213], v[82:83], v[238:239] op_sel:[0,1,0]
	v_mov_b32_dpp v231, v230 row_ror:8 row_mask:0xf bank_mask:0xf
	ds_write_b64 v217, v[228:229] offset:1152
	v_pk_fma_f32 v[206:207], v[88:89], v[230:231], v[232:233] op_sel_hi:[0,1,1] neg_lo:[1,0,0] neg_hi:[1,0,0]
	v_pk_fma_f32 v[208:209], v[88:89], v[230:231], v[234:235] op_sel:[1,0,0] neg_lo:[1,0,0] neg_hi:[1,0,0]
	v_pk_fma_f32 v[210:211], v[90:91], v[230:231], v[236:237] op_sel_hi:[0,1,1] neg_lo:[1,0,0] neg_hi:[1,0,0]
	v_pk_fma_f32 v[212:213], v[90:91], v[230:231], v[238:239] op_sel:[1,0,0] neg_lo:[1,0,0] neg_hi:[1,0,0]
	s_waitcnt lgkmcnt(7)
	ds_read_b128 v[84:87], v240 offset:10336
	ds_read_b128 v[60:63], v242 offset:45104
	ds_read_b128 v[92:95], v240 offset:27744
	ds_read_b128 v[80:83], v240 offset:1632
	ds_read_b128 v[88:91], v240 offset:19040
	v_pk_mul_f32 v[226:227], v[206:207], v[106:107] op_sel_hi:[1,0]
	v_pk_mul_f32 v[228:229], v[206:207], v[222:223] op_sel_hi:[1,0]
	v_pk_fma_f32 v[226:227], v[208:209], v[106:107], v[226:227] op_sel:[0,1,0]
	v_pk_fma_f32 v[228:229], v[208:209], v[222:223], v[228:229] op_sel:[0,1,0]
	v_pk_fma_f32 v[226:227], v[210:211], v[108:109], v[226:227] op_sel_hi:[1,0,1]
	v_pk_fma_f32 v[228:229], v[210:211], v[224:225], v[228:229] op_sel_hi:[1,0,1]
	v_pk_fma_f32 v[226:227], v[212:213], v[108:109], v[226:227] op_sel:[0,1,0]
	v_pk_fma_f32 v[228:229], v[212:213], v[224:225], v[228:229] op_sel:[0,1,0]
	v_pk_mul_f32 v[232:233], v[56:57], v[114:115] op_sel_hi:[1,0]
	v_add_f32_dpp v230, v227, v226 row_ror:8 row_mask:0xf bank_mask:0xf
	v_pk_mul_f32 v[234:235], v[56:57], v[114:115] op_sel:[0,1]
	v_pk_mul_f32 v[236:237], v[56:57], v[116:117] op_sel_hi:[1,0]
	v_add_f32_dpp v230, v230, v230 quad_perm:[1,0,3,2] row_mask:0xf bank_mask:0xf
	v_pk_mul_f32 v[238:239], v[56:57], v[116:117] op_sel:[0,1]
	ds_read_b128 v[222:225], v240 offset:36176
	v_add_f32_dpp v230, v230, v230 quad_perm:[2,3,0,1] row_mask:0xf bank_mask:0xf
	v_pk_fma_f32 v[232:233], v[206:207], v[102:103], v[232:233] op_sel_hi:[1,0,1]
	v_pk_fma_f32 v[234:235], v[208:209], v[102:103], v[234:235] op_sel:[0,1,0]
	v_add_f32_dpp v230, v230, v230 row_half_mirror row_mask:0xf bank_mask:0xf
	v_pk_fma_f32 v[236:237], v[210:211], v[104:105], v[236:237] op_sel_hi:[1,0,1]
	v_pk_fma_f32 v[238:239], v[212:213], v[104:105], v[238:239] op_sel:[0,1,0]
	v_mov_b32_dpp v231, v230 row_ror:8 row_mask:0xf bank_mask:0xf
	ds_write_b64 v217, v[228:229] offset:1728
	v_pk_fma_f32 v[206:207], v[110:111], v[230:231], v[232:233] op_sel_hi:[0,1,1] neg_lo:[1,0,0] neg_hi:[1,0,0]
	v_pk_fma_f32 v[208:209], v[110:111], v[230:231], v[234:235] op_sel:[1,0,0] neg_lo:[1,0,0] neg_hi:[1,0,0]
	v_pk_fma_f32 v[210:211], v[112:113], v[230:231], v[236:237] op_sel_hi:[0,1,1] neg_lo:[1,0,0] neg_hi:[1,0,0]
	v_pk_fma_f32 v[212:213], v[112:113], v[230:231], v[238:239] op_sel:[1,0,0] neg_lo:[1,0,0] neg_hi:[1,0,0]
	s_waitcnt lgkmcnt(8)
; template <int CTRL> __device__ __forceinline__ float dppf(float x) { return __builtin_bit_cast(float, __builtin_amdgcn_update_dpp(0, __builtin_bit_cast(int, x), CTRL, 0xF, 0xF, false)); }
; __device__ __forceinline__ void phase_rwkv_scan(const Fr& F, int jr) {
;     ...
;                 f32x4 w4 = PW[0], k4 = PW[1024], b4 = PW[2048], d4 = PW[3072], r4 = PR[0];
;                 float vv = PV[0];
;                 for (int pg = 0; pg < 64; pg += 16) {
; #pragma unroll
;                     for (int pi = 0; pi < 16; ++pi) {
;                         const int p = pg + pi, pn = p < 63 ? p + 1 : 63;
;                         const f32x4 w4n = PW[pn * 16], k4n = PW[1024 + pn * 16], b4n = PW[2048 + pn * 16], d4n = PW[3072 + pn * 16], r4n = PR[pn * 16];
;                         const float vvn = PV[pn * 32];
;                         f32x2 t = S01 * k4.xy; t = S23 * k4.zw + t; float sa = t.x + t.y;
;                         sa += dppf<0x128>(sa);
;                         const f32x2 dv01 = d4.xy * vv, dv23 = d4.zw * vv;
;                         sa += dppf<0x124>(sa);
;                         const f32x2 e01 = S01 * w4.xy + dv01;
;                         sa += dppf<0x122>(sa);
;                         const f32x2 e23 = S23 * w4.zw + dv23;
;                         sa += dppf<0x121>(sa);
;                         S01 = e01 - b4.xy * sa; S23 = e23 - b4.zw * sa;
;                         f32x2 u = S01 * r4.xy; u = S23 * r4.zw + u;
;                         PY[pi * 64] = u.x + u.y;
;                         w4 = w4n; k4 = k4n; b4 = b4n; d4 = d4n; r4 = r4n; vv = vvn;
;                     }
	ds_read_b128 v[106:109], v240 offset:10608
	ds_read_b128 v[114:117], v240 offset:28016
	ds_read_b128 v[102:105], v240 offset:1904
	ds_read_b128 v[110:113], v240 offset:19312
	v_pk_mul_f32 v[226:227], v[206:207], v[4:5] op_sel_hi:[1,0]
	v_pk_mul_f32 v[228:229], v[206:207], v[96:97] op_sel_hi:[1,0]
	v_pk_fma_f32 v[226:227], v[208:209], v[4:5], v[226:227] op_sel:[0,1,0]
	v_pk_fma_f32 v[228:229], v[208:209], v[96:97], v[228:229] op_sel:[0,1,0]
	v_pk_fma_f32 v[226:227], v[210:211], v[6:7], v[226:227] op_sel_hi:[1,0,1]
	v_pk_fma_f32 v[228:229], v[210:211], v[98:99], v[228:229] op_sel_hi:[1,0,1]
	v_pk_fma_f32 v[226:227], v[212:213], v[6:7], v[226:227] op_sel:[0,1,0]
	v_pk_fma_f32 v[228:229], v[212:213], v[98:99], v[228:229] op_sel:[0,1,0]
	v_pk_mul_f32 v[232:233], v[58:59], v[12:13] op_sel_hi:[1,0]
	v_add_f32_dpp v230, v227, v226 row_ror:8 row_mask:0xf bank_mask:0xf
	v_pk_mul_f32 v[234:235], v[58:59], v[12:13] op_sel:[0,1]
	v_pk_mul_f32 v[236:237], v[58:59], v[14:15] op_sel_hi:[1,0]
	v_add_f32_dpp v230, v230, v230 quad_perm:[1,0,3,2] row_mask:0xf bank_mask:0xf
	v_pk_mul_f32 v[238:239], v[58:59], v[14:15] op_sel:[0,1]
	ds_read_b128 v[96:99], v240 offset:36448
	v_add_f32_dpp v230, v230, v230 quad_perm:[2,3,0,1] row_mask:0xf bank_mask:0xf
	v_pk_fma_f32 v[232:233], v[206:207], v[0:1], v[232:233] op_sel_hi:[1,0,1]
	v_pk_fma_f32 v[234:235], v[208:209], v[0:1], v[234:235] op_sel:[0,1,0]
	v_add_f32_dpp v230, v230, v230 row_half_mirror row_mask:0xf bank_mask:0xf
	v_pk_fma_f32 v[236:237], v[210:211], v[2:3], v[236:237] op_sel_hi:[1,0,1]
	v_pk_fma_f32 v[238:239], v[212:213], v[2:3], v[238:239] op_sel:[0,1,0]
	v_mov_b32_dpp v231, v230 row_ror:8 row_mask:0xf bank_mask:0xf
	ds_write_b64 v217, v[228:229] offset:2304
	v_pk_fma_f32 v[206:207], v[8:9], v[230:231], v[232:233] op_sel_hi:[0,1,1] neg_lo:[1,0,0] neg_hi:[1,0,0]
	v_pk_fma_f32 v[208:209], v[8:9], v[230:231], v[234:235] op_sel:[1,0,0] neg_lo:[1,0,0] neg_hi:[1,0,0]
	v_pk_fma_f32 v[210:211], v[10:11], v[230:231], v[236:237] op_sel_hi:[0,1,1] neg_lo:[1,0,0] neg_hi:[1,0,0]
	v_pk_fma_f32 v[212:213], v[10:11], v[230:231], v[238:239] op_sel:[1,0,0] neg_lo:[1,0,0] neg_hi:[1,0,0]
	s_waitcnt lgkmcnt(7)
	ds_read_b128 v[4:7], v240 offset:10880
	ds_read_b128 v[56:59], v242 offset:45632
	ds_read_b128 v[12:15], v240 offset:28288
	ds_read_b128 v[0:3], v240 offset:2176
	ds_read_b128 v[8:11], v240 offset:19584
	v_pk_mul_f32 v[226:227], v[206:207], v[84:85] op_sel_hi:[1,0]
	v_pk_mul_f32 v[228:229], v[206:207], v[222:223] op_sel_hi:[1,0]
	v_pk_fma_f32 v[226:227], v[208:209], v[84:85], v[226:227] op_sel:[0,1,0]
	v_pk_fma_f32 v[228:229], v[208:209], v[222:223], v[228:229] op_sel:[0,1,0]
	v_pk_fma_f32 v[226:227], v[210:211], v[86:87], v[226:227] op_sel_hi:[1,0,1]
	v_pk_fma_f32 v[228:229], v[210:211], v[224:225], v[228:229] op_sel_hi:[1,0,1]
	v_pk_fma_f32 v[226:227], v[212:213], v[86:87], v[226:227] op_sel:[0,1,0]
	v_pk_fma_f32 v[228:229], v[212:213], v[224:225], v[228:229] op_sel:[0,1,0]
	v_pk_mul_f32 v[232:233], v[60:61], v[92:93] op_sel_hi:[1,0]
	v_add_f32_dpp v230, v227, v226 row_ror:8 row_mask:0xf bank_mask:0xf
	v_pk_mul_f32 v[234:235], v[60:61], v[92:93] op_sel:[0,1]
	v_pk_mul_f32 v[236:237], v[60:61], v[94:95] op_sel_hi:[1,0]
	v_add_f32_dpp v230, v230, v230 quad_perm:[1,0,3,2] row_mask:0xf bank_mask:0xf
	v_pk_mul_f32 v[238:239], v[60:61], v[94:95] op_sel:[0,1]
	ds_read_b128 v[222:225], v240 offset:36720
	v_add_f32_dpp v230, v230, v230 quad_perm:[2,3,0,1] row_mask:0xf bank_mask:0xf
	v_pk_fma_f32 v[232:233], v[206:207], v[80:81], v[232:233] op_sel_hi:[1,0,1]
	v_pk_fma_f32 v[234:235], v[208:209], v[80:81], v[234:235] op_sel:[0,1,0]
	v_add_f32_dpp v230, v230, v230 row_half_mirror row_mask:0xf bank_mask:0xf
	v_pk_fma_f32 v[236:237], v[210:211], v[82:83], v[236:237] op_sel_hi:[1,0,1]
	v_pk_fma_f32 v[238:239], v[212:213], v[82:83], v[238:239] op_sel:[0,1,0]
	v_mov_b32_dpp v231, v230 row_ror:8 row_mask:0xf bank_mask:0xf
	ds_write_b64 v217, v[228:229] offset:2880
	v_pk_fma_f32 v[206:207], v[88:89], v[230:231], v[232:233] op_sel_hi:[0,1,1] neg_lo:[1,0,0] neg_hi:[1,0,0]
	v_pk_fma_f32 v[208:209], v[88:89], v[230:231], v[234:235] op_sel:[1,0,0] neg_lo:[1,0,0] neg_hi:[1,0,0]
	v_pk_fma_f32 v[210:211], v[90:91], v[230:231], v[236:237] op_sel_hi:[0,1,1] neg_lo:[1,0,0] neg_hi:[1,0,0]
	v_pk_fma_f32 v[212:213], v[90:91], v[230:231], v[238:239] op_sel:[1,0,0] neg_lo:[1,0,0] neg_hi:[1,0,0]
	s_waitcnt lgkmcnt(8)
	ds_read_b128 v[84:87], v240 offset:11152
	ds_read_b128 v[92:95], v240 offset:28560
	ds_read_b128 v[80:83], v240 offset:2448
	ds_read_b128 v[88:91], v240 offset:19856
	v_pk_mul_f32 v[226:227], v[206:207], v[106:107] op_sel_hi:[1,0]
	v_pk_mul_f32 v[228:229], v[206:207], v[96:97] op_sel_hi:[1,0]
	v_pk_fma_f32 v[226:227], v[208:209], v[106:107], v[226:227] op_sel:[0,1,0]
	v_pk_fma_f32 v[228:229], v[208:209], v[96:97], v[228:229] op_sel:[0,1,0]
	v_pk_fma_f32 v[226:227], v[210:211], v[108:109], v[226:227] op_sel_hi:[1,0,1]
	v_pk_fma_f32 v[228:229], v[210:211], v[98:99], v[228:229] op_sel_hi:[1,0,1]
	v_pk_fma_f32 v[226:227], v[212:213], v[108:109], v[226:227] op_sel:[0,1,0]
	v_pk_fma_f32 v[228:229], v[212:213], v[98:99], v[228:229] op_sel:[0,1,0]
	v_pk_mul_f32 v[232:233], v[62:63], v[114:115] op_sel_hi:[1,0]
	v_add_f32_dpp v230, v227, v226 row_ror:8 row_mask:0xf bank_mask:0xf
	v_pk_mul_f32 v[234:235], v[62:63], v[114:115] op_sel:[0,1]
	v_pk_mul_f32 v[236:237], v[62:63], v[116:117] op_sel_hi:[1,0]
	v_add_f32_dpp v230, v230, v230 quad_perm:[1,0,3,2] row_mask:0xf bank_mask:0xf
	v_pk_mul_f32 v[238:239], v[62:63], v[116:117] op_sel:[0,1]
	ds_read_b128 v[96:99], v240 offset:36992
	v_add_f32_dpp v230, v230, v230 quad_perm:[2,3,0,1] row_mask:0xf bank_mask:0xf
	v_pk_fma_f32 v[232:233], v[206:207], v[102:103], v[232:233] op_sel_hi:[1,0,1]
	v_pk_fma_f32 v[234:235], v[208:209], v[102:103], v[234:235] op_sel:[0,1,0]
	v_add_f32_dpp v230, v230, v230 row_half_mirror row_mask:0xf bank_mask:0xf
	v_pk_fma_f32 v[236:237], v[210:211], v[104:105], v[236:237] op_sel_hi:[1,0,1]
	v_pk_fma_f32 v[238:239], v[212:213], v[104:105], v[238:239] op_sel:[0,1,0]
	v_mov_b32_dpp v231, v230 row_ror:8 row_mask:0xf bank_mask:0xf
	ds_write_b64 v217, v[228:229] offset:3456
	v_pk_fma_f32 v[206:207], v[110:111], v[230:231], v[232:233] op_sel_hi:[0,1,1] neg_lo:[1,0,0] neg_hi:[1,0,0]
	v_pk_fma_f32 v[208:209], v[110:111], v[230:231], v[234:235] op_sel:[1,0,0] neg_lo:[1,0,0] neg_hi:[1,0,0]
	v_pk_fma_f32 v[210:211], v[112:113], v[230:231], v[236:237] op_sel_hi:[0,1,1] neg_lo:[1,0,0] neg_hi:[1,0,0]
	v_pk_fma_f32 v[212:213], v[112:113], v[230:231], v[238:239] op_sel:[1,0,0] neg_lo:[1,0,0] neg_hi:[1,0,0]
	s_waitcnt lgkmcnt(7)
; template <int CTRL> __device__ __forceinline__ float dppf(float x) { return __builtin_bit_cast(float, __builtin_amdgcn_update_dpp(0, __builtin_bit_cast(int, x), CTRL, 0xF, 0xF, false)); }
; __device__ __forceinline__ void phase_rwkv_scan(const Fr& F, int jr) {
;     ...
;                 f32x4 w4 = PW[0], k4 = PW[1024], b4 = PW[2048], d4 = PW[3072], r4 = PR[0];
;                 float vv = PV[0];
;                 for (int pg = 0; pg < 64; pg += 16) {
; #pragma unroll
;                     for (int pi = 0; pi < 16; ++pi) {
;                         const int p = pg + pi, pn = p < 63 ? p + 1 : 63;
;                         const f32x4 w4n = PW[pn * 16], k4n = PW[1024 + pn * 16], b4n = PW[2048 + pn * 16], d4n = PW[3072 + pn * 16], r4n = PR[pn * 16];
;                         const float vvn = PV[pn * 32];
;                         f32x2 t = S01 * k4.xy; t = S23 * k4.zw + t; float sa = t.x + t.y;
;                         sa += dppf<0x128>(sa);
;                         const f32x2 dv01 = d4.xy * vv, dv23 = d4.zw * vv;
;                         sa += dppf<0x124>(sa);
;                         const f32x2 e01 = S01 * w4.xy + dv01;
;                         sa += dppf<0x122>(sa);
;                         const f32x2 e23 = S23 * w4.zw + dv23;
;                         sa += dppf<0x121>(sa);
;                         S01 = e01 - b4.xy * sa; S23 = e23 - b4.zw * sa;
;                         f32x2 u = S01 * r4.xy; u = S23 * r4.zw + u;
;                         PY[pi * 64] = u.x + u.y;
;                         w4 = w4n; k4 = k4n; b4 = b4n; d4 = d4n; r4 = r4n; vv = vvn;
;                     }
	ds_read_b128 v[106:109], v240 offset:11424
	ds_read_b128 v[60:63], v242 offset:46160
	ds_read_b128 v[114:117], v240 offset:28832
	ds_read_b128 v[102:105], v240 offset:2720
	ds_read_b128 v[110:113], v240 offset:20128
	v_pk_mul_f32 v[226:227], v[206:207], v[4:5] op_sel_hi:[1,0]
	v_pk_mul_f32 v[228:229], v[206:207], v[222:223] op_sel_hi:[1,0]
	v_pk_fma_f32 v[226:227], v[208:209], v[4:5], v[226:227] op_sel:[0,1,0]
	v_pk_fma_f32 v[228:229], v[208:209], v[222:223], v[228:229] op_sel:[0,1,0]
	v_pk_fma_f32 v[226:227], v[210:211], v[6:7], v[226:227] op_sel_hi:[1,0,1]
	v_pk_fma_f32 v[228:229], v[210:211], v[224:225], v[228:229] op_sel_hi:[1,0,1]
	v_pk_fma_f32 v[226:227], v[212:213], v[6:7], v[226:227] op_sel:[0,1,0]
	v_pk_fma_f32 v[228:229], v[212:213], v[224:225], v[228:229] op_sel:[0,1,0]
	v_pk_mul_f32 v[232:233], v[56:57], v[12:13] op_sel_hi:[1,0]
	v_add_f32_dpp v230, v227, v226 row_ror:8 row_mask:0xf bank_mask:0xf
	v_pk_mul_f32 v[234:235], v[56:57], v[12:13] op_sel:[0,1]
	v_pk_mul_f32 v[236:237], v[56:57], v[14:15] op_sel_hi:[1,0]
	v_add_f32_dpp v230, v230, v230 quad_perm:[1,0,3,2] row_mask:0xf bank_mask:0xf
	v_pk_mul_f32 v[238:239], v[56:57], v[14:15] op_sel:[0,1]
	ds_read_b128 v[222:225], v240 offset:37264
	v_add_f32_dpp v230, v230, v230 quad_perm:[2,3,0,1] row_mask:0xf bank_mask:0xf
	v_pk_fma_f32 v[232:233], v[206:207], v[0:1], v[232:233] op_sel_hi:[1,0,1]
	v_pk_fma_f32 v[234:235], v[208:209], v[0:1], v[234:235] op_sel:[0,1,0]
	v_add_f32_dpp v230, v230, v230 row_half_mirror row_mask:0xf bank_mask:0xf
	v_pk_fma_f32 v[236:237], v[210:211], v[2:3], v[236:237] op_sel_hi:[1,0,1]
	v_pk_fma_f32 v[238:239], v[212:213], v[2:3], v[238:239] op_sel:[0,1,0]
	v_mov_b32_dpp v231, v230 row_ror:8 row_mask:0xf bank_mask:0xf
	ds_write_b64 v217, v[228:229] offset:4032
	v_pk_fma_f32 v[206:207], v[8:9], v[230:231], v[232:233] op_sel_hi:[0,1,1] neg_lo:[1,0,0] neg_hi:[1,0,0]
	v_pk_fma_f32 v[208:209], v[8:9], v[230:231], v[234:235] op_sel:[1,0,0] neg_lo:[1,0,0] neg_hi:[1,0,0]
	v_pk_fma_f32 v[210:211], v[10:11], v[230:231], v[236:237] op_sel_hi:[0,1,1] neg_lo:[1,0,0] neg_hi:[1,0,0]
	v_pk_fma_f32 v[212:213], v[10:11], v[230:231], v[238:239] op_sel:[1,0,0] neg_lo:[1,0,0] neg_hi:[1,0,0]
	s_waitcnt lgkmcnt(8)
	ds_read_b128 v[4:7], v240 offset:11696
	ds_read_b128 v[12:15], v240 offset:29104
	ds_read_b128 v[0:3], v240 offset:2992
	ds_read_b128 v[8:11], v240 offset:20400
	v_pk_mul_f32 v[226:227], v[206:207], v[84:85] op_sel_hi:[1,0]
	v_pk_mul_f32 v[228:229], v[206:207], v[96:97] op_sel_hi:[1,0]
	v_pk_fma_f32 v[226:227], v[208:209], v[84:85], v[226:227] op_sel:[0,1,0]
	v_pk_fma_f32 v[228:229], v[208:209], v[96:97], v[228:229] op_sel:[0,1,0]
	v_pk_fma_f32 v[226:227], v[210:211], v[86:87], v[226:227] op_sel_hi:[1,0,1]
	v_pk_fma_f32 v[228:229], v[210:211], v[98:99], v[228:229] op_sel_hi:[1,0,1]
	v_pk_fma_f32 v[226:227], v[212:213], v[86:87], v[226:227] op_sel:[0,1,0]
	v_pk_fma_f32 v[228:229], v[212:213], v[98:99], v[228:229] op_sel:[0,1,0]
	v_pk_mul_f32 v[232:233], v[58:59], v[92:93] op_sel_hi:[1,0]
	v_add_f32_dpp v230, v227, v226 row_ror:8 row_mask:0xf bank_mask:0xf
	v_pk_mul_f32 v[234:235], v[58:59], v[92:93] op_sel:[0,1]
	v_pk_mul_f32 v[236:237], v[58:59], v[94:95] op_sel_hi:[1,0]
	v_add_f32_dpp v230, v230, v230 quad_perm:[1,0,3,2] row_mask:0xf bank_mask:0xf
	v_pk_mul_f32 v[238:239], v[58:59], v[94:95] op_sel:[0,1]
	ds_read_b128 v[96:99], v240 offset:37536
	v_add_f32_dpp v230, v230, v230 quad_perm:[2,3,0,1] row_mask:0xf bank_mask:0xf
	v_pk_fma_f32 v[232:233], v[206:207], v[80:81], v[232:233] op_sel_hi:[1,0,1]
	v_pk_fma_f32 v[234:235], v[208:209], v[80:81], v[234:235] op_sel:[0,1,0]
	v_add_f32_dpp v230, v230, v230 row_half_mirror row_mask:0xf bank_mask:0xf
	v_pk_fma_f32 v[236:237], v[210:211], v[82:83], v[236:237] op_sel_hi:[1,0,1]
	v_pk_fma_f32 v[238:239], v[212:213], v[82:83], v[238:239] op_sel:[0,1,0]
	v_mov_b32_dpp v231, v230 row_ror:8 row_mask:0xf bank_mask:0xf
	ds_write_b64 v217, v[228:229] offset:4608
	v_pk_fma_f32 v[206:207], v[88:89], v[230:231], v[232:233] op_sel_hi:[0,1,1] neg_lo:[1,0,0] neg_hi:[1,0,0]
	v_pk_fma_f32 v[208:209], v[88:89], v[230:231], v[234:235] op_sel:[1,0,0] neg_lo:[1,0,0] neg_hi:[1,0,0]
	v_pk_fma_f32 v[210:211], v[90:91], v[230:231], v[236:237] op_sel_hi:[0,1,1] neg_lo:[1,0,0] neg_hi:[1,0,0]
	v_pk_fma_f32 v[212:213], v[90:91], v[230:231], v[238:239] op_sel:[1,0,0] neg_lo:[1,0,0] neg_hi:[1,0,0]
	s_waitcnt lgkmcnt(7)
	ds_read_b128 v[84:87], v240 offset:11968
	ds_read_b128 v[56:59], v242 offset:46688
	ds_read_b128 v[92:95], v240 offset:29376
	ds_read_b128 v[80:83], v240 offset:3264
	ds_read_b128 v[88:91], v240 offset:20672
	v_pk_mul_f32 v[226:227], v[206:207], v[106:107] op_sel_hi:[1,0]
	v_pk_mul_f32 v[228:229], v[206:207], v[222:223] op_sel_hi:[1,0]
	v_pk_fma_f32 v[226:227], v[208:209], v[106:107], v[226:227] op_sel:[0,1,0]
	v_pk_fma_f32 v[228:229], v[208:209], v[222:223], v[228:229] op_sel:[0,1,0]
	v_pk_fma_f32 v[226:227], v[210:211], v[108:109], v[226:227] op_sel_hi:[1,0,1]
	v_pk_fma_f32 v[228:229], v[210:211], v[224:225], v[228:229] op_sel_hi:[1,0,1]
	v_pk_fma_f32 v[226:227], v[212:213], v[108:109], v[226:227] op_sel:[0,1,0]
	v_pk_fma_f32 v[228:229], v[212:213], v[224:225], v[228:229] op_sel:[0,1,0]
	v_pk_mul_f32 v[232:233], v[60:61], v[114:115] op_sel_hi:[1,0]
	v_add_f32_dpp v230, v227, v226 row_ror:8 row_mask:0xf bank_mask:0xf
	v_pk_mul_f32 v[234:235], v[60:61], v[114:115] op_sel:[0,1]
	v_pk_mul_f32 v[236:237], v[60:61], v[116:117] op_sel_hi:[1,0]
	v_add_f32_dpp v230, v230, v230 quad_perm:[1,0,3,2] row_mask:0xf bank_mask:0xf
	v_pk_mul_f32 v[238:239], v[60:61], v[116:117] op_sel:[0,1]
	ds_read_b128 v[222:225], v240 offset:37808
	v_add_f32_dpp v230, v230, v230 quad_perm:[2,3,0,1] row_mask:0xf bank_mask:0xf
	v_pk_fma_f32 v[232:233], v[206:207], v[102:103], v[232:233] op_sel_hi:[1,0,1]
	v_pk_fma_f32 v[234:235], v[208:209], v[102:103], v[234:235] op_sel:[0,1,0]
	v_add_f32_dpp v230, v230, v230 row_half_mirror row_mask:0xf bank_mask:0xf
	v_pk_fma_f32 v[236:237], v[210:211], v[104:105], v[236:237] op_sel_hi:[1,0,1]
	v_pk_fma_f32 v[238:239], v[212:213], v[104:105], v[238:239] op_sel:[0,1,0]
	v_mov_b32_dpp v231, v230 row_ror:8 row_mask:0xf bank_mask:0xf
	ds_write_b64 v217, v[228:229] offset:5184
	v_pk_fma_f32 v[206:207], v[110:111], v[230:231], v[232:233] op_sel_hi:[0,1,1] neg_lo:[1,0,0] neg_hi:[1,0,0]
	v_pk_fma_f32 v[208:209], v[110:111], v[230:231], v[234:235] op_sel:[1,0,0] neg_lo:[1,0,0] neg_hi:[1,0,0]
	v_pk_fma_f32 v[210:211], v[112:113], v[230:231], v[236:237] op_sel_hi:[0,1,1] neg_lo:[1,0,0] neg_hi:[1,0,0]
	v_pk_fma_f32 v[212:213], v[112:113], v[230:231], v[238:239] op_sel:[1,0,0] neg_lo:[1,0,0] neg_hi:[1,0,0]
	s_waitcnt lgkmcnt(8)
; template <int CTRL> __device__ __forceinline__ float dppf(float x) { return __builtin_bit_cast(float, __builtin_amdgcn_update_dpp(0, __builtin_bit_cast(int, x), CTRL, 0xF, 0xF, false)); }
; __device__ __forceinline__ void phase_rwkv_scan(const Fr& F, int jr) {
;     ...
;                 f32x4 w4 = PW[0], k4 = PW[1024], b4 = PW[2048], d4 = PW[3072], r4 = PR[0];
;                 float vv = PV[0];
;                 for (int pg = 0; pg < 64; pg += 16) {
; #pragma unroll
;                     for (int pi = 0; pi < 16; ++pi) {
;                         const int p = pg + pi, pn = p < 63 ? p + 1 : 63;
;                         const f32x4 w4n = PW[pn * 16], k4n = PW[1024 + pn * 16], b4n = PW[2048 + pn * 16], d4n = PW[3072 + pn * 16], r4n = PR[pn * 16];
;                         const float vvn = PV[pn * 32];
;                         f32x2 t = S01 * k4.xy; t = S23 * k4.zw + t; float sa = t.x + t.y;
;                         sa += dppf<0x128>(sa);
;                         const f32x2 dv01 = d4.xy * vv, dv23 = d4.zw * vv;
;                         sa += dppf<0x124>(sa);
;                         const f32x2 e01 = S01 * w4.xy + dv01;
;                         sa += dppf<0x122>(sa);
;                         const f32x2 e23 = S23 * w4.zw + dv23;
;                         sa += dppf<0x121>(sa);
;                         S01 = e01 - b4.xy * sa; S23 = e23 - b4.zw * sa;
;                         f32x2 u = S01 * r4.xy; u = S23 * r4.zw + u;
;                         PY[pi * 64] = u.x + u.y;
;                         w4 = w4n; k4 = k4n; b4 = b4n; d4 = d4n; r4 = r4n; vv = vvn;
;                     }
	ds_read_b128 v[106:109], v240 offset:12240
	ds_read_b128 v[114:117], v240 offset:29648
	ds_read_b128 v[102:105], v240 offset:3536
	ds_read_b128 v[110:113], v240 offset:20944
	v_pk_mul_f32 v[226:227], v[206:207], v[4:5] op_sel_hi:[1,0]
	v_pk_mul_f32 v[228:229], v[206:207], v[96:97] op_sel_hi:[1,0]
	v_pk_fma_f32 v[226:227], v[208:209], v[4:5], v[226:227] op_sel:[0,1,0]
	v_pk_fma_f32 v[228:229], v[208:209], v[96:97], v[228:229] op_sel:[0,1,0]
	v_pk_fma_f32 v[226:227], v[210:211], v[6:7], v[226:227] op_sel_hi:[1,0,1]
	v_pk_fma_f32 v[228:229], v[210:211], v[98:99], v[228:229] op_sel_hi:[1,0,1]
	v_pk_fma_f32 v[226:227], v[212:213], v[6:7], v[226:227] op_sel:[0,1,0]
	v_pk_fma_f32 v[228:229], v[212:213], v[98:99], v[228:229] op_sel:[0,1,0]
	v_pk_mul_f32 v[232:233], v[62:63], v[12:13] op_sel_hi:[1,0]
	v_add_f32_dpp v230, v227, v226 row_ror:8 row_mask:0xf bank_mask:0xf
	v_pk_mul_f32 v[234:235], v[62:63], v[12:13] op_sel:[0,1]
	v_pk_mul_f32 v[236:237], v[62:63], v[14:15] op_sel_hi:[1,0]
	v_add_f32_dpp v230, v230, v230 quad_perm:[1,0,3,2] row_mask:0xf bank_mask:0xf
	v_pk_mul_f32 v[238:239], v[62:63], v[14:15] op_sel:[0,1]
	ds_read_b128 v[96:99], v240 offset:38080
	v_add_f32_dpp v230, v230, v230 quad_perm:[2,3,0,1] row_mask:0xf bank_mask:0xf
	v_pk_fma_f32 v[232:233], v[206:207], v[0:1], v[232:233] op_sel_hi:[1,0,1]
	v_pk_fma_f32 v[234:235], v[208:209], v[0:1], v[234:235] op_sel:[0,1,0]
	v_add_f32_dpp v230, v230, v230 row_half_mirror row_mask:0xf bank_mask:0xf
	v_pk_fma_f32 v[236:237], v[210:211], v[2:3], v[236:237] op_sel_hi:[1,0,1]
	v_pk_fma_f32 v[238:239], v[212:213], v[2:3], v[238:239] op_sel:[0,1,0]
	v_mov_b32_dpp v231, v230 row_ror:8 row_mask:0xf bank_mask:0xf
	ds_write_b64 v217, v[228:229] offset:5760
	v_pk_fma_f32 v[206:207], v[8:9], v[230:231], v[232:233] op_sel_hi:[0,1,1] neg_lo:[1,0,0] neg_hi:[1,0,0]
	v_pk_fma_f32 v[208:209], v[8:9], v[230:231], v[234:235] op_sel:[1,0,0] neg_lo:[1,0,0] neg_hi:[1,0,0]
	v_pk_fma_f32 v[210:211], v[10:11], v[230:231], v[236:237] op_sel_hi:[0,1,1] neg_lo:[1,0,0] neg_hi:[1,0,0]
	v_pk_fma_f32 v[212:213], v[10:11], v[230:231], v[238:239] op_sel:[1,0,0] neg_lo:[1,0,0] neg_hi:[1,0,0]
	s_waitcnt lgkmcnt(7)
	ds_read_b128 v[4:7], v240 offset:12512
	ds_read_b128 v[60:63], v242 offset:47216
	ds_read_b128 v[12:15], v240 offset:29920
	ds_read_b128 v[0:3], v240 offset:3808
	ds_read_b128 v[8:11], v240 offset:21216
	v_pk_mul_f32 v[226:227], v[206:207], v[84:85] op_sel_hi:[1,0]
	v_pk_mul_f32 v[228:229], v[206:207], v[222:223] op_sel_hi:[1,0]
	v_pk_fma_f32 v[226:227], v[208:209], v[84:85], v[226:227] op_sel:[0,1,0]
	v_pk_fma_f32 v[228:229], v[208:209], v[222:223], v[228:229] op_sel:[0,1,0]
	v_pk_fma_f32 v[226:227], v[210:211], v[86:87], v[226:227] op_sel_hi:[1,0,1]
	v_pk_fma_f32 v[228:229], v[210:211], v[224:225], v[228:229] op_sel_hi:[1,0,1]
	v_pk_fma_f32 v[226:227], v[212:213], v[86:87], v[226:227] op_sel:[0,1,0]
	v_pk_fma_f32 v[228:229], v[212:213], v[224:225], v[228:229] op_sel:[0,1,0]
	v_pk_mul_f32 v[232:233], v[56:57], v[92:93] op_sel_hi:[1,0]
	v_add_f32_dpp v230, v227, v226 row_ror:8 row_mask:0xf bank_mask:0xf
	v_pk_mul_f32 v[234:235], v[56:57], v[92:93] op_sel:[0,1]
	v_pk_mul_f32 v[236:237], v[56:57], v[94:95] op_sel_hi:[1,0]
	v_add_f32_dpp v230, v230, v230 quad_perm:[1,0,3,2] row_mask:0xf bank_mask:0xf
	v_pk_mul_f32 v[238:239], v[56:57], v[94:95] op_sel:[0,1]
	ds_read_b128 v[222:225], v240 offset:38352
	v_add_f32_dpp v230, v230, v230 quad_perm:[2,3,0,1] row_mask:0xf bank_mask:0xf
	v_pk_fma_f32 v[232:233], v[206:207], v[80:81], v[232:233] op_sel_hi:[1,0,1]
	v_pk_fma_f32 v[234:235], v[208:209], v[80:81], v[234:235] op_sel:[0,1,0]
	v_add_f32_dpp v230, v230, v230 row_half_mirror row_mask:0xf bank_mask:0xf
	v_pk_fma_f32 v[236:237], v[210:211], v[82:83], v[236:237] op_sel_hi:[1,0,1]
	v_pk_fma_f32 v[238:239], v[212:213], v[82:83], v[238:239] op_sel:[0,1,0]
	v_mov_b32_dpp v231, v230 row_ror:8 row_mask:0xf bank_mask:0xf
	ds_write_b64 v217, v[228:229] offset:6336
	v_pk_fma_f32 v[206:207], v[88:89], v[230:231], v[232:233] op_sel_hi:[0,1,1] neg_lo:[1,0,0] neg_hi:[1,0,0]
	v_pk_fma_f32 v[208:209], v[88:89], v[230:231], v[234:235] op_sel:[1,0,0] neg_lo:[1,0,0] neg_hi:[1,0,0]
	v_pk_fma_f32 v[210:211], v[90:91], v[230:231], v[236:237] op_sel_hi:[0,1,1] neg_lo:[1,0,0] neg_hi:[1,0,0]
	v_pk_fma_f32 v[212:213], v[90:91], v[230:231], v[238:239] op_sel:[1,0,0] neg_lo:[1,0,0] neg_hi:[1,0,0]
	s_waitcnt lgkmcnt(8)
	ds_read_b128 v[84:87], v240 offset:12784
	ds_read_b128 v[92:95], v240 offset:30192
	ds_read_b128 v[80:83], v240 offset:4080
	ds_read_b128 v[88:91], v240 offset:21488
	v_pk_mul_f32 v[226:227], v[206:207], v[106:107] op_sel_hi:[1,0]
	v_pk_mul_f32 v[228:229], v[206:207], v[96:97] op_sel_hi:[1,0]
	v_pk_fma_f32 v[226:227], v[208:209], v[106:107], v[226:227] op_sel:[0,1,0]
	v_pk_fma_f32 v[228:229], v[208:209], v[96:97], v[228:229] op_sel:[0,1,0]
	v_pk_fma_f32 v[226:227], v[210:211], v[108:109], v[226:227] op_sel_hi:[1,0,1]
	v_pk_fma_f32 v[228:229], v[210:211], v[98:99], v[228:229] op_sel_hi:[1,0,1]
	v_pk_fma_f32 v[226:227], v[212:213], v[108:109], v[226:227] op_sel:[0,1,0]
	v_pk_fma_f32 v[228:229], v[212:213], v[98:99], v[228:229] op_sel:[0,1,0]
	v_pk_mul_f32 v[232:233], v[58:59], v[114:115] op_sel_hi:[1,0]
	v_add_f32_dpp v230, v227, v226 row_ror:8 row_mask:0xf bank_mask:0xf
	v_pk_mul_f32 v[234:235], v[58:59], v[114:115] op_sel:[0,1]
	v_pk_mul_f32 v[236:237], v[58:59], v[116:117] op_sel_hi:[1,0]
	v_add_f32_dpp v230, v230, v230 quad_perm:[1,0,3,2] row_mask:0xf bank_mask:0xf
	v_pk_mul_f32 v[238:239], v[58:59], v[116:117] op_sel:[0,1]
	ds_read_b128 v[96:99], v240 offset:38624
	v_add_f32_dpp v230, v230, v230 quad_perm:[2,3,0,1] row_mask:0xf bank_mask:0xf
	v_pk_fma_f32 v[232:233], v[206:207], v[102:103], v[232:233] op_sel_hi:[1,0,1]
	v_pk_fma_f32 v[234:235], v[208:209], v[102:103], v[234:235] op_sel:[0,1,0]
	v_add_f32_dpp v230, v230, v230 row_half_mirror row_mask:0xf bank_mask:0xf
	v_pk_fma_f32 v[236:237], v[210:211], v[104:105], v[236:237] op_sel_hi:[1,0,1]
	v_pk_fma_f32 v[238:239], v[212:213], v[104:105], v[238:239] op_sel:[0,1,0]
	v_mov_b32_dpp v231, v230 row_ror:8 row_mask:0xf bank_mask:0xf
	ds_write_b64 v217, v[228:229] offset:6912
	v_pk_fma_f32 v[206:207], v[110:111], v[230:231], v[232:233] op_sel_hi:[0,1,1] neg_lo:[1,0,0] neg_hi:[1,0,0]
	v_pk_fma_f32 v[208:209], v[110:111], v[230:231], v[234:235] op_sel:[1,0,0] neg_lo:[1,0,0] neg_hi:[1,0,0]
	v_pk_fma_f32 v[210:211], v[112:113], v[230:231], v[236:237] op_sel_hi:[0,1,1] neg_lo:[1,0,0] neg_hi:[1,0,0]
	v_pk_fma_f32 v[212:213], v[112:113], v[230:231], v[238:239] op_sel:[1,0,0] neg_lo:[1,0,0] neg_hi:[1,0,0]
	s_waitcnt lgkmcnt(7)
; __device__ __forceinline__ unsigned f2bf(float f) { unsigned u = __builtin_bit_cast(unsigned, f); return (u + 0x7fffu + ((u >> 16) & 1u)) >> 16; }
; template <int CTRL> __device__ __forceinline__ float dppf(float x) { return __builtin_bit_cast(float, __builtin_amdgcn_update_dpp(0, __builtin_bit_cast(int, x), CTRL, 0xF, 0xF, false)); }
; __device__ __forceinline__ void phase_rwkv_scan(const Fr& F, int jr) {
;     ...
;                         const int p = pg + pi, pn = p < 63 ? p + 1 : 63;
;                         const f32x4 w4n = PW[pn * 16], k4n = PW[1024 + pn * 16], b4n = PW[2048 + pn * 16], d4n = PW[3072 + pn * 16], r4n = PR[pn * 16];
;                         const float vvn = PV[pn * 32];
;                         f32x2 t = S01 * k4.xy; t = S23 * k4.zw + t; float sa = t.x + t.y;
;                         sa += dppf<0x128>(sa);
;                         const f32x2 dv01 = d4.xy * vv, dv23 = d4.zw * vv;
;                         sa += dppf<0x124>(sa);
;                         const f32x2 e01 = S01 * w4.xy + dv01;
;                         sa += dppf<0x122>(sa);
;                         const f32x2 e23 = S23 * w4.zw + dv23;
;                         sa += dppf<0x121>(sa);
;                         S01 = e01 - b4.xy * sa; S23 = e23 - b4.zw * sa;
;                         f32x2 u = S01 * r4.xy; u = S23 * r4.zw + u;
;                         PY[pi * 64] = u.x + u.y;
;                         w4 = w4n; k4 = k4n; b4 = b4n; d4 = d4n; r4 = r4n; vv = vvn;
;                     }
;                     asm volatile("s_waitcnt lgkmcnt(0)" ::: "memory");
;                     {
;                         const int j = lane >> 2, q = lane & 3; const float* yp = Ypw + j * 64 + q * 16;
;                         const f32x4 a0 = *(const f32x4*)yp, a1 = *(const f32x4*)(yp + 4), a2 = *(const f32x4*)(yp + 8), a3 = *(const f32x4*)(yp + 12);
;                         const f32x4 ssum = (a0 + a1) + (a2 + a3); const float yv = (ssum.x + ssum.y) + (ssum.z + ssum.w);
;                         const size_t row = (size_t)b * TB + tokof(s, chunk * 64 + pg + j);
;                         Yb[row * D + h * 64 + 32 * half + 4 * wave + q] = (bf16)f2bf(yv);
;                     }
	ds_read_b128 v[106:109], v240 offset:13056
	ds_read_b128 v[56:59], v242 offset:47744
	ds_read_b128 v[114:117], v240 offset:30464
	ds_read_b128 v[102:105], v240 offset:4352
	ds_read_b128 v[110:113], v240 offset:21760
	v_pk_mul_f32 v[226:227], v[206:207], v[4:5] op_sel_hi:[1,0]
	v_pk_mul_f32 v[228:229], v[206:207], v[222:223] op_sel_hi:[1,0]
	v_pk_fma_f32 v[226:227], v[208:209], v[4:5], v[226:227] op_sel:[0,1,0]
	v_pk_fma_f32 v[228:229], v[208:209], v[222:223], v[228:229] op_sel:[0,1,0]
	v_pk_fma_f32 v[226:227], v[210:211], v[6:7], v[226:227] op_sel_hi:[1,0,1]
	v_pk_fma_f32 v[228:229], v[210:211], v[224:225], v[228:229] op_sel_hi:[1,0,1]
	v_pk_fma_f32 v[226:227], v[212:213], v[6:7], v[226:227] op_sel:[0,1,0]
	v_pk_fma_f32 v[228:229], v[212:213], v[224:225], v[228:229] op_sel:[0,1,0]
	v_pk_mul_f32 v[232:233], v[60:61], v[12:13] op_sel_hi:[1,0]
	v_add_f32_dpp v230, v227, v226 row_ror:8 row_mask:0xf bank_mask:0xf
	v_pk_mul_f32 v[234:235], v[60:61], v[12:13] op_sel:[0,1]
	v_pk_mul_f32 v[236:237], v[60:61], v[14:15] op_sel_hi:[1,0]
	v_add_f32_dpp v230, v230, v230 quad_perm:[1,0,3,2] row_mask:0xf bank_mask:0xf
	v_pk_mul_f32 v[238:239], v[60:61], v[14:15] op_sel:[0,1]
	ds_read_b128 v[222:225], v240 offset:38896
	v_add_f32_dpp v230, v230, v230 quad_perm:[2,3,0,1] row_mask:0xf bank_mask:0xf
	v_pk_fma_f32 v[232:233], v[206:207], v[0:1], v[232:233] op_sel_hi:[1,0,1]
	v_pk_fma_f32 v[234:235], v[208:209], v[0:1], v[234:235] op_sel:[0,1,0]
	v_add_f32_dpp v230, v230, v230 row_half_mirror row_mask:0xf bank_mask:0xf
	v_pk_fma_f32 v[236:237], v[210:211], v[2:3], v[236:237] op_sel_hi:[1,0,1]
	v_pk_fma_f32 v[238:239], v[212:213], v[2:3], v[238:239] op_sel:[0,1,0]
	v_mov_b32_dpp v231, v230 row_ror:8 row_mask:0xf bank_mask:0xf
	ds_write_b64 v217, v[228:229] offset:7488
	v_pk_fma_f32 v[206:207], v[8:9], v[230:231], v[232:233] op_sel_hi:[0,1,1] neg_lo:[1,0,0] neg_hi:[1,0,0]
	v_pk_fma_f32 v[208:209], v[8:9], v[230:231], v[234:235] op_sel:[1,0,0] neg_lo:[1,0,0] neg_hi:[1,0,0]
	v_pk_fma_f32 v[210:211], v[10:11], v[230:231], v[236:237] op_sel_hi:[0,1,1] neg_lo:[1,0,0] neg_hi:[1,0,0]
	v_pk_fma_f32 v[212:213], v[10:11], v[230:231], v[238:239] op_sel:[1,0,0] neg_lo:[1,0,0] neg_hi:[1,0,0]
	s_waitcnt lgkmcnt(8)
	ds_read_b128 v[4:7], v240 offset:13328
	ds_read_b128 v[12:15], v240 offset:30736
	ds_read_b128 v[0:3], v240 offset:4624
	ds_read_b128 v[8:11], v240 offset:22032
	v_pk_mul_f32 v[226:227], v[206:207], v[84:85] op_sel_hi:[1,0]
	v_pk_mul_f32 v[228:229], v[206:207], v[96:97] op_sel_hi:[1,0]
	v_pk_fma_f32 v[226:227], v[208:209], v[84:85], v[226:227] op_sel:[0,1,0]
	v_pk_fma_f32 v[228:229], v[208:209], v[96:97], v[228:229] op_sel:[0,1,0]
	v_pk_fma_f32 v[226:227], v[210:211], v[86:87], v[226:227] op_sel_hi:[1,0,1]
	v_pk_fma_f32 v[228:229], v[210:211], v[98:99], v[228:229] op_sel_hi:[1,0,1]
	v_pk_fma_f32 v[226:227], v[212:213], v[86:87], v[226:227] op_sel:[0,1,0]
	v_pk_fma_f32 v[228:229], v[212:213], v[98:99], v[228:229] op_sel:[0,1,0]
	v_pk_mul_f32 v[232:233], v[62:63], v[92:93] op_sel_hi:[1,0]
	v_add_f32_dpp v230, v227, v226 row_ror:8 row_mask:0xf bank_mask:0xf
	v_pk_mul_f32 v[234:235], v[62:63], v[92:93] op_sel:[0,1]
	v_pk_mul_f32 v[236:237], v[62:63], v[94:95] op_sel_hi:[1,0]
	v_add_f32_dpp v230, v230, v230 quad_perm:[1,0,3,2] row_mask:0xf bank_mask:0xf
	v_pk_mul_f32 v[238:239], v[62:63], v[94:95] op_sel:[0,1]
	ds_read_b128 v[96:99], v240 offset:39168
	v_add_f32_dpp v230, v230, v230 quad_perm:[2,3,0,1] row_mask:0xf bank_mask:0xf
	v_pk_fma_f32 v[232:233], v[206:207], v[80:81], v[232:233] op_sel_hi:[1,0,1]
	v_pk_fma_f32 v[234:235], v[208:209], v[80:81], v[234:235] op_sel:[0,1,0]
	v_add_f32_dpp v230, v230, v230 row_half_mirror row_mask:0xf bank_mask:0xf
	v_pk_fma_f32 v[236:237], v[210:211], v[82:83], v[236:237] op_sel_hi:[1,0,1]
	v_pk_fma_f32 v[238:239], v[212:213], v[82:83], v[238:239] op_sel:[0,1,0]
	v_mov_b32_dpp v231, v230 row_ror:8 row_mask:0xf bank_mask:0xf
	ds_write_b64 v217, v[228:229] offset:8064
	v_pk_fma_f32 v[206:207], v[88:89], v[230:231], v[232:233] op_sel_hi:[0,1,1] neg_lo:[1,0,0] neg_hi:[1,0,0]
	v_pk_fma_f32 v[208:209], v[88:89], v[230:231], v[234:235] op_sel:[1,0,0] neg_lo:[1,0,0] neg_hi:[1,0,0]
	v_pk_fma_f32 v[210:211], v[90:91], v[230:231], v[236:237] op_sel_hi:[0,1,1] neg_lo:[1,0,0] neg_hi:[1,0,0]
	v_pk_fma_f32 v[212:213], v[90:91], v[230:231], v[238:239] op_sel:[1,0,0] neg_lo:[1,0,0] neg_hi:[1,0,0]
	s_waitcnt lgkmcnt(7)
	v_pk_mul_f32 v[228:229], v[206:207], v[222:223] op_sel_hi:[1,0]
	v_add_u32_e32 v243, s15, v219
	v_pk_fma_f32 v[228:229], v[208:209], v[222:223], v[228:229] op_sel:[0,1,0]
	v_lshl_add_u32 v243, v243, 11, v220
	v_pk_fma_f32 v[228:229], v[210:211], v[224:225], v[228:229] op_sel_hi:[1,0,1]
	v_pk_fma_f32 v[228:229], v[212:213], v[224:225], v[228:229] op_sel:[0,1,0]
	s_waitcnt lgkmcnt(6)
	ds_write_b64 v217, v[228:229] offset:8640
	ds_read_b128 v[24:27], v218 offset:0
	ds_read_b128 v[28:31], v218 offset:16
	ds_read_b128 v[32:35], v218 offset:32
	ds_read_b128 v[36:39], v218 offset:48
	ds_read_b128 v[40:43], v218 offset:64
	ds_read_b128 v[44:47], v218 offset:80
	ds_read_b128 v[48:51], v218 offset:96
	s_waitcnt lgkmcnt(5)
	ds_read_b128 v[52:55], v218 offset:112
	v_pk_add_f32 v[24:25], v[24:25], v[26:27]
	v_pk_add_f32 v[28:29], v[28:29], v[30:31]
	s_waitcnt lgkmcnt(4)
	v_pk_add_f32 v[32:33], v[32:33], v[34:35]
	v_pk_add_f32 v[36:37], v[36:37], v[38:39]
	v_pk_add_f32 v[24:25], v[24:25], v[28:29]
	s_waitcnt lgkmcnt(2)
	v_pk_add_f32 v[40:41], v[40:41], v[42:43]
	v_pk_add_f32 v[44:45], v[44:45], v[46:47]
	v_pk_add_f32 v[32:33], v[32:33], v[36:37]
	s_waitcnt lgkmcnt(0)
; __device__ __forceinline__ unsigned f2bf(float f) { unsigned u = __builtin_bit_cast(unsigned, f); return (u + 0x7fffu + ((u >> 16) & 1u)) >> 16; }
; template <int CTRL> __device__ __forceinline__ float dppf(float x) { return __builtin_bit_cast(float, __builtin_amdgcn_update_dpp(0, __builtin_bit_cast(int, x), CTRL, 0xF, 0xF, false)); }
; __device__ __forceinline__ void phase_rwkv_scan(const Fr& F, int jr) {
;     ...
;                         const int p = pg + pi, pn = p < 63 ? p + 1 : 63;
;                         const f32x4 w4n = PW[pn * 16], k4n = PW[1024 + pn * 16], b4n = PW[2048 + pn * 16], d4n = PW[3072 + pn * 16], r4n = PR[pn * 16];
;                         const float vvn = PV[pn * 32];
;                         f32x2 t = S01 * k4.xy; t = S23 * k4.zw + t; float sa = t.x + t.y;
;                         sa += dppf<0x128>(sa);
;                         const f32x2 dv01 = d4.xy * vv, dv23 = d4.zw * vv;
;                         sa += dppf<0x124>(sa);
;                         const f32x2 e01 = S01 * w4.xy + dv01;
;                         sa += dppf<0x122>(sa);
;                         const f32x2 e23 = S23 * w4.zw + dv23;
;                         sa += dppf<0x121>(sa);
;                         S01 = e01 - b4.xy * sa; S23 = e23 - b4.zw * sa;
;                         f32x2 u = S01 * r4.xy; u = S23 * r4.zw + u;
;                         PY[pi * 64] = u.x + u.y;
;                         w4 = w4n; k4 = k4n; b4 = b4n; d4 = d4n; r4 = r4n; vv = vvn;
;                     }
;                     asm volatile("s_waitcnt lgkmcnt(0)" ::: "memory");
;                     {
;                         const int j = lane >> 2, q = lane & 3; const float* yp = Ypw + j * 64 + q * 16;
;                         const f32x4 a0 = *(const f32x4*)yp, a1 = *(const f32x4*)(yp + 4), a2 = *(const f32x4*)(yp + 8), a3 = *(const f32x4*)(yp + 12);
;                         const f32x4 ssum = (a0 + a1) + (a2 + a3); const float yv = (ssum.x + ssum.y) + (ssum.z + ssum.w);
;                         const size_t row = (size_t)b * TB + tokof(s, chunk * 64 + pg + j);
;                         Yb[row * D + h * 64 + 32 * half + 4 * wave + q] = (bf16)f2bf(yv);
;                     }
	v_pk_add_f32 v[48:49], v[48:49], v[50:51]
	v_pk_add_f32 v[52:53], v[52:53], v[54:55]
	v_pk_add_f32 v[40:41], v[40:41], v[44:45]
	v_pk_add_f32 v[24:25], v[24:25], v[32:33]
	v_pk_add_f32 v[48:49], v[48:49], v[52:53]
	s_add_i32 s15, s15, s19
	v_pk_add_f32 v[40:41], v[40:41], v[48:49]
	v_pk_add_f32 v[24:25], v[24:25], v[40:41] op_sel:[0,1] op_sel_hi:[1,0]
	v_cvt_pk_bf16_f32 v244, v24, v25
	global_store_dword v243, v244, s[20:21]
	ds_read_b128 v[84:87], v240 offset:13600
	ds_read_b128 v[60:63], v242 offset:48272
	ds_read_b128 v[92:95], v240 offset:31008
	ds_read_b128 v[80:83], v240 offset:4896
	ds_read_b128 v[88:91], v240 offset:22304
	v_pk_mul_f32 v[226:227], v[206:207], v[106:107] op_sel_hi:[1,0]
	v_pk_mul_f32 v[232:233], v[56:57], v[114:115] op_sel_hi:[1,0]
	v_pk_fma_f32 v[226:227], v[208:209], v[106:107], v[226:227] op_sel:[0,1,0]
	v_pk_mul_f32 v[234:235], v[56:57], v[114:115] op_sel:[0,1]
	v_pk_fma_f32 v[226:227], v[210:211], v[108:109], v[226:227] op_sel_hi:[1,0,1]
	v_pk_mul_f32 v[236:237], v[56:57], v[116:117] op_sel_hi:[1,0]
	v_pk_fma_f32 v[226:227], v[212:213], v[108:109], v[226:227] op_sel:[0,1,0]
	v_pk_mul_f32 v[238:239], v[56:57], v[116:117] op_sel:[0,1]
	s_nop 0
	v_add_f32_dpp v230, v227, v226 row_ror:8 row_mask:0xf bank_mask:0xf
	v_pk_fma_f32 v[232:233], v[206:207], v[102:103], v[232:233] op_sel_hi:[1,0,1]
	v_pk_fma_f32 v[234:235], v[208:209], v[102:103], v[234:235] op_sel:[0,1,0]
	v_add_f32_dpp v230, v230, v230 quad_perm:[1,0,3,2] row_mask:0xf bank_mask:0xf
	v_pk_fma_f32 v[236:237], v[210:211], v[104:105], v[236:237] op_sel_hi:[1,0,1]
	v_pk_fma_f32 v[238:239], v[212:213], v[104:105], v[238:239] op_sel:[0,1,0]
	v_add_f32_dpp v230, v230, v230 quad_perm:[2,3,0,1] row_mask:0xf bank_mask:0xf
	ds_read_b128 v[222:225], v240 offset:39440
	s_nop 0
	v_add_f32_dpp v230, v230, v230 row_half_mirror row_mask:0xf bank_mask:0xf
	s_nop 1
	v_mov_b32_dpp v231, v230 row_ror:8 row_mask:0xf bank_mask:0xf
	v_pk_fma_f32 v[206:207], v[110:111], v[230:231], v[232:233] op_sel_hi:[0,1,1] neg_lo:[1,0,0] neg_hi:[1,0,0]
	v_pk_fma_f32 v[208:209], v[110:111], v[230:231], v[234:235] op_sel:[1,0,0] neg_lo:[1,0,0] neg_hi:[1,0,0]
	v_pk_fma_f32 v[210:211], v[112:113], v[230:231], v[236:237] op_sel_hi:[0,1,1] neg_lo:[1,0,0] neg_hi:[1,0,0]
	v_pk_fma_f32 v[212:213], v[112:113], v[230:231], v[238:239] op_sel:[1,0,0] neg_lo:[1,0,0] neg_hi:[1,0,0]
	ds_read_b128 v[106:109], v240 offset:13872
	ds_read_b128 v[114:117], v240 offset:31280
	ds_read_b128 v[102:105], v240 offset:5168
	ds_read_b128 v[110:113], v240 offset:22576
	v_pk_mul_f32 v[226:227], v[206:207], v[4:5] op_sel_hi:[1,0]
	v_pk_mul_f32 v[228:229], v[206:207], v[96:97] op_sel_hi:[1,0]
	v_pk_fma_f32 v[226:227], v[208:209], v[4:5], v[226:227] op_sel:[0,1,0]
	v_pk_fma_f32 v[228:229], v[208:209], v[96:97], v[228:229] op_sel:[0,1,0]
	v_pk_fma_f32 v[226:227], v[210:211], v[6:7], v[226:227] op_sel_hi:[1,0,1]
	v_pk_fma_f32 v[228:229], v[210:211], v[98:99], v[228:229] op_sel_hi:[1,0,1]
	v_pk_fma_f32 v[226:227], v[212:213], v[6:7], v[226:227] op_sel:[0,1,0]
	v_pk_fma_f32 v[228:229], v[212:213], v[98:99], v[228:229] op_sel:[0,1,0]
	v_pk_mul_f32 v[232:233], v[58:59], v[12:13] op_sel_hi:[1,0]
	v_add_f32_dpp v230, v227, v226 row_ror:8 row_mask:0xf bank_mask:0xf
	v_pk_mul_f32 v[234:235], v[58:59], v[12:13] op_sel:[0,1]
	v_pk_mul_f32 v[236:237], v[58:59], v[14:15] op_sel_hi:[1,0]
	v_add_f32_dpp v230, v230, v230 quad_perm:[1,0,3,2] row_mask:0xf bank_mask:0xf
	v_pk_mul_f32 v[238:239], v[58:59], v[14:15] op_sel:[0,1]
	ds_read_b128 v[96:99], v240 offset:39712
	v_add_f32_dpp v230, v230, v230 quad_perm:[2,3,0,1] row_mask:0xf bank_mask:0xf
	v_pk_fma_f32 v[232:233], v[206:207], v[0:1], v[232:233] op_sel_hi:[1,0,1]
	v_pk_fma_f32 v[234:235], v[208:209], v[0:1], v[234:235] op_sel:[0,1,0]
	v_add_f32_dpp v230, v230, v230 row_half_mirror row_mask:0xf bank_mask:0xf
	v_pk_fma_f32 v[236:237], v[210:211], v[2:3], v[236:237] op_sel_hi:[1,0,1]
	v_pk_fma_f32 v[238:239], v[212:213], v[2:3], v[238:239] op_sel:[0,1,0]
	v_mov_b32_dpp v231, v230 row_ror:8 row_mask:0xf bank_mask:0xf
	ds_write_b64 v217, v[228:229] offset:0
	v_pk_fma_f32 v[206:207], v[8:9], v[230:231], v[232:233] op_sel_hi:[0,1,1] neg_lo:[1,0,0] neg_hi:[1,0,0]
	v_pk_fma_f32 v[208:209], v[8:9], v[230:231], v[234:235] op_sel:[1,0,0] neg_lo:[1,0,0] neg_hi:[1,0,0]
	v_pk_fma_f32 v[210:211], v[10:11], v[230:231], v[236:237] op_sel_hi:[0,1,1] neg_lo:[1,0,0] neg_hi:[1,0,0]
	v_pk_fma_f32 v[212:213], v[10:11], v[230:231], v[238:239] op_sel:[1,0,0] neg_lo:[1,0,0] neg_hi:[1,0,0]
	s_waitcnt lgkmcnt(6)
	ds_read_b128 v[4:7], v240 offset:14144
	ds_read_b128 v[56:59], v242 offset:48800
	ds_read_b128 v[12:15], v240 offset:31552
	ds_read_b128 v[0:3], v240 offset:5440
	ds_read_b128 v[8:11], v240 offset:22848
	v_pk_mul_f32 v[226:227], v[206:207], v[84:85] op_sel_hi:[1,0]
	v_pk_mul_f32 v[228:229], v[206:207], v[222:223] op_sel_hi:[1,0]
	v_pk_fma_f32 v[226:227], v[208:209], v[84:85], v[226:227] op_sel:[0,1,0]
	v_pk_fma_f32 v[228:229], v[208:209], v[222:223], v[228:229] op_sel:[0,1,0]
	v_pk_fma_f32 v[226:227], v[210:211], v[86:87], v[226:227] op_sel_hi:[1,0,1]
	v_pk_fma_f32 v[228:229], v[210:211], v[224:225], v[228:229] op_sel_hi:[1,0,1]
	v_pk_fma_f32 v[226:227], v[212:213], v[86:87], v[226:227] op_sel:[0,1,0]
	v_pk_fma_f32 v[228:229], v[212:213], v[224:225], v[228:229] op_sel:[0,1,0]
	v_pk_mul_f32 v[232:233], v[60:61], v[92:93] op_sel_hi:[1,0]
	v_add_f32_dpp v230, v227, v226 row_ror:8 row_mask:0xf bank_mask:0xf
	v_pk_mul_f32 v[234:235], v[60:61], v[92:93] op_sel:[0,1]
	v_pk_mul_f32 v[236:237], v[60:61], v[94:95] op_sel_hi:[1,0]
	v_add_f32_dpp v230, v230, v230 quad_perm:[1,0,3,2] row_mask:0xf bank_mask:0xf
	v_pk_mul_f32 v[238:239], v[60:61], v[94:95] op_sel:[0,1]
	ds_read_b128 v[222:225], v240 offset:39984
	v_add_f32_dpp v230, v230, v230 quad_perm:[2,3,0,1] row_mask:0xf bank_mask:0xf
	v_pk_fma_f32 v[232:233], v[206:207], v[80:81], v[232:233] op_sel_hi:[1,0,1]
	v_pk_fma_f32 v[234:235], v[208:209], v[80:81], v[234:235] op_sel:[0,1,0]
	v_add_f32_dpp v230, v230, v230 row_half_mirror row_mask:0xf bank_mask:0xf
	v_pk_fma_f32 v[236:237], v[210:211], v[82:83], v[236:237] op_sel_hi:[1,0,1]
	v_pk_fma_f32 v[238:239], v[212:213], v[82:83], v[238:239] op_sel:[0,1,0]
	v_mov_b32_dpp v231, v230 row_ror:8 row_mask:0xf bank_mask:0xf
	ds_write_b64 v217, v[228:229] offset:576
	v_pk_fma_f32 v[206:207], v[88:89], v[230:231], v[232:233] op_sel_hi:[0,1,1] neg_lo:[1,0,0] neg_hi:[1,0,0]
	v_pk_fma_f32 v[208:209], v[88:89], v[230:231], v[234:235] op_sel:[1,0,0] neg_lo:[1,0,0] neg_hi:[1,0,0]
	v_pk_fma_f32 v[210:211], v[90:91], v[230:231], v[236:237] op_sel_hi:[0,1,1] neg_lo:[1,0,0] neg_hi:[1,0,0]
	v_pk_fma_f32 v[212:213], v[90:91], v[230:231], v[238:239] op_sel:[1,0,0] neg_lo:[1,0,0] neg_hi:[1,0,0]
	s_waitcnt lgkmcnt(8)
; template <int CTRL> __device__ __forceinline__ float dppf(float x) { return __builtin_bit_cast(float, __builtin_amdgcn_update_dpp(0, __builtin_bit_cast(int, x), CTRL, 0xF, 0xF, false)); }
; __device__ __forceinline__ void phase_rwkv_scan(const Fr& F, int jr) {
;     ...
;                 f32x4 w4 = PW[0], k4 = PW[1024], b4 = PW[2048], d4 = PW[3072], r4 = PR[0];
;                 float vv = PV[0];
;                 for (int pg = 0; pg < 64; pg += 16) {
; #pragma unroll
;                     for (int pi = 0; pi < 16; ++pi) {
;                         const int p = pg + pi, pn = p < 63 ? p + 1 : 63;
;                         const f32x4 w4n = PW[pn * 16], k4n = PW[1024 + pn * 16], b4n = PW[2048 + pn * 16], d4n = PW[3072 + pn * 16], r4n = PR[pn * 16];
;                         const float vvn = PV[pn * 32];
;                         f32x2 t = S01 * k4.xy; t = S23 * k4.zw + t; float sa = t.x + t.y;
;                         sa += dppf<0x128>(sa);
;                         const f32x2 dv01 = d4.xy * vv, dv23 = d4.zw * vv;
;                         sa += dppf<0x124>(sa);
;                         const f32x2 e01 = S01 * w4.xy + dv01;
;                         sa += dppf<0x122>(sa);
;                         const f32x2 e23 = S23 * w4.zw + dv23;
;                         sa += dppf<0x121>(sa);
;                         S01 = e01 - b4.xy * sa; S23 = e23 - b4.zw * sa;
;                         f32x2 u = S01 * r4.xy; u = S23 * r4.zw + u;
;                         PY[pi * 64] = u.x + u.y;
;                         w4 = w4n; k4 = k4n; b4 = b4n; d4 = d4n; r4 = r4n; vv = vvn;
;                     }
	ds_read_b128 v[84:87], v240 offset:14416
	ds_read_b128 v[92:95], v240 offset:31824
	ds_read_b128 v[80:83], v240 offset:5712
	ds_read_b128 v[88:91], v240 offset:23120
	v_pk_mul_f32 v[226:227], v[206:207], v[106:107] op_sel_hi:[1,0]
	v_pk_mul_f32 v[228:229], v[206:207], v[96:97] op_sel_hi:[1,0]
	v_pk_fma_f32 v[226:227], v[208:209], v[106:107], v[226:227] op_sel:[0,1,0]
	v_pk_fma_f32 v[228:229], v[208:209], v[96:97], v[228:229] op_sel:[0,1,0]
	v_pk_fma_f32 v[226:227], v[210:211], v[108:109], v[226:227] op_sel_hi:[1,0,1]
	v_pk_fma_f32 v[228:229], v[210:211], v[98:99], v[228:229] op_sel_hi:[1,0,1]
	v_pk_fma_f32 v[226:227], v[212:213], v[108:109], v[226:227] op_sel:[0,1,0]
	v_pk_fma_f32 v[228:229], v[212:213], v[98:99], v[228:229] op_sel:[0,1,0]
	v_pk_mul_f32 v[232:233], v[62:63], v[114:115] op_sel_hi:[1,0]
	v_add_f32_dpp v230, v227, v226 row_ror:8 row_mask:0xf bank_mask:0xf
	v_pk_mul_f32 v[234:235], v[62:63], v[114:115] op_sel:[0,1]
	v_pk_mul_f32 v[236:237], v[62:63], v[116:117] op_sel_hi:[1,0]
	v_add_f32_dpp v230, v230, v230 quad_perm:[1,0,3,2] row_mask:0xf bank_mask:0xf
	v_pk_mul_f32 v[238:239], v[62:63], v[116:117] op_sel:[0,1]
	ds_read_b128 v[96:99], v240 offset:40256
	v_add_f32_dpp v230, v230, v230 quad_perm:[2,3,0,1] row_mask:0xf bank_mask:0xf
	v_pk_fma_f32 v[232:233], v[206:207], v[102:103], v[232:233] op_sel_hi:[1,0,1]
	v_pk_fma_f32 v[234:235], v[208:209], v[102:103], v[234:235] op_sel:[0,1,0]
	v_add_f32_dpp v230, v230, v230 row_half_mirror row_mask:0xf bank_mask:0xf
	v_pk_fma_f32 v[236:237], v[210:211], v[104:105], v[236:237] op_sel_hi:[1,0,1]
	v_pk_fma_f32 v[238:239], v[212:213], v[104:105], v[238:239] op_sel:[0,1,0]
	v_mov_b32_dpp v231, v230 row_ror:8 row_mask:0xf bank_mask:0xf
	ds_write_b64 v217, v[228:229] offset:1152
	v_pk_fma_f32 v[206:207], v[110:111], v[230:231], v[232:233] op_sel_hi:[0,1,1] neg_lo:[1,0,0] neg_hi:[1,0,0]
	v_pk_fma_f32 v[208:209], v[110:111], v[230:231], v[234:235] op_sel:[1,0,0] neg_lo:[1,0,0] neg_hi:[1,0,0]
	v_pk_fma_f32 v[210:211], v[112:113], v[230:231], v[236:237] op_sel_hi:[0,1,1] neg_lo:[1,0,0] neg_hi:[1,0,0]
	v_pk_fma_f32 v[212:213], v[112:113], v[230:231], v[238:239] op_sel:[1,0,0] neg_lo:[1,0,0] neg_hi:[1,0,0]
	s_waitcnt lgkmcnt(7)
	ds_read_b128 v[106:109], v240 offset:14688
	ds_read_b128 v[60:63], v242 offset:49328
	ds_read_b128 v[114:117], v240 offset:32096
	ds_read_b128 v[102:105], v240 offset:5984
	ds_read_b128 v[110:113], v240 offset:23392
	v_pk_mul_f32 v[226:227], v[206:207], v[4:5] op_sel_hi:[1,0]
	v_pk_mul_f32 v[228:229], v[206:207], v[222:223] op_sel_hi:[1,0]
	v_pk_fma_f32 v[226:227], v[208:209], v[4:5], v[226:227] op_sel:[0,1,0]
	v_pk_fma_f32 v[228:229], v[208:209], v[222:223], v[228:229] op_sel:[0,1,0]
	v_pk_fma_f32 v[226:227], v[210:211], v[6:7], v[226:227] op_sel_hi:[1,0,1]
	v_pk_fma_f32 v[228:229], v[210:211], v[224:225], v[228:229] op_sel_hi:[1,0,1]
	v_pk_fma_f32 v[226:227], v[212:213], v[6:7], v[226:227] op_sel:[0,1,0]
	v_pk_fma_f32 v[228:229], v[212:213], v[224:225], v[228:229] op_sel:[0,1,0]
	v_pk_mul_f32 v[232:233], v[56:57], v[12:13] op_sel_hi:[1,0]
	v_add_f32_dpp v230, v227, v226 row_ror:8 row_mask:0xf bank_mask:0xf
	v_pk_mul_f32 v[234:235], v[56:57], v[12:13] op_sel:[0,1]
	v_pk_mul_f32 v[236:237], v[56:57], v[14:15] op_sel_hi:[1,0]
	v_add_f32_dpp v230, v230, v230 quad_perm:[1,0,3,2] row_mask:0xf bank_mask:0xf
	v_pk_mul_f32 v[238:239], v[56:57], v[14:15] op_sel:[0,1]
	ds_read_b128 v[222:225], v240 offset:40528
	v_add_f32_dpp v230, v230, v230 quad_perm:[2,3,0,1] row_mask:0xf bank_mask:0xf
	v_pk_fma_f32 v[232:233], v[206:207], v[0:1], v[232:233] op_sel_hi:[1,0,1]
	v_pk_fma_f32 v[234:235], v[208:209], v[0:1], v[234:235] op_sel:[0,1,0]
	v_add_f32_dpp v230, v230, v230 row_half_mirror row_mask:0xf bank_mask:0xf
	v_pk_fma_f32 v[236:237], v[210:211], v[2:3], v[236:237] op_sel_hi:[1,0,1]
	v_pk_fma_f32 v[238:239], v[212:213], v[2:3], v[238:239] op_sel:[0,1,0]
	v_mov_b32_dpp v231, v230 row_ror:8 row_mask:0xf bank_mask:0xf
	ds_write_b64 v217, v[228:229] offset:1728
	v_pk_fma_f32 v[206:207], v[8:9], v[230:231], v[232:233] op_sel_hi:[0,1,1] neg_lo:[1,0,0] neg_hi:[1,0,0]
	v_pk_fma_f32 v[208:209], v[8:9], v[230:231], v[234:235] op_sel:[1,0,0] neg_lo:[1,0,0] neg_hi:[1,0,0]
	v_pk_fma_f32 v[210:211], v[10:11], v[230:231], v[236:237] op_sel_hi:[0,1,1] neg_lo:[1,0,0] neg_hi:[1,0,0]
	v_pk_fma_f32 v[212:213], v[10:11], v[230:231], v[238:239] op_sel:[1,0,0] neg_lo:[1,0,0] neg_hi:[1,0,0]
	s_waitcnt lgkmcnt(8)
	ds_read_b128 v[4:7], v240 offset:14960
	ds_read_b128 v[12:15], v240 offset:32368
	ds_read_b128 v[0:3], v240 offset:6256
	ds_read_b128 v[8:11], v240 offset:23664
	v_pk_mul_f32 v[226:227], v[206:207], v[84:85] op_sel_hi:[1,0]
	v_pk_mul_f32 v[228:229], v[206:207], v[96:97] op_sel_hi:[1,0]
	v_pk_fma_f32 v[226:227], v[208:209], v[84:85], v[226:227] op_sel:[0,1,0]
	v_pk_fma_f32 v[228:229], v[208:209], v[96:97], v[228:229] op_sel:[0,1,0]
	v_pk_fma_f32 v[226:227], v[210:211], v[86:87], v[226:227] op_sel_hi:[1,0,1]
	v_pk_fma_f32 v[228:229], v[210:211], v[98:99], v[228:229] op_sel_hi:[1,0,1]
	v_pk_fma_f32 v[226:227], v[212:213], v[86:87], v[226:227] op_sel:[0,1,0]
	v_pk_fma_f32 v[228:229], v[212:213], v[98:99], v[228:229] op_sel:[0,1,0]
	v_pk_mul_f32 v[232:233], v[58:59], v[92:93] op_sel_hi:[1,0]
	v_add_f32_dpp v230, v227, v226 row_ror:8 row_mask:0xf bank_mask:0xf
	v_pk_mul_f32 v[234:235], v[58:59], v[92:93] op_sel:[0,1]
	v_pk_mul_f32 v[236:237], v[58:59], v[94:95] op_sel_hi:[1,0]
	v_add_f32_dpp v230, v230, v230 quad_perm:[1,0,3,2] row_mask:0xf bank_mask:0xf
	v_pk_mul_f32 v[238:239], v[58:59], v[94:95] op_sel:[0,1]
	ds_read_b128 v[96:99], v240 offset:40800
	v_add_f32_dpp v230, v230, v230 quad_perm:[2,3,0,1] row_mask:0xf bank_mask:0xf
	v_pk_fma_f32 v[232:233], v[206:207], v[80:81], v[232:233] op_sel_hi:[1,0,1]
	v_pk_fma_f32 v[234:235], v[208:209], v[80:81], v[234:235] op_sel:[0,1,0]
	v_add_f32_dpp v230, v230, v230 row_half_mirror row_mask:0xf bank_mask:0xf
	v_pk_fma_f32 v[236:237], v[210:211], v[82:83], v[236:237] op_sel_hi:[1,0,1]
	v_pk_fma_f32 v[238:239], v[212:213], v[82:83], v[238:239] op_sel:[0,1,0]
	v_mov_b32_dpp v231, v230 row_ror:8 row_mask:0xf bank_mask:0xf
	ds_write_b64 v217, v[228:229] offset:2304
	v_pk_fma_f32 v[206:207], v[88:89], v[230:231], v[232:233] op_sel_hi:[0,1,1] neg_lo:[1,0,0] neg_hi:[1,0,0]
	v_pk_fma_f32 v[208:209], v[88:89], v[230:231], v[234:235] op_sel:[1,0,0] neg_lo:[1,0,0] neg_hi:[1,0,0]
	v_pk_fma_f32 v[210:211], v[90:91], v[230:231], v[236:237] op_sel_hi:[0,1,1] neg_lo:[1,0,0] neg_hi:[1,0,0]
	v_pk_fma_f32 v[212:213], v[90:91], v[230:231], v[238:239] op_sel:[1,0,0] neg_lo:[1,0,0] neg_hi:[1,0,0]
	s_waitcnt lgkmcnt(7)
; template <int CTRL> __device__ __forceinline__ float dppf(float x) { return __builtin_bit_cast(float, __builtin_amdgcn_update_dpp(0, __builtin_bit_cast(int, x), CTRL, 0xF, 0xF, false)); }
; __device__ __forceinline__ void phase_rwkv_scan(const Fr& F, int jr) {
;     ...
;                 f32x4 w4 = PW[0], k4 = PW[1024], b4 = PW[2048], d4 = PW[3072], r4 = PR[0];
;                 float vv = PV[0];
;                 for (int pg = 0; pg < 64; pg += 16) {
; #pragma unroll
;                     for (int pi = 0; pi < 16; ++pi) {
;                         const int p = pg + pi, pn = p < 63 ? p + 1 : 63;
;                         const f32x4 w4n = PW[pn * 16], k4n = PW[1024 + pn * 16], b4n = PW[2048 + pn * 16], d4n = PW[3072 + pn * 16], r4n = PR[pn * 16];
;                         const float vvn = PV[pn * 32];
;                         f32x2 t = S01 * k4.xy; t = S23 * k4.zw + t; float sa = t.x + t.y;
;                         sa += dppf<0x128>(sa);
;                         const f32x2 dv01 = d4.xy * vv, dv23 = d4.zw * vv;
;                         sa += dppf<0x124>(sa);
;                         const f32x2 e01 = S01 * w4.xy + dv01;
;                         sa += dppf<0x122>(sa);
;                         const f32x2 e23 = S23 * w4.zw + dv23;
;                         sa += dppf<0x121>(sa);
;                         S01 = e01 - b4.xy * sa; S23 = e23 - b4.zw * sa;
;                         f32x2 u = S01 * r4.xy; u = S23 * r4.zw + u;
;                         PY[pi * 64] = u.x + u.y;
;                         w4 = w4n; k4 = k4n; b4 = b4n; d4 = d4n; r4 = r4n; vv = vvn;
;                     }
	ds_read_b128 v[84:87], v240 offset:15232
	ds_read_b128 v[56:59], v242 offset:49856
	ds_read_b128 v[92:95], v240 offset:32640
	ds_read_b128 v[80:83], v240 offset:6528
	ds_read_b128 v[88:91], v240 offset:23936
	v_pk_mul_f32 v[226:227], v[206:207], v[106:107] op_sel_hi:[1,0]
	v_pk_mul_f32 v[228:229], v[206:207], v[222:223] op_sel_hi:[1,0]
	v_pk_fma_f32 v[226:227], v[208:209], v[106:107], v[226:227] op_sel:[0,1,0]
	v_pk_fma_f32 v[228:229], v[208:209], v[222:223], v[228:229] op_sel:[0,1,0]
	v_pk_fma_f32 v[226:227], v[210:211], v[108:109], v[226:227] op_sel_hi:[1,0,1]
	v_pk_fma_f32 v[228:229], v[210:211], v[224:225], v[228:229] op_sel_hi:[1,0,1]
	v_pk_fma_f32 v[226:227], v[212:213], v[108:109], v[226:227] op_sel:[0,1,0]
	v_pk_fma_f32 v[228:229], v[212:213], v[224:225], v[228:229] op_sel:[0,1,0]
	v_pk_mul_f32 v[232:233], v[60:61], v[114:115] op_sel_hi:[1,0]
	v_add_f32_dpp v230, v227, v226 row_ror:8 row_mask:0xf bank_mask:0xf
	v_pk_mul_f32 v[234:235], v[60:61], v[114:115] op_sel:[0,1]
	v_pk_mul_f32 v[236:237], v[60:61], v[116:117] op_sel_hi:[1,0]
	v_add_f32_dpp v230, v230, v230 quad_perm:[1,0,3,2] row_mask:0xf bank_mask:0xf
	v_pk_mul_f32 v[238:239], v[60:61], v[116:117] op_sel:[0,1]
	ds_read_b128 v[222:225], v240 offset:41072
	v_add_f32_dpp v230, v230, v230 quad_perm:[2,3,0,1] row_mask:0xf bank_mask:0xf
	v_pk_fma_f32 v[232:233], v[206:207], v[102:103], v[232:233] op_sel_hi:[1,0,1]
	v_pk_fma_f32 v[234:235], v[208:209], v[102:103], v[234:235] op_sel:[0,1,0]
	v_add_f32_dpp v230, v230, v230 row_half_mirror row_mask:0xf bank_mask:0xf
	v_pk_fma_f32 v[236:237], v[210:211], v[104:105], v[236:237] op_sel_hi:[1,0,1]
	v_pk_fma_f32 v[238:239], v[212:213], v[104:105], v[238:239] op_sel:[0,1,0]
	v_mov_b32_dpp v231, v230 row_ror:8 row_mask:0xf bank_mask:0xf
	ds_write_b64 v217, v[228:229] offset:2880
	v_pk_fma_f32 v[206:207], v[110:111], v[230:231], v[232:233] op_sel_hi:[0,1,1] neg_lo:[1,0,0] neg_hi:[1,0,0]
	v_pk_fma_f32 v[208:209], v[110:111], v[230:231], v[234:235] op_sel:[1,0,0] neg_lo:[1,0,0] neg_hi:[1,0,0]
	v_pk_fma_f32 v[210:211], v[112:113], v[230:231], v[236:237] op_sel_hi:[0,1,1] neg_lo:[1,0,0] neg_hi:[1,0,0]
	v_pk_fma_f32 v[212:213], v[112:113], v[230:231], v[238:239] op_sel:[1,0,0] neg_lo:[1,0,0] neg_hi:[1,0,0]
	s_waitcnt lgkmcnt(8)
	ds_read_b128 v[106:109], v240 offset:15504
	ds_read_b128 v[114:117], v240 offset:32912
	ds_read_b128 v[102:105], v240 offset:6800
	ds_read_b128 v[110:113], v240 offset:24208
	v_pk_mul_f32 v[226:227], v[206:207], v[4:5] op_sel_hi:[1,0]
	v_pk_mul_f32 v[228:229], v[206:207], v[96:97] op_sel_hi:[1,0]
	v_pk_fma_f32 v[226:227], v[208:209], v[4:5], v[226:227] op_sel:[0,1,0]
	v_pk_fma_f32 v[228:229], v[208:209], v[96:97], v[228:229] op_sel:[0,1,0]
	v_pk_fma_f32 v[226:227], v[210:211], v[6:7], v[226:227] op_sel_hi:[1,0,1]
	v_pk_fma_f32 v[228:229], v[210:211], v[98:99], v[228:229] op_sel_hi:[1,0,1]
	v_pk_fma_f32 v[226:227], v[212:213], v[6:7], v[226:227] op_sel:[0,1,0]
	v_pk_fma_f32 v[228:229], v[212:213], v[98:99], v[228:229] op_sel:[0,1,0]
	v_pk_mul_f32 v[232:233], v[62:63], v[12:13] op_sel_hi:[1,0]
	v_add_f32_dpp v230, v227, v226 row_ror:8 row_mask:0xf bank_mask:0xf
	v_pk_mul_f32 v[234:235], v[62:63], v[12:13] op_sel:[0,1]
	v_pk_mul_f32 v[236:237], v[62:63], v[14:15] op_sel_hi:[1,0]
	v_add_f32_dpp v230, v230, v230 quad_perm:[1,0,3,2] row_mask:0xf bank_mask:0xf
	v_pk_mul_f32 v[238:239], v[62:63], v[14:15] op_sel:[0,1]
	ds_read_b128 v[96:99], v240 offset:41344
	v_add_f32_dpp v230, v230, v230 quad_perm:[2,3,0,1] row_mask:0xf bank_mask:0xf
	v_pk_fma_f32 v[232:233], v[206:207], v[0:1], v[232:233] op_sel_hi:[1,0,1]
	v_pk_fma_f32 v[234:235], v[208:209], v[0:1], v[234:235] op_sel:[0,1,0]
	v_add_f32_dpp v230, v230, v230 row_half_mirror row_mask:0xf bank_mask:0xf
	v_pk_fma_f32 v[236:237], v[210:211], v[2:3], v[236:237] op_sel_hi:[1,0,1]
	v_pk_fma_f32 v[238:239], v[212:213], v[2:3], v[238:239] op_sel:[0,1,0]
	v_mov_b32_dpp v231, v230 row_ror:8 row_mask:0xf bank_mask:0xf
	ds_write_b64 v217, v[228:229] offset:3456
	v_pk_fma_f32 v[206:207], v[8:9], v[230:231], v[232:233] op_sel_hi:[0,1,1] neg_lo:[1,0,0] neg_hi:[1,0,0]
	v_pk_fma_f32 v[208:209], v[8:9], v[230:231], v[234:235] op_sel:[1,0,0] neg_lo:[1,0,0] neg_hi:[1,0,0]
	v_pk_fma_f32 v[210:211], v[10:11], v[230:231], v[236:237] op_sel_hi:[0,1,1] neg_lo:[1,0,0] neg_hi:[1,0,0]
	v_pk_fma_f32 v[212:213], v[10:11], v[230:231], v[238:239] op_sel:[1,0,0] neg_lo:[1,0,0] neg_hi:[1,0,0]
	s_waitcnt lgkmcnt(7)
	ds_read_b128 v[4:7], v240 offset:15776
	ds_read_b128 v[60:63], v242 offset:50384
	ds_read_b128 v[12:15], v240 offset:33184
	ds_read_b128 v[0:3], v240 offset:7072
	ds_read_b128 v[8:11], v240 offset:24480
	v_pk_mul_f32 v[226:227], v[206:207], v[84:85] op_sel_hi:[1,0]
	v_pk_mul_f32 v[228:229], v[206:207], v[222:223] op_sel_hi:[1,0]
	v_pk_fma_f32 v[226:227], v[208:209], v[84:85], v[226:227] op_sel:[0,1,0]
	v_pk_fma_f32 v[228:229], v[208:209], v[222:223], v[228:229] op_sel:[0,1,0]
	v_pk_fma_f32 v[226:227], v[210:211], v[86:87], v[226:227] op_sel_hi:[1,0,1]
	v_pk_fma_f32 v[228:229], v[210:211], v[224:225], v[228:229] op_sel_hi:[1,0,1]
	v_pk_fma_f32 v[226:227], v[212:213], v[86:87], v[226:227] op_sel:[0,1,0]
	v_pk_fma_f32 v[228:229], v[212:213], v[224:225], v[228:229] op_sel:[0,1,0]
	v_pk_mul_f32 v[232:233], v[56:57], v[92:93] op_sel_hi:[1,0]
	v_add_f32_dpp v230, v227, v226 row_ror:8 row_mask:0xf bank_mask:0xf
	v_pk_mul_f32 v[234:235], v[56:57], v[92:93] op_sel:[0,1]
	v_pk_mul_f32 v[236:237], v[56:57], v[94:95] op_sel_hi:[1,0]
	v_add_f32_dpp v230, v230, v230 quad_perm:[1,0,3,2] row_mask:0xf bank_mask:0xf
	v_pk_mul_f32 v[238:239], v[56:57], v[94:95] op_sel:[0,1]
	ds_read_b128 v[222:225], v240 offset:41616
	v_add_f32_dpp v230, v230, v230 quad_perm:[2,3,0,1] row_mask:0xf bank_mask:0xf
	v_pk_fma_f32 v[232:233], v[206:207], v[80:81], v[232:233] op_sel_hi:[1,0,1]
	v_pk_fma_f32 v[234:235], v[208:209], v[80:81], v[234:235] op_sel:[0,1,0]
	v_add_f32_dpp v230, v230, v230 row_half_mirror row_mask:0xf bank_mask:0xf
	v_pk_fma_f32 v[236:237], v[210:211], v[82:83], v[236:237] op_sel_hi:[1,0,1]
	v_pk_fma_f32 v[238:239], v[212:213], v[82:83], v[238:239] op_sel:[0,1,0]
	v_mov_b32_dpp v231, v230 row_ror:8 row_mask:0xf bank_mask:0xf
	ds_write_b64 v217, v[228:229] offset:4032
	v_pk_fma_f32 v[206:207], v[88:89], v[230:231], v[232:233] op_sel_hi:[0,1,1] neg_lo:[1,0,0] neg_hi:[1,0,0]
	v_pk_fma_f32 v[208:209], v[88:89], v[230:231], v[234:235] op_sel:[1,0,0] neg_lo:[1,0,0] neg_hi:[1,0,0]
	v_pk_fma_f32 v[210:211], v[90:91], v[230:231], v[236:237] op_sel_hi:[0,1,1] neg_lo:[1,0,0] neg_hi:[1,0,0]
	v_pk_fma_f32 v[212:213], v[90:91], v[230:231], v[238:239] op_sel:[1,0,0] neg_lo:[1,0,0] neg_hi:[1,0,0]
	s_waitcnt lgkmcnt(8)
; template <int CTRL> __device__ __forceinline__ float dppf(float x) { return __builtin_bit_cast(float, __builtin_amdgcn_update_dpp(0, __builtin_bit_cast(int, x), CTRL, 0xF, 0xF, false)); }
; __device__ __forceinline__ void phase_rwkv_scan(const Fr& F, int jr) {
;     ...
;                 f32x4 w4 = PW[0], k4 = PW[1024], b4 = PW[2048], d4 = PW[3072], r4 = PR[0];
;                 float vv = PV[0];
;                 for (int pg = 0; pg < 64; pg += 16) {
; #pragma unroll
;                     for (int pi = 0; pi < 16; ++pi) {
;                         const int p = pg + pi, pn = p < 63 ? p + 1 : 63;
;                         const f32x4 w4n = PW[pn * 16], k4n = PW[1024 + pn * 16], b4n = PW[2048 + pn * 16], d4n = PW[3072 + pn * 16], r4n = PR[pn * 16];
;                         const float vvn = PV[pn * 32];
;                         f32x2 t = S01 * k4.xy; t = S23 * k4.zw + t; float sa = t.x + t.y;
;                         sa += dppf<0x128>(sa);
;                         const f32x2 dv01 = d4.xy * vv, dv23 = d4.zw * vv;
;                         sa += dppf<0x124>(sa);
;                         const f32x2 e01 = S01 * w4.xy + dv01;
;                         sa += dppf<0x122>(sa);
;                         const f32x2 e23 = S23 * w4.zw + dv23;
;                         sa += dppf<0x121>(sa);
;                         S01 = e01 - b4.xy * sa; S23 = e23 - b4.zw * sa;
;                         f32x2 u = S01 * r4.xy; u = S23 * r4.zw + u;
;                         PY[pi * 64] = u.x + u.y;
;                         w4 = w4n; k4 = k4n; b4 = b4n; d4 = d4n; r4 = r4n; vv = vvn;
;                     }
	ds_read_b128 v[84:87], v240 offset:16048
	ds_read_b128 v[92:95], v240 offset:33456
	ds_read_b128 v[80:83], v240 offset:7344
	ds_read_b128 v[88:91], v240 offset:24752
	v_pk_mul_f32 v[226:227], v[206:207], v[106:107] op_sel_hi:[1,0]
	v_pk_mul_f32 v[228:229], v[206:207], v[96:97] op_sel_hi:[1,0]
	v_pk_fma_f32 v[226:227], v[208:209], v[106:107], v[226:227] op_sel:[0,1,0]
	v_pk_fma_f32 v[228:229], v[208:209], v[96:97], v[228:229] op_sel:[0,1,0]
	v_pk_fma_f32 v[226:227], v[210:211], v[108:109], v[226:227] op_sel_hi:[1,0,1]
	v_pk_fma_f32 v[228:229], v[210:211], v[98:99], v[228:229] op_sel_hi:[1,0,1]
	v_pk_fma_f32 v[226:227], v[212:213], v[108:109], v[226:227] op_sel:[0,1,0]
	v_pk_fma_f32 v[228:229], v[212:213], v[98:99], v[228:229] op_sel:[0,1,0]
	v_pk_mul_f32 v[232:233], v[58:59], v[114:115] op_sel_hi:[1,0]
	v_add_f32_dpp v230, v227, v226 row_ror:8 row_mask:0xf bank_mask:0xf
	v_pk_mul_f32 v[234:235], v[58:59], v[114:115] op_sel:[0,1]
	v_pk_mul_f32 v[236:237], v[58:59], v[116:117] op_sel_hi:[1,0]
	v_add_f32_dpp v230, v230, v230 quad_perm:[1,0,3,2] row_mask:0xf bank_mask:0xf
	v_pk_mul_f32 v[238:239], v[58:59], v[116:117] op_sel:[0,1]
	ds_read_b128 v[96:99], v240 offset:41888
	v_add_f32_dpp v230, v230, v230 quad_perm:[2,3,0,1] row_mask:0xf bank_mask:0xf
	v_pk_fma_f32 v[232:233], v[206:207], v[102:103], v[232:233] op_sel_hi:[1,0,1]
	v_pk_fma_f32 v[234:235], v[208:209], v[102:103], v[234:235] op_sel:[0,1,0]
	v_add_f32_dpp v230, v230, v230 row_half_mirror row_mask:0xf bank_mask:0xf
	v_pk_fma_f32 v[236:237], v[210:211], v[104:105], v[236:237] op_sel_hi:[1,0,1]
	v_pk_fma_f32 v[238:239], v[212:213], v[104:105], v[238:239] op_sel:[0,1,0]
	v_mov_b32_dpp v231, v230 row_ror:8 row_mask:0xf bank_mask:0xf
	ds_write_b64 v217, v[228:229] offset:4608
	v_pk_fma_f32 v[206:207], v[110:111], v[230:231], v[232:233] op_sel_hi:[0,1,1] neg_lo:[1,0,0] neg_hi:[1,0,0]
	v_pk_fma_f32 v[208:209], v[110:111], v[230:231], v[234:235] op_sel:[1,0,0] neg_lo:[1,0,0] neg_hi:[1,0,0]
	v_pk_fma_f32 v[210:211], v[112:113], v[230:231], v[236:237] op_sel_hi:[0,1,1] neg_lo:[1,0,0] neg_hi:[1,0,0]
	v_pk_fma_f32 v[212:213], v[112:113], v[230:231], v[238:239] op_sel:[1,0,0] neg_lo:[1,0,0] neg_hi:[1,0,0]
	s_waitcnt lgkmcnt(7)
	ds_read_b128 v[106:109], v240 offset:16320
	ds_read_b128 v[56:59], v242 offset:50912
	ds_read_b128 v[114:117], v240 offset:33728
	ds_read_b128 v[102:105], v240 offset:7616
	ds_read_b128 v[110:113], v240 offset:25024
	v_pk_mul_f32 v[226:227], v[206:207], v[4:5] op_sel_hi:[1,0]
	v_pk_mul_f32 v[228:229], v[206:207], v[222:223] op_sel_hi:[1,0]
	v_pk_fma_f32 v[226:227], v[208:209], v[4:5], v[226:227] op_sel:[0,1,0]
	v_pk_fma_f32 v[228:229], v[208:209], v[222:223], v[228:229] op_sel:[0,1,0]
	v_pk_fma_f32 v[226:227], v[210:211], v[6:7], v[226:227] op_sel_hi:[1,0,1]
	v_pk_fma_f32 v[228:229], v[210:211], v[224:225], v[228:229] op_sel_hi:[1,0,1]
	v_pk_fma_f32 v[226:227], v[212:213], v[6:7], v[226:227] op_sel:[0,1,0]
	v_pk_fma_f32 v[228:229], v[212:213], v[224:225], v[228:229] op_sel:[0,1,0]
	v_pk_mul_f32 v[232:233], v[60:61], v[12:13] op_sel_hi:[1,0]
	v_add_f32_dpp v230, v227, v226 row_ror:8 row_mask:0xf bank_mask:0xf
	v_pk_mul_f32 v[234:235], v[60:61], v[12:13] op_sel:[0,1]
	v_pk_mul_f32 v[236:237], v[60:61], v[14:15] op_sel_hi:[1,0]
	v_add_f32_dpp v230, v230, v230 quad_perm:[1,0,3,2] row_mask:0xf bank_mask:0xf
	v_pk_mul_f32 v[238:239], v[60:61], v[14:15] op_sel:[0,1]
	ds_read_b128 v[222:225], v240 offset:42160
	v_add_f32_dpp v230, v230, v230 quad_perm:[2,3,0,1] row_mask:0xf bank_mask:0xf
	v_pk_fma_f32 v[232:233], v[206:207], v[0:1], v[232:233] op_sel_hi:[1,0,1]
	v_pk_fma_f32 v[234:235], v[208:209], v[0:1], v[234:235] op_sel:[0,1,0]
	v_add_f32_dpp v230, v230, v230 row_half_mirror row_mask:0xf bank_mask:0xf
	v_pk_fma_f32 v[236:237], v[210:211], v[2:3], v[236:237] op_sel_hi:[1,0,1]
	v_pk_fma_f32 v[238:239], v[212:213], v[2:3], v[238:239] op_sel:[0,1,0]
	v_mov_b32_dpp v231, v230 row_ror:8 row_mask:0xf bank_mask:0xf
	ds_write_b64 v217, v[228:229] offset:5184
	v_pk_fma_f32 v[206:207], v[8:9], v[230:231], v[232:233] op_sel_hi:[0,1,1] neg_lo:[1,0,0] neg_hi:[1,0,0]
	v_pk_fma_f32 v[208:209], v[8:9], v[230:231], v[234:235] op_sel:[1,0,0] neg_lo:[1,0,0] neg_hi:[1,0,0]
	v_pk_fma_f32 v[210:211], v[10:11], v[230:231], v[236:237] op_sel_hi:[0,1,1] neg_lo:[1,0,0] neg_hi:[1,0,0]
	v_pk_fma_f32 v[212:213], v[10:11], v[230:231], v[238:239] op_sel:[1,0,0] neg_lo:[1,0,0] neg_hi:[1,0,0]
	s_waitcnt lgkmcnt(8)
	ds_read_b128 v[4:7], v240 offset:16592
	ds_read_b128 v[12:15], v240 offset:34000
	ds_read_b128 v[0:3], v240 offset:7888
	ds_read_b128 v[8:11], v240 offset:25296
	v_pk_mul_f32 v[226:227], v[206:207], v[84:85] op_sel_hi:[1,0]
	v_pk_mul_f32 v[228:229], v[206:207], v[96:97] op_sel_hi:[1,0]
	v_pk_fma_f32 v[226:227], v[208:209], v[84:85], v[226:227] op_sel:[0,1,0]
	v_pk_fma_f32 v[228:229], v[208:209], v[96:97], v[228:229] op_sel:[0,1,0]
	v_pk_fma_f32 v[226:227], v[210:211], v[86:87], v[226:227] op_sel_hi:[1,0,1]
	v_pk_fma_f32 v[228:229], v[210:211], v[98:99], v[228:229] op_sel_hi:[1,0,1]
	v_pk_fma_f32 v[226:227], v[212:213], v[86:87], v[226:227] op_sel:[0,1,0]
	v_pk_fma_f32 v[228:229], v[212:213], v[98:99], v[228:229] op_sel:[0,1,0]
	v_pk_mul_f32 v[232:233], v[62:63], v[92:93] op_sel_hi:[1,0]
	v_add_f32_dpp v230, v227, v226 row_ror:8 row_mask:0xf bank_mask:0xf
	v_pk_mul_f32 v[234:235], v[62:63], v[92:93] op_sel:[0,1]
	v_pk_mul_f32 v[236:237], v[62:63], v[94:95] op_sel_hi:[1,0]
	v_add_f32_dpp v230, v230, v230 quad_perm:[1,0,3,2] row_mask:0xf bank_mask:0xf
	v_pk_mul_f32 v[238:239], v[62:63], v[94:95] op_sel:[0,1]
	ds_read_b128 v[96:99], v240 offset:42432
	v_add_f32_dpp v230, v230, v230 quad_perm:[2,3,0,1] row_mask:0xf bank_mask:0xf
	v_pk_fma_f32 v[232:233], v[206:207], v[80:81], v[232:233] op_sel_hi:[1,0,1]
	v_pk_fma_f32 v[234:235], v[208:209], v[80:81], v[234:235] op_sel:[0,1,0]
	v_add_f32_dpp v230, v230, v230 row_half_mirror row_mask:0xf bank_mask:0xf
	v_pk_fma_f32 v[236:237], v[210:211], v[82:83], v[236:237] op_sel_hi:[1,0,1]
	v_pk_fma_f32 v[238:239], v[212:213], v[82:83], v[238:239] op_sel:[0,1,0]
	v_mov_b32_dpp v231, v230 row_ror:8 row_mask:0xf bank_mask:0xf
	ds_write_b64 v217, v[228:229] offset:5760
	v_pk_fma_f32 v[206:207], v[88:89], v[230:231], v[232:233] op_sel_hi:[0,1,1] neg_lo:[1,0,0] neg_hi:[1,0,0]
	v_pk_fma_f32 v[208:209], v[88:89], v[230:231], v[234:235] op_sel:[1,0,0] neg_lo:[1,0,0] neg_hi:[1,0,0]
	v_pk_fma_f32 v[210:211], v[90:91], v[230:231], v[236:237] op_sel_hi:[0,1,1] neg_lo:[1,0,0] neg_hi:[1,0,0]
	v_pk_fma_f32 v[212:213], v[90:91], v[230:231], v[238:239] op_sel:[1,0,0] neg_lo:[1,0,0] neg_hi:[1,0,0]
	s_waitcnt lgkmcnt(7)
; template <int CTRL> __device__ __forceinline__ float dppf(float x) { return __builtin_bit_cast(float, __builtin_amdgcn_update_dpp(0, __builtin_bit_cast(int, x), CTRL, 0xF, 0xF, false)); }
; __device__ __forceinline__ void phase_rwkv_scan(const Fr& F, int jr) {
;     ...
;                 f32x4 w4 = PW[0], k4 = PW[1024], b4 = PW[2048], d4 = PW[3072], r4 = PR[0];
;                 float vv = PV[0];
;                 for (int pg = 0; pg < 64; pg += 16) {
; #pragma unroll
;                     for (int pi = 0; pi < 16; ++pi) {
;                         const int p = pg + pi, pn = p < 63 ? p + 1 : 63;
;                         const f32x4 w4n = PW[pn * 16], k4n = PW[1024 + pn * 16], b4n = PW[2048 + pn * 16], d4n = PW[3072 + pn * 16], r4n = PR[pn * 16];
;                         const float vvn = PV[pn * 32];
;                         f32x2 t = S01 * k4.xy; t = S23 * k4.zw + t; float sa = t.x + t.y;
;                         sa += dppf<0x128>(sa);
;                         const f32x2 dv01 = d4.xy * vv, dv23 = d4.zw * vv;
;                         sa += dppf<0x124>(sa);
;                         const f32x2 e01 = S01 * w4.xy + dv01;
;                         sa += dppf<0x122>(sa);
;                         const f32x2 e23 = S23 * w4.zw + dv23;
;                         sa += dppf<0x121>(sa);
;                         S01 = e01 - b4.xy * sa; S23 = e23 - b4.zw * sa;
;                         f32x2 u = S01 * r4.xy; u = S23 * r4.zw + u;
;                         PY[pi * 64] = u.x + u.y;
;                         w4 = w4n; k4 = k4n; b4 = b4n; d4 = d4n; r4 = r4n; vv = vvn;
;                     }
	ds_read_b128 v[84:87], v240 offset:16864
	ds_read_b128 v[60:63], v242 offset:51440
	ds_read_b128 v[92:95], v240 offset:34272
	ds_read_b128 v[80:83], v240 offset:8160
	ds_read_b128 v[88:91], v240 offset:25568
	v_pk_mul_f32 v[226:227], v[206:207], v[106:107] op_sel_hi:[1,0]
	v_pk_mul_f32 v[228:229], v[206:207], v[222:223] op_sel_hi:[1,0]
	v_pk_fma_f32 v[226:227], v[208:209], v[106:107], v[226:227] op_sel:[0,1,0]
	v_pk_fma_f32 v[228:229], v[208:209], v[222:223], v[228:229] op_sel:[0,1,0]
	v_pk_fma_f32 v[226:227], v[210:211], v[108:109], v[226:227] op_sel_hi:[1,0,1]
	v_pk_fma_f32 v[228:229], v[210:211], v[224:225], v[228:229] op_sel_hi:[1,0,1]
	v_pk_fma_f32 v[226:227], v[212:213], v[108:109], v[226:227] op_sel:[0,1,0]
	v_pk_fma_f32 v[228:229], v[212:213], v[224:225], v[228:229] op_sel:[0,1,0]
	v_pk_mul_f32 v[232:233], v[56:57], v[114:115] op_sel_hi:[1,0]
	v_add_f32_dpp v230, v227, v226 row_ror:8 row_mask:0xf bank_mask:0xf
	v_pk_mul_f32 v[234:235], v[56:57], v[114:115] op_sel:[0,1]
	v_pk_mul_f32 v[236:237], v[56:57], v[116:117] op_sel_hi:[1,0]
	v_add_f32_dpp v230, v230, v230 quad_perm:[1,0,3,2] row_mask:0xf bank_mask:0xf
	v_pk_mul_f32 v[238:239], v[56:57], v[116:117] op_sel:[0,1]
	ds_read_b128 v[222:225], v240 offset:42704
	v_add_f32_dpp v230, v230, v230 quad_perm:[2,3,0,1] row_mask:0xf bank_mask:0xf
	v_pk_fma_f32 v[232:233], v[206:207], v[102:103], v[232:233] op_sel_hi:[1,0,1]
	v_pk_fma_f32 v[234:235], v[208:209], v[102:103], v[234:235] op_sel:[0,1,0]
	v_add_f32_dpp v230, v230, v230 row_half_mirror row_mask:0xf bank_mask:0xf
	v_pk_fma_f32 v[236:237], v[210:211], v[104:105], v[236:237] op_sel_hi:[1,0,1]
	v_pk_fma_f32 v[238:239], v[212:213], v[104:105], v[238:239] op_sel:[0,1,0]
	v_mov_b32_dpp v231, v230 row_ror:8 row_mask:0xf bank_mask:0xf
	ds_write_b64 v217, v[228:229] offset:6336
	v_pk_fma_f32 v[206:207], v[110:111], v[230:231], v[232:233] op_sel_hi:[0,1,1] neg_lo:[1,0,0] neg_hi:[1,0,0]
	v_pk_fma_f32 v[208:209], v[110:111], v[230:231], v[234:235] op_sel:[1,0,0] neg_lo:[1,0,0] neg_hi:[1,0,0]
	v_pk_fma_f32 v[210:211], v[112:113], v[230:231], v[236:237] op_sel_hi:[0,1,1] neg_lo:[1,0,0] neg_hi:[1,0,0]
	v_pk_fma_f32 v[212:213], v[112:113], v[230:231], v[238:239] op_sel:[1,0,0] neg_lo:[1,0,0] neg_hi:[1,0,0]
	s_waitcnt lgkmcnt(8)
	ds_read_b128 v[106:109], v240 offset:17136
	ds_read_b128 v[114:117], v240 offset:34544
	ds_read_b128 v[102:105], v240 offset:8432
	ds_read_b128 v[110:113], v240 offset:25840
	v_pk_mul_f32 v[226:227], v[206:207], v[4:5] op_sel_hi:[1,0]
	v_pk_mul_f32 v[228:229], v[206:207], v[96:97] op_sel_hi:[1,0]
	v_pk_fma_f32 v[226:227], v[208:209], v[4:5], v[226:227] op_sel:[0,1,0]
	v_pk_fma_f32 v[228:229], v[208:209], v[96:97], v[228:229] op_sel:[0,1,0]
	v_pk_fma_f32 v[226:227], v[210:211], v[6:7], v[226:227] op_sel_hi:[1,0,1]
	v_pk_fma_f32 v[228:229], v[210:211], v[98:99], v[228:229] op_sel_hi:[1,0,1]
	v_pk_fma_f32 v[226:227], v[212:213], v[6:7], v[226:227] op_sel:[0,1,0]
	v_pk_fma_f32 v[228:229], v[212:213], v[98:99], v[228:229] op_sel:[0,1,0]
	v_pk_mul_f32 v[232:233], v[58:59], v[12:13] op_sel_hi:[1,0]
	v_add_f32_dpp v230, v227, v226 row_ror:8 row_mask:0xf bank_mask:0xf
	v_pk_mul_f32 v[234:235], v[58:59], v[12:13] op_sel:[0,1]
	v_pk_mul_f32 v[236:237], v[58:59], v[14:15] op_sel_hi:[1,0]
	v_add_f32_dpp v230, v230, v230 quad_perm:[1,0,3,2] row_mask:0xf bank_mask:0xf
	v_pk_mul_f32 v[238:239], v[58:59], v[14:15] op_sel:[0,1]
	ds_read_b128 v[96:99], v240 offset:42976
	v_add_f32_dpp v230, v230, v230 quad_perm:[2,3,0,1] row_mask:0xf bank_mask:0xf
	v_pk_fma_f32 v[232:233], v[206:207], v[0:1], v[232:233] op_sel_hi:[1,0,1]
	v_pk_fma_f32 v[234:235], v[208:209], v[0:1], v[234:235] op_sel:[0,1,0]
	v_add_f32_dpp v230, v230, v230 row_half_mirror row_mask:0xf bank_mask:0xf
	v_pk_fma_f32 v[236:237], v[210:211], v[2:3], v[236:237] op_sel_hi:[1,0,1]
	v_pk_fma_f32 v[238:239], v[212:213], v[2:3], v[238:239] op_sel:[0,1,0]
	v_mov_b32_dpp v231, v230 row_ror:8 row_mask:0xf bank_mask:0xf
	ds_write_b64 v217, v[228:229] offset:6912
	v_pk_fma_f32 v[206:207], v[8:9], v[230:231], v[232:233] op_sel_hi:[0,1,1] neg_lo:[1,0,0] neg_hi:[1,0,0]
	v_pk_fma_f32 v[208:209], v[8:9], v[230:231], v[234:235] op_sel:[1,0,0] neg_lo:[1,0,0] neg_hi:[1,0,0]
	v_pk_fma_f32 v[210:211], v[10:11], v[230:231], v[236:237] op_sel_hi:[0,1,1] neg_lo:[1,0,0] neg_hi:[1,0,0]
	v_pk_fma_f32 v[212:213], v[10:11], v[230:231], v[238:239] op_sel:[1,0,0] neg_lo:[1,0,0] neg_hi:[1,0,0]
	s_waitcnt lgkmcnt(7)
; __device__ __forceinline__ unsigned f2bf(float f) { unsigned u = __builtin_bit_cast(unsigned, f); return (u + 0x7fffu + ((u >> 16) & 1u)) >> 16; }
; __device__ __forceinline__ void phase_rwkv_scan(const Fr& F, int jr) {
;     ...
;                 for (int pg = 0; pg < 64; pg += 16) {
; #pragma unroll
;                     for (int pi = 0; pi < 16; ++pi) {
;                         const int p = pg + pi, pn = p < 63 ? p + 1 : 63;
;                         const f32x4 w4n = PW[pn * 16], k4n = PW[1024 + pn * 16], b4n = PW[2048 + pn * 16], d4n = PW[3072 + pn * 16], r4n = PR[pn * 16];
;                         const float vvn = PV[pn * 32];
;                         f32x2 t = S01 * k4.xy; t = S23 * k4.zw + t; float sa = t.x + t.y;
;                         sa += dppf<0x128>(sa);
;                         const f32x2 dv01 = d4.xy * vv, dv23 = d4.zw * vv;
;                         sa += dppf<0x124>(sa);
;                         const f32x2 e01 = S01 * w4.xy + dv01;
;                         sa += dppf<0x122>(sa);
;                         const f32x2 e23 = S23 * w4.zw + dv23;
;                         sa += dppf<0x121>(sa);
;                         S01 = e01 - b4.xy * sa; S23 = e23 - b4.zw * sa;
;                         f32x2 u = S01 * r4.xy; u = S23 * r4.zw + u;
;                         PY[pi * 64] = u.x + u.y;
;                         w4 = w4n; k4 = k4n; b4 = b4n; d4 = d4n; r4 = r4n; vv = vvn;
;                     }
;                     asm volatile("s_waitcnt lgkmcnt(0)" ::: "memory");
;                     {
;                         const int j = lane >> 2, q = lane & 3; const float* yp = Ypw + j * 64 + q * 16;
;                         const f32x4 a0 = *(const f32x4*)yp, a1 = *(const f32x4*)(yp + 4), a2 = *(const f32x4*)(yp + 8), a3 = *(const f32x4*)(yp + 12);
;                         const f32x4 ssum = (a0 + a1) + (a2 + a3); const float yv = (ssum.x + ssum.y) + (ssum.z + ssum.w);
;                         const size_t row = (size_t)b * TB + tokof(s, chunk * 64 + pg + j);
;                         Yb[row * D + h * 64 + 32 * half + 4 * wave + q] = (bf16)f2bf(yv);
;                     }
;                     asm volatile("s_waitcnt lgkmcnt(0)" ::: "memory");
;                 }
	v_pk_mul_f32 v[226:227], v[206:207], v[84:85] op_sel_hi:[1,0]
	v_pk_mul_f32 v[228:229], v[206:207], v[222:223] op_sel_hi:[1,0]
	v_pk_fma_f32 v[226:227], v[208:209], v[84:85], v[226:227] op_sel:[0,1,0]
	v_pk_fma_f32 v[228:229], v[208:209], v[222:223], v[228:229] op_sel:[0,1,0]
	v_pk_fma_f32 v[226:227], v[210:211], v[86:87], v[226:227] op_sel_hi:[1,0,1]
	v_pk_fma_f32 v[228:229], v[210:211], v[224:225], v[228:229] op_sel_hi:[1,0,1]
	v_pk_fma_f32 v[226:227], v[212:213], v[86:87], v[226:227] op_sel:[0,1,0]
	v_pk_fma_f32 v[228:229], v[212:213], v[224:225], v[228:229] op_sel:[0,1,0]
	v_pk_mul_f32 v[232:233], v[60:61], v[92:93] op_sel_hi:[1,0]
	v_add_f32_dpp v230, v227, v226 row_ror:8 row_mask:0xf bank_mask:0xf
	v_pk_mul_f32 v[234:235], v[60:61], v[92:93] op_sel:[0,1]
	v_pk_mul_f32 v[236:237], v[60:61], v[94:95] op_sel_hi:[1,0]
	v_add_f32_dpp v230, v230, v230 quad_perm:[1,0,3,2] row_mask:0xf bank_mask:0xf
	v_pk_mul_f32 v[238:239], v[60:61], v[94:95] op_sel:[0,1]
	ds_read_b128 v[222:225], v240 offset:43248
	v_add_f32_dpp v230, v230, v230 quad_perm:[2,3,0,1] row_mask:0xf bank_mask:0xf
	v_pk_fma_f32 v[232:233], v[206:207], v[80:81], v[232:233] op_sel_hi:[1,0,1]
	v_pk_fma_f32 v[234:235], v[208:209], v[80:81], v[234:235] op_sel:[0,1,0]
	v_add_f32_dpp v230, v230, v230 row_half_mirror row_mask:0xf bank_mask:0xf
	v_pk_fma_f32 v[236:237], v[210:211], v[82:83], v[236:237] op_sel_hi:[1,0,1]
	v_pk_fma_f32 v[238:239], v[212:213], v[82:83], v[238:239] op_sel:[0,1,0]
	v_mov_b32_dpp v231, v230 row_ror:8 row_mask:0xf bank_mask:0xf
	ds_write_b64 v217, v[228:229] offset:7488
	v_pk_fma_f32 v[206:207], v[88:89], v[230:231], v[232:233] op_sel_hi:[0,1,1] neg_lo:[1,0,0] neg_hi:[1,0,0]
	v_pk_fma_f32 v[208:209], v[88:89], v[230:231], v[234:235] op_sel:[1,0,0] neg_lo:[1,0,0] neg_hi:[1,0,0]
	v_pk_fma_f32 v[210:211], v[90:91], v[230:231], v[236:237] op_sel_hi:[0,1,1] neg_lo:[1,0,0] neg_hi:[1,0,0]
	v_pk_fma_f32 v[212:213], v[90:91], v[230:231], v[238:239] op_sel:[1,0,0] neg_lo:[1,0,0] neg_hi:[1,0,0]
	s_waitcnt lgkmcnt(3)
	v_pk_mul_f32 v[226:227], v[206:207], v[106:107] op_sel_hi:[1,0]
	v_pk_mul_f32 v[228:229], v[206:207], v[96:97] op_sel_hi:[1,0]
	v_pk_fma_f32 v[226:227], v[208:209], v[106:107], v[226:227] op_sel:[0,1,0]
	v_pk_fma_f32 v[228:229], v[208:209], v[96:97], v[228:229] op_sel:[0,1,0]
	v_pk_fma_f32 v[226:227], v[210:211], v[108:109], v[226:227] op_sel_hi:[1,0,1]
	v_pk_fma_f32 v[228:229], v[210:211], v[98:99], v[228:229] op_sel_hi:[1,0,1]
	v_pk_fma_f32 v[226:227], v[212:213], v[108:109], v[226:227] op_sel:[0,1,0]
	v_pk_fma_f32 v[228:229], v[212:213], v[98:99], v[228:229] op_sel:[0,1,0]
	v_pk_mul_f32 v[232:233], v[62:63], v[114:115] op_sel_hi:[1,0]
	v_add_f32_dpp v230, v227, v226 row_ror:8 row_mask:0xf bank_mask:0xf
	v_pk_mul_f32 v[234:235], v[62:63], v[114:115] op_sel:[0,1]
	v_pk_mul_f32 v[236:237], v[62:63], v[116:117] op_sel_hi:[1,0]
	v_add_f32_dpp v230, v230, v230 quad_perm:[1,0,3,2] row_mask:0xf bank_mask:0xf
	v_pk_mul_f32 v[238:239], v[62:63], v[116:117] op_sel:[0,1]
	s_nop 0
	v_add_f32_dpp v230, v230, v230 quad_perm:[2,3,0,1] row_mask:0xf bank_mask:0xf
	v_pk_fma_f32 v[232:233], v[206:207], v[102:103], v[232:233] op_sel_hi:[1,0,1]
	v_pk_fma_f32 v[234:235], v[208:209], v[102:103], v[234:235] op_sel:[0,1,0]
	v_add_f32_dpp v230, v230, v230 row_half_mirror row_mask:0xf bank_mask:0xf
	v_pk_fma_f32 v[236:237], v[210:211], v[104:105], v[236:237] op_sel_hi:[1,0,1]
	v_pk_fma_f32 v[238:239], v[212:213], v[104:105], v[238:239] op_sel:[0,1,0]
	v_mov_b32_dpp v231, v230 row_ror:8 row_mask:0xf bank_mask:0xf
	ds_write_b64 v217, v[228:229] offset:8064
	v_pk_fma_f32 v[206:207], v[110:111], v[230:231], v[232:233] op_sel_hi:[0,1,1] neg_lo:[1,0,0] neg_hi:[1,0,0]
	v_pk_fma_f32 v[208:209], v[110:111], v[230:231], v[234:235] op_sel:[1,0,0] neg_lo:[1,0,0] neg_hi:[1,0,0]
	v_pk_fma_f32 v[210:211], v[112:113], v[230:231], v[236:237] op_sel_hi:[0,1,1] neg_lo:[1,0,0] neg_hi:[1,0,0]
	v_pk_fma_f32 v[212:213], v[112:113], v[230:231], v[238:239] op_sel:[1,0,0] neg_lo:[1,0,0] neg_hi:[1,0,0]
	s_waitcnt lgkmcnt(2)
	v_pk_mul_f32 v[228:229], v[206:207], v[222:223] op_sel_hi:[1,0]
	v_add_u32_e32 v243, s15, v219
	v_pk_fma_f32 v[228:229], v[208:209], v[222:223], v[228:229] op_sel:[0,1,0]
	v_lshl_add_u32 v243, v243, 11, v220
	v_pk_fma_f32 v[228:229], v[210:211], v[224:225], v[228:229] op_sel_hi:[1,0,1]
	v_pk_fma_f32 v[228:229], v[212:213], v[224:225], v[228:229] op_sel:[0,1,0]
	s_waitcnt lgkmcnt(1)
	ds_write_b64 v217, v[228:229] offset:8640
	ds_read_b128 v[24:27], v218 offset:0
	ds_read_b128 v[28:31], v218 offset:16
	ds_read_b128 v[32:35], v218 offset:32
	ds_read_b128 v[36:39], v218 offset:48
	ds_read_b128 v[40:43], v218 offset:64
	ds_read_b128 v[44:47], v218 offset:80
	ds_read_b128 v[48:51], v218 offset:96
	s_waitcnt lgkmcnt(5)
	ds_read_b128 v[52:55], v218 offset:112
	v_pk_add_f32 v[24:25], v[24:25], v[26:27]
	v_pk_add_f32 v[28:29], v[28:29], v[30:31]
	s_waitcnt lgkmcnt(4)
	v_pk_add_f32 v[32:33], v[32:33], v[34:35]
	v_pk_add_f32 v[36:37], v[36:37], v[38:39]
	v_pk_add_f32 v[24:25], v[24:25], v[28:29]
	s_waitcnt lgkmcnt(2)
	v_pk_add_f32 v[40:41], v[40:41], v[42:43]
	v_pk_add_f32 v[44:45], v[44:45], v[46:47]
	v_pk_add_f32 v[32:33], v[32:33], v[36:37]
	s_waitcnt lgkmcnt(0)
	v_pk_add_f32 v[48:49], v[48:49], v[50:51]
	v_pk_add_f32 v[52:53], v[52:53], v[54:55]
	v_pk_add_f32 v[40:41], v[40:41], v[44:45]
	v_pk_add_f32 v[24:25], v[24:25], v[32:33]
	v_pk_add_f32 v[48:49], v[48:49], v[52:53]
	s_add_i32 s15, s15, s19
	v_pk_add_f32 v[40:41], v[40:41], v[48:49]
	v_pk_add_f32 v[24:25], v[24:25], v[40:41] op_sel:[0,1] op_sel_hi:[1,0]
	v_cvt_pk_bf16_f32 v244, v24, v25
	global_store_dword v243, v244, s[20:21]
	s_waitcnt lgkmcnt(0)
	s_add_i32 s10, s10, 1
	s_xor_b32 s11, s11, 0xcc00
	s_barrier
	s_cmp_lt_u32 s10, 136
	s_cbranch_scc1 .Lrw0_shc
	s_setprio 0
	s_branch .Lrw0_end

;     __device__ __forceinline__ bf16* R(int i) const { return (bf16*)(ws + OFF_R0 + (size_t)i * RSZ); }
; __device__ __forceinline__ void phase_rwkv_scan(const Fr& F, int jr) {
;     ...
;         const int half = task & 1, h = (task >> 1) & 15, b = (task >> 5) & 3, s = task >> 7;
;         bf16* Yb = F.R(s);
;         const float* w0 = F.a->in[9] + (size_t)(jr * 2 + s) * D + h * 64; const float* a0 = F.a->in[12] + (size_t)(jr * 2 + s) * D + h * 64;
;         const float* kkw = F.a->in[15] + (size_t)jr * D + h * 64; const float* kaw = F.a->in[16] + (size_t)jr * D + h * 64;
;         f32x2 S01 = {0.f, 0.f}, S23 = {0.f, 0.f};
;         const int ks = 4 * l15, rloc = 4 * wave + lq;
;         const int pt = wave & 3, ht0 = (wave >> 2) * 2;
;         const int p1 = pt * 16 + l15;
;         const int p2 = tid >> 3, j8 = tid & 7, hk0 = 8 * j8;
;         bf16x8 Bw[2][2], Ba[2][2]; float w0v[2], a0v[2];
; #pragma unroll
;         for (int hh = 0; hh < 2; ++hh) { const int hk = (ht0 + hh) * 16 + l15, e = h * 64 + hk; w0v[hh] = w0[hk]; a0v[hh] = a0[hk];
; #pragma unroll
;             for (int kst = 0; kst < 2; ++kst) { Bw[hh][kst] = *(const bf16x8*)(L2T + ((size_t)s * D + e) * 64 + 32 * kst + 8 * lq); Ba[hh][kst] = *(const bf16x8*)(L2T + ((size_t)(2 + s) * D + e) * 64 + 32 * kst + 8 * lq); } }
;         float kkc[8], kac[8], rkc[8];
; #pragma unroll
;         for (int i = 0; i < 8; ++i) { kkc[i] = kkw[hk0 + i]; kac[i] = kaw[hk0 + i]; rkc[i] = F.a->in[17][(size_t)jr * D + h * 64 + hk0 + i]; }
;         float* Bon = (float*)(F.ws + OFF_R0 + 6 * RSZ + 16 * MiB);
;         bf16x8 Aw[2], Aa[2]; u32x4 kw, rw; u32x2 vw;
;         {   const size_t row1 = (size_t)b * TB + tokof(s, p1), row2 = (size_t)b * TB + tokof(s, p2);
; #pragma unroll
;             for (int kst = 0; kst < 2; ++kst) { Aw[kst] = *(const bf16x8*)(LM + row1 * 256 + 64 * s + 32 * kst + 8 * lq); Aa[kst] = *(const bf16x8*)(LM + row1 * 256 + 128 + 64 * s + 32 * kst + 8 * lq); }
;             kw = *(const u32x4*)(Kb + row2 * D + h * 64 + hk0); rw = *(const u32x4*)(Rb + row2 * D + h * 64 + hk0); vw = *(const u32x2*)(Vb + row2 * D + h * 64 + 32 * half + 4 * j8); }
.Lrw0_hdir0:
	s_mul_i32 s16, s7, 0x1100
	v_lshlrev_b32_e32 v221, 4, v217
	s_lshl_b32 s17, s15, 6
	v_lshl_add_u32 v219, v217, 3, s17
	s_xor_b32 s18, s17, 64
	v_lshl_add_u32 v220, v217, 3, s18
	s_lshl_b32 s17, s15, 7
	v_mul_u32_u24_e32 v197, 0x110, v216
	v_add_u32_e32 v197, s17, v197
	v_lshl_add_u32 v222, v217, 4, v197
	v_lshrrev_b32_e32 v201, 1, v216
	v_mul_u32_u24_e32 v201, 0x210, v201
	v_and_b32_e32 v203, 1, v216
	v_lshl_add_u32 v201, v203, 3, v201
	s_lshl_b32 s18, s15, 8
	v_lshl_add_u32 v203, v217, 6, s18
	v_add_u32_e32 v223, v201, v203
	s_lshl_b32 s17, s6, 7
	s_add_u32 s20, s26, 0xde00000
	s_addc_u32 s21, s27, 0
	s_add_u32 s20, s20, s17
	s_addc_u32 s21, s21, 0
	s_lshl_b32 s17, s8, 7
	s_add_u32 s22, s26, 0xbc00000
	s_addc_u32 s23, s27, 0
	s_add_u32 s22, s22, s17
	s_addc_u32 s23, s23, 0
	s_add_u32 s24, s26, 0x9a00000
	s_addc_u32 s25, s27, 0
	s_add_u32 s24, s24, s17
	s_addc_u32 s25, s25, 0
	s_lshl_b32 s18, s9, 6
	s_add_i32 s17, s17, s18
	s_lshl_b32 s18, s15, 5
	s_add_i32 s17, s17, s18
	s_add_u32 s42, s26, 0x5600000
	s_addc_u32 s43, s27, 0
	s_add_u32 s42, s42, s17
	s_addc_u32 s43, s43, 0
	s_lshl_b32 s17, s8, 2
	s_add_u32 s44, s26, 0xee00000
	s_addc_u32 s45, s27, 0
	s_add_u32 s44, s44, s17
	s_addc_u32 s45, s45, 0
	s_or_b32 s17, s6, s9
	s_or_b32 s17, s17, s15
	s_cmp_eq_u32 s17, 0
	s_cselect_b32 s32, 1, 0
	s_load_dwordx2 s[46:47], s[0:1], 0x48
	s_load_dwordx2 s[48:49], s[0:1], 0x60
	s_load_dwordx2 s[50:51], s[0:1], 0x78
	s_load_dwordx2 s[52:53], s[0:1], 0x80
	s_load_dwordx2 s[54:55], s[0:1], 0x88
	s_lshl_b32 s17, s8, 8
	s_lshl_b32 s18, s15, 7
	s_add_i32 s19, s17, s18
	v_lshl_add_u32 v198, v217, 4, s19
	s_xor_b32 s18, s18, 128
	s_add_i32 s19, s17, s18
	v_lshl_add_u32 v199, v217, 4, s19
	s_waitcnt lgkmcnt(0)
	s_lshl_b32 s17, s6, 12
	s_add_u32 s46, s46, s17
	s_addc_u32 s47, s47, 0
	s_add_u32 s48, s48, s17
	s_addc_u32 s49, s49, 0
	global_load_dwordx4 v[32:35], v198, s[46:47] offset:0
	global_load_dwordx4 v[40:43], v198, s[48:49] offset:0
	global_load_dwordx4 v[64:67], v198, s[52:53] offset:0
	global_load_dwordx4 v[36:39], v198, s[46:47] offset:64
	global_load_dwordx4 v[44:47], v198, s[48:49] offset:64
	global_load_dwordx4 v[68:71], v198, s[52:53] offset:64
	global_load_dwordx4 v[48:51], v198, s[50:51] offset:0
	global_load_dwordx4 v[72:75], v198, s[54:55] offset:0
	global_load_dwordx4 v[52:55], v198, s[50:51] offset:64
	global_load_dwordx4 v[76:79], v198, s[54:55] offset:64
	global_load_dwordx4 v[56:59], v199, s[50:51] offset:0
	global_load_dwordx4 v[80:83], v199, s[54:55] offset:0
	global_load_dwordx4 v[60:63], v199, s[50:51] offset:64
	global_load_dwordx4 v[84:87], v199, s[54:55] offset:64
	s_lshl_b32 s17, s8, 6
	s_lshl_b32 s18, s15, 5
	s_add_i32 s17, s17, s18
	v_add_u32_e32 v200, s17, v196
	v_lshlrev_b32_e32 v200, 7, v200
	v_add_u32_e32 v200, v200, v221
	s_lshl_b32 s17, s6, 17
	s_add_u32 s46, s26, 0x200000
	s_addc_u32 s47, s27, 0
	s_add_u32 s46, s46, s17
	s_addc_u32 s47, s47, 0
	s_add_u32 s48, s46, 0x40000
	s_addc_u32 s49, s47, 0
	global_load_dwordx4 v[0:3], v200, s[46:47] offset:0
	global_load_dwordx4 v[16:19], v200, s[48:49] offset:0
	global_load_dwordx4 v[4:7], v200, s[46:47] offset:64
	global_load_dwordx4 v[20:23], v200, s[48:49] offset:64
	global_load_dwordx4 v[8:11], v200, s[46:47] offset:2048
	global_load_dwordx4 v[24:27], v200, s[48:49] offset:2048
	global_load_dwordx4 v[12:15], v200, s[46:47] offset:2112
	global_load_dwordx4 v[28:31], v200, s[48:49] offset:2112
	s_mov_b32 s10, 0
	s_mov_b32 s11, 0
	s_lshl_b32 s17, s10, 5
	s_cmp_lt_u32 s10, 8
	s_movk_i32 s18, 0x11ff
	s_cselect_b32 s18, 0xff, s18
	s_sub_i32 s18, s18, s17
	s_cmp_eq_u32 s6, 0
	s_cselect_b32 s17, s17, s18
	s_add_i32 s17, s17, s16
	v_add_u32_e32 v231, s17, v218
	v_lshl_add_u32 v226, v231, 9, v221
	v_lshl_add_u32 v227, v231, 11, v219
	v_lshl_add_u32 v228, v231, 11, v220
	v_lshlrev_b32_e32 v229, 3, v217
	v_lshl_add_u32 v229, v231, 11, v229
	v_lshlrev_b32_e32 v230, 6, v231
	global_load_dwordx4 v[88:91], v226, s[20:21]
	global_load_dwordx4 v[92:95], v226, s[20:21] offset:64
	global_load_dwordx4 v[96:99], v226, s[20:21] offset:256
	global_load_dwordx4 v[100:103], v226, s[20:21] offset:320
	global_load_dwordx2 v[104:105], v227, s[22:23] offset:0
	global_load_dwordx2 v[106:107], v227, s[22:23] offset:32
	global_load_dwordx2 v[108:109], v228, s[22:23] offset:0
	global_load_dwordx2 v[110:111], v228, s[22:23] offset:32
	global_load_dwordx2 v[112:113], v227, s[24:25] offset:0
	global_load_dwordx2 v[114:115], v227, s[24:25] offset:32
	global_load_dwordx2 v[116:117], v228, s[24:25] offset:0
	global_load_dwordx2 v[118:119], v228, s[24:25] offset:32
	global_load_dwordx2 v[120:121], v229, s[42:43]
	v_mov_b32_e32 v224, v222
	v_mov_b32_e32 v225, v223
	v_mov_b32_e32 v202, v230
	s_waitcnt vmcnt(0)
; __device__ __forceinline__ float sigm(float x) { return __builtin_amdgcn_rcpf(1.f + __expf(-x)); }
; template <int CTRL> __device__ __forceinline__ float dppf(float x) { return __builtin_bit_cast(float, __builtin_amdgcn_update_dpp(0, __builtin_bit_cast(int, x), CTRL, 0xF, 0xF, false)); }
; #define LDS_BAR() asm volatile("s_waitcnt lgkmcnt(0)\n\ts_barrier" ::: "memory")
; __device__ __forceinline__ void phase_rwkv_scan(const Fr& F, int jr) {
;     ...
;         for (int chunk = 0; chunk < TB / 64; ++chunk) {
; #pragma unroll
;             for (int hh = 0; hh < 2; ++hh) {
;                 const int hk = (ht0 + hh) * 16 + l15;
;                 f32x4 cw = {0.f, 0.f, 0.f, 0.f}, ca = {0.f, 0.f, 0.f, 0.f};
; #pragma unroll
;                 for (int kst = 0; kst < 2; ++kst) { cw = __builtin_amdgcn_mfma_f32_16x16x32_bf16(Aw[kst], Bw[hh][kst], cw, 0, 0, 0); ca = __builtin_amdgcn_mfma_f32_16x16x32_bf16(Aa[kst], Ba[hh][kst], ca, 0, 0, 0); }
; #pragma unroll
;                 for (int reg = 0; reg < 4; ++reg) { const int pp = pt * 16 + lq * 4 + reg;
;                     Wv[pp * 64 + hk] = __expf(-0.60653066f * sigm(w0v[hh] + cw[reg]));
;                     Av[pp * 64 + hk] = sigm(a0v[hh] + ca[reg]); }
;             }
;             LDS_BAR();
;             {
;                 const float kr[8] = {lo_bf(kw.x), hi_bf(kw.x), lo_bf(kw.y), hi_bf(kw.y), lo_bf(kw.z), hi_bf(kw.z), lo_bf(kw.w), hi_bf(kw.w)};
;                 const float rr[8] = {lo_bf(rw.x), hi_bf(rw.x), lo_bf(rw.y), hi_bf(rw.y), lo_bf(rw.z), hi_bf(rw.z), lo_bf(rw.w), hi_bf(rw.w)};
;                 float kq[8]; float ss = 0.f, bon = 0.f;
; #pragma unroll
;                 for (int i = 0; i < 8; ++i) { kq[i] = kr[i] * kkc[i]; ss += kq[i] * kq[i]; bon += rr[i] * kr[i] * rkc[i]; }
;                 ss += dppf<0xB1>(ss); ss += dppf<0x4E>(ss); ss += dppf<0x141>(ss); bon += dppf<0xB1>(bon); bon += dppf<0x4E>(bon); bon += dppf<0x141>(bon);
;                 if (s == 0 && half == 0 && j8 == 0) Bon[((size_t)b * TB + tokof(s, chunk * 64 + p2)) * 16 + h] = bon;
	v_mfma_f32_16x16x32_bf16 v[136:139], v[0:3], v[88:91], 0
	v_mfma_f32_16x16x32_bf16 v[136:139], v[4:7], v[92:95], v[136:139]
	v_mfma_f32_16x16x32_bf16 v[140:143], v[8:11], v[88:91], 0
	v_mfma_f32_16x16x32_bf16 v[140:143], v[12:15], v[92:95], v[140:143]
	v_mfma_f32_16x16x32_bf16 v[144:147], v[16:19], v[96:99], 0
	v_mfma_f32_16x16x32_bf16 v[144:147], v[20:23], v[100:103], v[144:147]
	v_mfma_f32_16x16x32_bf16 v[148:151], v[24:27], v[96:99], 0
	v_mfma_f32_16x16x32_bf16 v[148:151], v[28:31], v[100:103], v[148:151]
	v_lshlrev_b32_e32 v152, 16, v104
	v_and_b32_e32 v153, 0xffff0000, v104
	v_lshlrev_b32_e32 v154, 16, v105
	v_and_b32_e32 v155, 0xffff0000, v105
	v_lshlrev_b32_e32 v156, 16, v106
	v_and_b32_e32 v157, 0xffff0000, v106
	v_lshlrev_b32_e32 v158, 16, v107
	v_and_b32_e32 v159, 0xffff0000, v107
	v_lshlrev_b32_e32 v160, 16, v108
	v_and_b32_e32 v161, 0xffff0000, v108
	v_lshlrev_b32_e32 v162, 16, v109
	v_and_b32_e32 v163, 0xffff0000, v109
	v_lshlrev_b32_e32 v164, 16, v110
	v_and_b32_e32 v165, 0xffff0000, v110
	v_lshlrev_b32_e32 v166, 16, v111
	v_and_b32_e32 v167, 0xffff0000, v111
	v_lshlrev_b32_e32 v168, 16, v112
	v_and_b32_e32 v169, 0xffff0000, v112
	v_lshlrev_b32_e32 v170, 16, v113
	v_and_b32_e32 v171, 0xffff0000, v113
	v_lshlrev_b32_e32 v172, 16, v114
	v_and_b32_e32 v173, 0xffff0000, v114
	v_lshlrev_b32_e32 v174, 16, v115
	v_and_b32_e32 v175, 0xffff0000, v115
	v_lshlrev_b32_e32 v192, 16, v120
	v_and_b32_e32 v193, 0xffff0000, v120
	v_lshlrev_b32_e32 v194, 16, v121
	v_and_b32_e32 v195, 0xffff0000, v121
	v_pk_mul_f32 v[176:177], v[152:153], v[48:49]
	v_pk_mul_f32 v[178:179], v[154:155], v[50:51]
	v_pk_mul_f32 v[180:181], v[156:157], v[52:53]
	v_pk_mul_f32 v[182:183], v[158:159], v[54:55]
	v_pk_mul_f32 v[184:185], v[160:161], v[56:57]
	v_pk_mul_f32 v[186:187], v[162:163], v[58:59]
	v_pk_mul_f32 v[188:189], v[164:165], v[60:61]
	v_pk_mul_f32 v[190:191], v[166:167], v[62:63]
	v_pk_mul_f32 v[196:197], v[176:177], v[176:177]
	v_pk_mul_f32 v[198:199], v[178:179], v[178:179]
	v_pk_fma_f32 v[196:197], v[180:181], v[180:181], v[196:197]
	v_pk_fma_f32 v[198:199], v[182:183], v[182:183], v[198:199]
	v_pk_fma_f32 v[196:197], v[184:185], v[184:185], v[196:197]
	v_pk_fma_f32 v[198:199], v[186:187], v[186:187], v[198:199]
	v_pk_fma_f32 v[196:197], v[188:189], v[188:189], v[196:197]
	v_pk_fma_f32 v[198:199], v[190:191], v[190:191], v[198:199]
	s_nop 0
	v_pk_add_f32 v[196:197], v[196:197], v[198:199]
	s_cmp_eq_u32 s32, 0
	s_cbranch_scc1 .Lrw0_hnbc0
	v_mul_f32_e32 v208, v168, v152
	v_mul_f32_e32 v209, v169, v153
	v_mul_f32_e32 v210, v170, v154
	v_mul_f32_e32 v211, v171, v155
	v_mul_f32_e32 v234, v72, v208
	v_fmac_f32_e32 v234, v73, v209
	v_fmac_f32_e32 v234, v74, v210
	v_fmac_f32_e32 v234, v75, v211
	v_mul_f32_e32 v208, v172, v156
	v_mul_f32_e32 v209, v173, v157
	v_mul_f32_e32 v210, v174, v158
	v_mul_f32_e32 v211, v175, v159
	v_fmac_f32_e32 v234, v76, v208
	v_fmac_f32_e32 v234, v77, v209
	v_fmac_f32_e32 v234, v78, v210
	v_fmac_f32_e32 v234, v79, v211
	v_lshlrev_b32_e32 v204, 16, v116
	v_and_b32_e32 v205, 0xffff0000, v116
	v_lshlrev_b32_e32 v206, 16, v117
	v_and_b32_e32 v207, 0xffff0000, v117
	v_mul_f32_e32 v208, v204, v160
	v_mul_f32_e32 v209, v205, v161
	v_mul_f32_e32 v210, v206, v162
	v_mul_f32_e32 v211, v207, v163
	v_fmac_f32_e32 v234, v80, v208
	v_fmac_f32_e32 v234, v81, v209
	v_fmac_f32_e32 v234, v82, v210
	v_fmac_f32_e32 v234, v83, v211
	v_lshlrev_b32_e32 v204, 16, v118
	v_and_b32_e32 v205, 0xffff0000, v118
	v_lshlrev_b32_e32 v206, 16, v119
	v_and_b32_e32 v207, 0xffff0000, v119
	v_mul_f32_e32 v208, v204, v164
	v_mul_f32_e32 v209, v205, v165
	v_mul_f32_e32 v210, v206, v166
	v_mul_f32_e32 v211, v207, v167
	v_fmac_f32_e32 v234, v84, v208
	v_fmac_f32_e32 v234, v85, v209
	v_fmac_f32_e32 v234, v86, v210
	v_fmac_f32_e32 v234, v87, v211

; __device__ __forceinline__ float sigm(float x) { return __builtin_amdgcn_rcpf(1.f + __expf(-x)); }
; template <int CTRL> __device__ __forceinline__ float dppf(float x) { return __builtin_bit_cast(float, __builtin_amdgcn_update_dpp(0, __builtin_bit_cast(int, x), CTRL, 0xF, 0xF, false)); }
; __device__ __forceinline__ void phase_rwkv_scan(const Fr& F, int jr) {
;     ...
;                     Wv[pp * 64 + hk] = __expf(-0.60653066f * sigm(w0v[hh] + cw[reg]));
;                     Av[pp * 64 + hk] = sigm(a0v[hh] + ca[reg]); }
;     ...
;                 ss += dppf<0xB1>(ss); ss += dppf<0x4E>(ss); ss += dppf<0x141>(ss); bon += dppf<0xB1>(bon); bon += dppf<0x4E>(bon); bon += dppf<0x141>(bon);
;                 if (s == 0 && half == 0 && j8 == 0) Bon[((size_t)b * TB + tokof(s, chunk * 64 + p2)) * 16 + h] = bon;
;                 const float inv = 1.f / fmaxf(sqrtf(ss), 1e-12f);
;                 const f32x4 av0 = *(const f32x4*)(Av + p2 * 64 + hk0), av1 = *(const f32x4*)(Av + p2 * 64 + hk0 + 4);
;                 const float av[8] = {av0.x, av0.y, av0.z, av0.w, av1.x, av1.y, av1.z, av1.w};
;                 float o1[8], o2[8], o3[8];
; #pragma unroll
;                 for (int i = 0; i < 8; ++i) { const float kkv = kq[i] * inv; o1[i] = kkv; o2[i] = kkv * av[i]; o3[i] = kr[i] * (1.f + (av[i] - 1.f) * kac[i]); }
;                 const int o = p2 * 64 + hk0;
;                 *(f32x4*)(KK + o) = (f32x4){o1[0], o1[1], o1[2], o1[3]}; *(f32x4*)(KK + o + 4) = (f32x4){o1[4], o1[5], o1[6], o1[7]};
;                 *(f32x4*)(Bv + o) = (f32x4){o2[0], o2[1], o2[2], o2[3]}; *(f32x4*)(Bv + o + 4) = (f32x4){o2[4], o2[5], o2[6], o2[7]};
;                 *(f32x4*)(KD + o) = (f32x4){o3[0], o3[1], o3[2], o3[3]}; *(f32x4*)(KD + o + 4) = (f32x4){o3[4], o3[5], o3[6], o3[7]};
;                 *(f32x4*)(Rr + o) = (f32x4){rr[0], rr[1], rr[2], rr[3]}; *(f32x4*)(Rr + o + 4) = (f32x4){rr[4], rr[5], rr[6], rr[7]};
;                 *(f32x4*)(Vv + p2 * 32 + 4 * j8) = (f32x4){lo_bf(vw.x), hi_bf(vw.x), lo_bf(vw.y), hi_bf(vw.y)};
.Lrw0_hnl0:
	v_mov_b32_e32 v196, v232
	s_nop 1
	v_permlane16_swap_b32_e32 v232, v196
	s_nop 1
	v_add_f32_e32 v232, v232, v196
	v_mov_b32_e32 v196, v232
	s_nop 1
	v_permlane32_swap_b32_e32 v232, v196
	s_nop 1
	v_add_f32_e32 v232, v232, v196
	v_mul_f32_e32 v197, 0x4f800000, v232
	v_mov_b32_e32 v198, 0xf800000
	v_cmp_gt_f32_e32 vcc, v198, v232
	s_nop 1
	v_cndmask_b32_e32 v196, v232, v197, vcc
	v_sqrt_f32_e32 v197, v196
	s_nop 0
	v_add_u32_e32 v198, -1, v197
	v_fma_f32 v200, -v198, v197, v196
	v_add_u32_e32 v199, 1, v197
	v_cmp_ge_f32_e64 s[56:57], 0, v200
	s_nop 1
	v_cndmask_b32_e64 v198, v197, v198, s[56:57]
	v_fma_f32 v197, -v199, v197, v196
	v_cmp_lt_f32_e64 s[56:57], 0, v197
	s_nop 1
	v_cndmask_b32_e64 v197, v198, v199, s[56:57]
	v_mul_f32_e32 v198, 0x37800000, v197
	v_cndmask_b32_e32 v197, v197, v198, vcc
	v_mov_b32_e32 v198, 0x260
	v_cmp_class_f32_e32 vcc, v196, v198
	s_nop 1
	v_cndmask_b32_e32 v196, v197, v196, vcc
	v_max_f32_e32 v196, 0x2b8cbccc, v196
	v_div_scale_f32 v197, s[56:57], v196, v196, 1.0
	v_rcp_f32_e32 v198, v197
	s_nop 0
	v_fma_f32 v199, -v197, v198, 1.0
	v_fmac_f32_e32 v198, v199, v198
	v_div_scale_f32 v199, vcc, 1.0, v196, 1.0
	v_mul_f32_e32 v200, v199, v198
	v_fma_f32 v201, -v197, v200, v199
	v_fmac_f32_e32 v200, v201, v198
	v_fma_f32 v197, -v197, v200, v199
	s_nop 0
	v_div_fmas_f32 v197, v197, v198, v200
	v_div_fixup_f32 v232, v197, v196, 1.0
	v_pk_add_f32 v[136:137], v[32:33], v[136:137]
	v_pk_add_f32 v[138:139], v[34:35], v[138:139]
	v_pk_add_f32 v[144:145], v[40:41], v[144:145]
	v_pk_add_f32 v[146:147], v[42:43], v[146:147]
	v_pk_add_f32 v[140:141], v[36:37], v[140:141]
	v_pk_add_f32 v[142:143], v[38:39], v[142:143]
	v_pk_add_f32 v[148:149], v[44:45], v[148:149]
	v_pk_add_f32 v[150:151], v[46:47], v[150:151]
	v_pk_mul_f32 v[136:137], v[136:137], v[122:123]
	v_pk_mul_f32 v[138:139], v[138:139], v[122:123]
	v_pk_mul_f32 v[144:145], v[144:145], v[122:123]
	v_pk_mul_f32 v[146:147], v[146:147], v[122:123]
	v_pk_mul_f32 v[140:141], v[140:141], v[122:123]
	v_pk_mul_f32 v[142:143], v[142:143], v[122:123]
	v_pk_mul_f32 v[148:149], v[148:149], v[122:123]
	v_pk_mul_f32 v[150:151], v[150:151], v[122:123]
	v_exp_f32_e32 v136, v136
	v_exp_f32_e32 v137, v137
	v_exp_f32_e32 v138, v138
	v_exp_f32_e32 v139, v139
	v_exp_f32_e32 v144, v144
	v_exp_f32_e32 v145, v145
	v_exp_f32_e32 v146, v146
	v_exp_f32_e32 v147, v147
	v_exp_f32_e32 v140, v140
	v_exp_f32_e32 v141, v141
	v_exp_f32_e32 v142, v142
	v_exp_f32_e32 v143, v143
	v_exp_f32_e32 v148, v148
	v_exp_f32_e32 v149, v149
	v_exp_f32_e32 v150, v150
	v_exp_f32_e32 v151, v151
	v_pk_add_f32 v[136:137], v[136:137], 1.0 op_sel_hi:[1,0]
	v_pk_add_f32 v[138:139], v[138:139], 1.0 op_sel_hi:[1,0]
	v_pk_add_f32 v[144:145], v[144:145], 1.0 op_sel_hi:[1,0]
	v_pk_add_f32 v[146:147], v[146:147], 1.0 op_sel_hi:[1,0]
	v_pk_add_f32 v[140:141], v[140:141], 1.0 op_sel_hi:[1,0]
	v_pk_add_f32 v[142:143], v[142:143], 1.0 op_sel_hi:[1,0]
	v_pk_add_f32 v[148:149], v[148:149], 1.0 op_sel_hi:[1,0]
	v_pk_add_f32 v[150:151], v[150:151], 1.0 op_sel_hi:[1,0]
	v_rcp_f32_e32 v136, v136
	v_rcp_f32_e32 v137, v137
	v_rcp_f32_e32 v138, v138
	v_rcp_f32_e32 v139, v139
	v_rcp_f32_e32 v144, v144
	v_rcp_f32_e32 v145, v145
	v_rcp_f32_e32 v146, v146
	v_rcp_f32_e32 v147, v147
	v_rcp_f32_e32 v140, v140
	v_rcp_f32_e32 v141, v141
	v_rcp_f32_e32 v142, v142
	v_rcp_f32_e32 v143, v143
	v_rcp_f32_e32 v148, v148
	v_rcp_f32_e32 v149, v149
	v_rcp_f32_e32 v150, v150
	v_rcp_f32_e32 v151, v151
	v_pk_mul_f32 v[136:137], v[136:137], v[124:125]
	v_pk_mul_f32 v[138:139], v[138:139], v[124:125]
	v_pk_mul_f32 v[140:141], v[140:141], v[124:125]
	v_pk_mul_f32 v[142:143], v[142:143], v[124:125]
	v_pk_mul_f32 v[136:137], v[136:137], v[126:127]
	v_pk_mul_f32 v[138:139], v[138:139], v[126:127]
	v_pk_mul_f32 v[140:141], v[140:141], v[126:127]
	v_pk_mul_f32 v[142:143], v[142:143], v[126:127]
	v_exp_f32_e32 v136, v136
	v_exp_f32_e32 v137, v137
	v_exp_f32_e32 v138, v138
	v_exp_f32_e32 v139, v139
	v_exp_f32_e32 v140, v140
	v_exp_f32_e32 v141, v141
	v_exp_f32_e32 v142, v142
	v_exp_f32_e32 v143, v143
	v_pk_mul_f32 v[204:205], v[176:177], v[232:233] op_sel_hi:[1,0]
	v_pk_mul_f32 v[206:207], v[178:179], v[232:233] op_sel_hi:[1,0]
	v_pk_add_f32 v[212:213], v[144:145], -1.0 op_sel_hi:[1,0]
	v_pk_add_f32 v[214:215], v[146:147], -1.0 op_sel_hi:[1,0]
	v_pk_mul_f32 v[208:209], v[204:205], v[144:145]
	v_pk_mul_f32 v[210:211], v[206:207], v[146:147]
	v_pk_fma_f32 v[212:213], v[64:65], v[212:213], 1.0 op_sel_hi:[1,1,0]
	v_pk_fma_f32 v[214:215], v[66:67], v[214:215], 1.0 op_sel_hi:[1,1,0]
	ds_write_b128 v224, v[136:139] offset:0
	ds_write_b128 v224, v[204:207] offset:8704
	v_pk_mul_f32 v[212:213], v[212:213], v[152:153]
	v_pk_mul_f32 v[214:215], v[214:215], v[154:155]
	ds_write_b128 v224, v[208:211] offset:17408
	ds_write_b128 v224, v[168:171] offset:34816
	ds_write_b128 v224, v[212:215] offset:26112
	v_pk_mul_f32 v[204:205], v[180:181], v[232:233] op_sel_hi:[1,0]
	v_pk_mul_f32 v[206:207], v[182:183], v[232:233] op_sel_hi:[1,0]
	v_pk_add_f32 v[212:213], v[148:149], -1.0 op_sel_hi:[1,0]
	v_pk_add_f32 v[214:215], v[150:151], -1.0 op_sel_hi:[1,0]
	v_pk_mul_f32 v[208:209], v[204:205], v[148:149]
	v_pk_mul_f32 v[210:211], v[206:207], v[150:151]
	v_pk_fma_f32 v[212:213], v[68:69], v[212:213], 1.0 op_sel_hi:[1,1,0]
	v_pk_fma_f32 v[214:215], v[70:71], v[214:215], 1.0 op_sel_hi:[1,1,0]
	ds_write_b128 v224, v[140:143] offset:64
	ds_write_b128 v224, v[204:207] offset:8768
	v_pk_mul_f32 v[212:213], v[212:213], v[156:157]
	v_pk_mul_f32 v[214:215], v[214:215], v[158:159]
	ds_write_b128 v224, v[208:211] offset:17472
	ds_write_b128 v224, v[172:175] offset:34880
	ds_write_b128 v224, v[212:215] offset:26176
	v_mov_b32_e32 v204, v193
	v_mov_b32_e32 v205, v192
	v_mov_b32_e32 v206, v195
	v_mov_b32_e32 v207, v194
	ds_write_b64 v225, v[192:193] offset:43520
	ds_write_b64 v225, v[204:205] offset:43536
	ds_write_b64 v225, v[194:195] offset:43552
	ds_write_b64 v225, v[206:207] offset:43568
	s_cmp_eq_u32 s32, 0
	s_cbranch_scc1 .Lrw0_hnb0
	v_mov_b32_e32 v196, v234
	s_nop 1
	v_permlane16_swap_b32_e32 v234, v196
	s_nop 1
	v_add_f32_e32 v234, v234, v196
	v_mov_b32_e32 v196, v234
	s_nop 1
	v_permlane32_swap_b32_e32 v234, v196
	s_nop 1
	v_add_f32_e32 v234, v234, v196
	v_cmp_gt_u32_e32 vcc, 16, v130
	s_and_saveexec_b64 s[56:57], vcc
	global_store_dword v202, v234, s[44:45]
	s_mov_b64 exec, s[56:57]

;     __device__ __forceinline__ bf16* R(int i) const { return (bf16*)(ws + OFF_R0 + (size_t)i * RSZ); }
; __device__ __forceinline__ void phase_rwkv_scan(const Fr& F, int jr) {
;     ...
;     const int bxs = (int)blockIdx.x, bxcd = (gridDim.x == 256) ? (bxs & 7) * 32 + (bxs >> 3) : bxs;
;     for (int task = bxcd; task < 256; task += gridDim.x) {
;         const int half = task & 1, h = (task >> 1) & 15, b = (task >> 5) & 3, s = task >> 7;
;         bf16* Yb = F.R(s);
;         const float* w0 = F.a->in[9] + (size_t)(jr * 2 + s) * D + h * 64; const float* a0 = F.a->in[12] + (size_t)(jr * 2 + s) * D + h * 64;
;         const float* kkw = F.a->in[15] + (size_t)jr * D + h * 64; const float* kaw = F.a->in[16] + (size_t)jr * D + h * 64;
;         f32x2 S01 = {0.f, 0.f}, S23 = {0.f, 0.f};
;         const int ks = 4 * l15, rloc = 4 * wave + lq;
;         const int pt = wave & 3, ht0 = (wave >> 2) * 2;
;     ...
;                 float* Ypw = Yp + wave * 1024;
;                 unsigned a1 = (unsigned)(size_t)(__attribute__((address_space(3))) float*)(Wv + ks), a2 = (unsigned)(size_t)(__attribute__((address_space(3))) float*)(Rr + ks),
;                          a3 = (unsigned)(size_t)(__attribute__((address_space(3))) float*)(Vv + rloc), a4 = (unsigned)(size_t)(__attribute__((address_space(3))) float*)(Ypw + lane);
;                 asm volatile("" : "+v"(a1), "+v"(a2), "+v"(a3), "+v"(a4));
;                 typedef const __attribute__((address_space(3))) f32x4* lp4; typedef const __attribute__((address_space(3))) float* lp1; typedef __attribute__((address_space(3))) float* lw1;
;                 const lp4 PW = (lp4)a1, PR = (lp4)a2; const lp1 PV = (lp1)a3; const lw1 PY = (lw1)a4;
.LBB0_2530:
	s_cmp_lt_i32 s34, 26
	s_cselect_b64 s[6:7], -1, 0
	s_cmp_gt_i32 s35, 25
	s_cselect_b64 s[8:9], -1, 0
	s_and_b64 s[6:7], s[6:7], s[8:9]
	s_andn2_b64 vcc, exec, s[6:7]
	s_cbranch_vccnz .LBB0_2542
	s_and_b32 s3, s2, 7
	s_lshl_b32 s3, s3, 5
	s_lshr_b32 s6, s2, 3
	s_add_i32 s3, s3, s6
	s_lshr_b32 s6, s3, 7
	s_bfe_u32 s7, s3, 0x20005
	s_bfe_u32 s8, s3, 0x40001
	s_and_b32 s9, s3, 1
	s_cmp_gt_u32 s68, 3
	s_cbranch_scc1 .Lrw3_helper
	s_setprio 3
	v_mov_b32_e32 v206, 0
	v_mov_b32_e32 v207, 0
	v_mov_b32_e32 v208, 0
	v_mov_b32_e32 v209, 0
	v_mov_b32_e32 v210, 0
	v_mov_b32_e32 v211, 0
	v_mov_b32_e32 v212, 0
	v_mov_b32_e32 v213, 0
	v_and_b32_e32 v243, 15, v130
	v_lshlrev_b32_e32 v214, 4, v243
	v_lshrrev_b32_e32 v244, 4, v130
	v_lshrrev_b32_e32 v245, 3, v243
	v_lshl_add_u32 v245, v244, 1, v245
	s_lshl_b32 s16, s68, 3
	v_add_u32_e32 v245, s16, v245
	v_lshlrev_b32_e32 v216, 4, v245
	s_mul_i32 s16, s68, 0x2400
	s_add_i32 s16, s16, 0x19800
	s_cmp_eq_u32 s68, 3
	s_cselect_b32 s16, 0x20800, s16
	v_mul_u32_u24_e32 v218, 0x90, v130
	v_add_u32_e32 v218, s16, v218
	v_mul_u32_u24_e32 v244, 0x90, v244
	v_lshl_add_u32 v244, v243, 3, v244
	v_add_u32_e32 v217, s16, v244
	v_lshrrev_b32_e32 v219, 2, v130
	s_cmp_eq_u32 s6, 0
	s_cbranch_scc1 .Lrw3_sdir0
	v_sub_u32_e32 v219, 0, v219

;     __device__ __forceinline__ bf16* R(int i) const { return (bf16*)(ws + OFF_R0 + (size_t)i * RSZ); }
; __device__ __forceinline__ void phase_rwkv_scan(const Fr& F, int jr) {
;     ...
;         const int half = task & 1, h = (task >> 1) & 15, b = (task >> 5) & 3, s = task >> 7;
;         bf16* Yb = F.R(s);
;         const float* w0 = F.a->in[9] + (size_t)(jr * 2 + s) * D + h * 64; const float* a0 = F.a->in[12] + (size_t)(jr * 2 + s) * D + h * 64;
;         const float* kkw = F.a->in[15] + (size_t)jr * D + h * 64; const float* kaw = F.a->in[16] + (size_t)jr * D + h * 64;
;         f32x2 S01 = {0.f, 0.f}, S23 = {0.f, 0.f};
;         const int ks = 4 * l15, rloc = 4 * wave + lq;
;         const int pt = wave & 3, ht0 = (wave >> 2) * 2;
;         const int p1 = pt * 16 + l15;
;         const int p2 = tid >> 3, j8 = tid & 7, hk0 = 8 * j8;
;         bf16x8 Bw[2][2], Ba[2][2]; float w0v[2], a0v[2];
; #pragma unroll
;         for (int hh = 0; hh < 2; ++hh) { const int hk = (ht0 + hh) * 16 + l15, e = h * 64 + hk; w0v[hh] = w0[hk]; a0v[hh] = a0[hk];
; #pragma unroll
;             for (int kst = 0; kst < 2; ++kst) { Bw[hh][kst] = *(const bf16x8*)(L2T + ((size_t)s * D + e) * 64 + 32 * kst + 8 * lq); Ba[hh][kst] = *(const bf16x8*)(L2T + ((size_t)(2 + s) * D + e) * 64 + 32 * kst + 8 * lq); } }
;         float kkc[8], kac[8], rkc[8];
; #pragma unroll
;         for (int i = 0; i < 8; ++i) { kkc[i] = kkw[hk0 + i]; kac[i] = kaw[hk0 + i]; rkc[i] = F.a->in[17][(size_t)jr * D + h * 64 + hk0 + i]; }
;         float* Bon = (float*)(F.ws + OFF_R0 + 6 * RSZ + 16 * MiB);
;         bf16x8 Aw[2], Aa[2]; u32x4 kw, rw; u32x2 vw;
;         {   const size_t row1 = (size_t)b * TB + tokof(s, p1), row2 = (size_t)b * TB + tokof(s, p2);
; #pragma unroll
;             for (int kst = 0; kst < 2; ++kst) { Aw[kst] = *(const bf16x8*)(LM + row1 * 256 + 64 * s + 32 * kst + 8 * lq); Aa[kst] = *(const bf16x8*)(LM + row1 * 256 + 128 + 64 * s + 32 * kst + 8 * lq); }
;             kw = *(const u32x4*)(Kb + row2 * D + h * 64 + hk0); rw = *(const u32x4*)(Rb + row2 * D + h * 64 + hk0); vw = *(const u32x2*)(Vb + row2 * D + h * 64 + 32 * half + 4 * j8); }
.Lrw3_hdir0:
	s_mul_i32 s16, s7, 0x1100
	v_lshlrev_b32_e32 v221, 4, v217
	s_lshl_b32 s17, s15, 6
	v_lshl_add_u32 v219, v217, 3, s17
	s_xor_b32 s18, s17, 64
	v_lshl_add_u32 v220, v217, 3, s18
	s_lshl_b32 s17, s15, 7
	v_mul_u32_u24_e32 v197, 0x110, v216
	v_add_u32_e32 v197, s17, v197
	v_lshl_add_u32 v222, v217, 4, v197
	v_lshrrev_b32_e32 v201, 1, v216
	v_mul_u32_u24_e32 v201, 0x210, v201
	v_and_b32_e32 v203, 1, v216
	v_lshl_add_u32 v201, v203, 3, v201
	s_lshl_b32 s18, s15, 8
	v_lshl_add_u32 v203, v217, 6, s18
	v_add_u32_e32 v223, v201, v203
	s_lshl_b32 s17, s6, 7
	s_add_u32 s20, s26, 0xde00000
	s_addc_u32 s21, s27, 0
	s_add_u32 s20, s20, s17
	s_addc_u32 s21, s21, 0
	s_lshl_b32 s17, s8, 7
	s_add_u32 s22, s26, 0xbc00000
	s_addc_u32 s23, s27, 0
	s_add_u32 s22, s22, s17
	s_addc_u32 s23, s23, 0
	s_add_u32 s24, s26, 0x9a00000
	s_addc_u32 s25, s27, 0
	s_add_u32 s24, s24, s17
	s_addc_u32 s25, s25, 0
	s_lshl_b32 s18, s9, 6
	s_add_i32 s17, s17, s18
	s_lshl_b32 s18, s15, 5
	s_add_i32 s17, s17, s18
	s_add_u32 s42, s26, 0x5600000
	s_addc_u32 s43, s27, 0
	s_add_u32 s42, s42, s17
	s_addc_u32 s43, s43, 0
	s_lshl_b32 s17, s8, 2
	s_add_u32 s44, s26, 0xee00000
	s_addc_u32 s45, s27, 0
	s_add_u32 s44, s44, s17
	s_addc_u32 s45, s45, 0
	s_or_b32 s17, s6, s9
	s_or_b32 s17, s17, s15
	s_cmp_eq_u32 s17, 0
	s_cselect_b32 s32, 1, 0
	s_load_dwordx2 s[46:47], s[0:1], 0x48
	s_load_dwordx2 s[48:49], s[0:1], 0x60
	s_load_dwordx2 s[50:51], s[0:1], 0x78
	s_load_dwordx2 s[52:53], s[0:1], 0x80
	s_load_dwordx2 s[54:55], s[0:1], 0x88
	s_lshl_b32 s17, s8, 8
	s_lshl_b32 s18, s15, 7
	s_add_i32 s19, s17, s18
	v_lshl_add_u32 v198, v217, 4, s19
	s_xor_b32 s18, s18, 128
	s_add_i32 s19, s17, s18
	v_lshl_add_u32 v199, v217, 4, s19
	s_waitcnt lgkmcnt(0)
	s_lshl_b32 s17, s6, 12
	s_add_u32 s46, s46, s17
	s_addc_u32 s47, s47, 0
	s_add_u32 s48, s48, s17
	s_addc_u32 s49, s49, 0
	s_add_u32 s46, s46, 0x2000
	s_addc_u32 s47, s47, 0
	s_add_u32 s48, s48, 0x2000
	s_addc_u32 s49, s49, 0
	s_add_u32 s50, s50, 0x1000
	s_addc_u32 s51, s51, 0
	s_add_u32 s52, s52, 0x1000
	s_addc_u32 s53, s53, 0
	s_add_u32 s54, s54, 0x1000
	s_addc_u32 s55, s55, 0
	global_load_dwordx4 v[32:35], v198, s[46:47] offset:0
	global_load_dwordx4 v[40:43], v198, s[48:49] offset:0
	global_load_dwordx4 v[64:67], v198, s[52:53] offset:0
	global_load_dwordx4 v[36:39], v198, s[46:47] offset:64
	global_load_dwordx4 v[44:47], v198, s[48:49] offset:64
	global_load_dwordx4 v[68:71], v198, s[52:53] offset:64
	global_load_dwordx4 v[48:51], v198, s[50:51] offset:0
	global_load_dwordx4 v[72:75], v198, s[54:55] offset:0
	global_load_dwordx4 v[52:55], v198, s[50:51] offset:64
	global_load_dwordx4 v[76:79], v198, s[54:55] offset:64
	global_load_dwordx4 v[56:59], v199, s[50:51] offset:0
	global_load_dwordx4 v[80:83], v199, s[54:55] offset:0
	global_load_dwordx4 v[60:63], v199, s[50:51] offset:64
	global_load_dwordx4 v[84:87], v199, s[54:55] offset:64
	s_lshl_b32 s17, s8, 6
	s_lshl_b32 s18, s15, 5
	s_add_i32 s17, s17, s18
	v_add_u32_e32 v200, s17, v196
	v_lshlrev_b32_e32 v200, 7, v200
	v_add_u32_e32 v200, v200, v221
	s_lshl_b32 s17, s6, 17
	s_add_u32 s46, s26, 0x200000
	s_addc_u32 s47, s27, 0
	s_add_u32 s46, s46, s17
	s_addc_u32 s47, s47, 0
	s_add_u32 s48, s46, 0x40000
	s_addc_u32 s49, s47, 0
	global_load_dwordx4 v[0:3], v200, s[46:47] offset:0
	global_load_dwordx4 v[16:19], v200, s[48:49] offset:0
	global_load_dwordx4 v[4:7], v200, s[46:47] offset:64
	global_load_dwordx4 v[20:23], v200, s[48:49] offset:64
	global_load_dwordx4 v[8:11], v200, s[46:47] offset:2048
	global_load_dwordx4 v[24:27], v200, s[48:49] offset:2048
	global_load_dwordx4 v[12:15], v200, s[46:47] offset:2112
	global_load_dwordx4 v[28:31], v200, s[48:49] offset:2112
	s_mov_b32 s10, 0
	s_mov_b32 s11, 0
	s_lshl_b32 s17, s10, 5
	s_cmp_lt_u32 s10, 8
	s_movk_i32 s18, 0x11ff
	s_cselect_b32 s18, 0xff, s18
	s_sub_i32 s18, s18, s17
	s_cmp_eq_u32 s6, 0
	s_cselect_b32 s17, s17, s18
	s_add_i32 s17, s17, s16
	v_add_u32_e32 v231, s17, v218
	v_lshl_add_u32 v226, v231, 9, v221
	v_lshl_add_u32 v227, v231, 11, v219
	v_lshl_add_u32 v228, v231, 11, v220
	v_lshlrev_b32_e32 v229, 3, v217
	v_lshl_add_u32 v229, v231, 11, v229
	v_lshlrev_b32_e32 v230, 6, v231
	global_load_dwordx4 v[88:91], v226, s[20:21]
	global_load_dwordx4 v[92:95], v226, s[20:21] offset:64
	global_load_dwordx4 v[96:99], v226, s[20:21] offset:256
	global_load_dwordx4 v[100:103], v226, s[20:21] offset:320
	global_load_dwordx2 v[104:105], v227, s[22:23] offset:0
	global_load_dwordx2 v[106:107], v227, s[22:23] offset:32
	global_load_dwordx2 v[108:109], v228, s[22:23] offset:0
	global_load_dwordx2 v[110:111], v228, s[22:23] offset:32
	global_load_dwordx2 v[112:113], v227, s[24:25] offset:0
	global_load_dwordx2 v[114:115], v227, s[24:25] offset:32
	global_load_dwordx2 v[116:117], v228, s[24:25] offset:0
	global_load_dwordx2 v[118:119], v228, s[24:25] offset:32
	global_load_dwordx2 v[120:121], v229, s[42:43]
	v_mov_b32_e32 v224, v222
	v_mov_b32_e32 v225, v223
	v_mov_b32_e32 v202, v230
	s_waitcnt vmcnt(0)
; __device__ __forceinline__ float sigm(float x) { return __builtin_amdgcn_rcpf(1.f + __expf(-x)); }
; template <int CTRL> __device__ __forceinline__ float dppf(float x) { return __builtin_bit_cast(float, __builtin_amdgcn_update_dpp(0, __builtin_bit_cast(int, x), CTRL, 0xF, 0xF, false)); }
; #define LDS_BAR() asm volatile("s_waitcnt lgkmcnt(0)\n\ts_barrier" ::: "memory")
; __device__ __forceinline__ void phase_rwkv_scan(const Fr& F, int jr) {
;     ...
;         for (int chunk = 0; chunk < TB / 64; ++chunk) {
; #pragma unroll
;             for (int hh = 0; hh < 2; ++hh) {
;                 const int hk = (ht0 + hh) * 16 + l15;
;                 f32x4 cw = {0.f, 0.f, 0.f, 0.f}, ca = {0.f, 0.f, 0.f, 0.f};
; #pragma unroll
;                 for (int kst = 0; kst < 2; ++kst) { cw = __builtin_amdgcn_mfma_f32_16x16x32_bf16(Aw[kst], Bw[hh][kst], cw, 0, 0, 0); ca = __builtin_amdgcn_mfma_f32_16x16x32_bf16(Aa[kst], Ba[hh][kst], ca, 0, 0, 0); }
; #pragma unroll
;                 for (int reg = 0; reg < 4; ++reg) { const int pp = pt * 16 + lq * 4 + reg;
;                     Wv[pp * 64 + hk] = __expf(-0.60653066f * sigm(w0v[hh] + cw[reg]));
;                     Av[pp * 64 + hk] = sigm(a0v[hh] + ca[reg]); }
;             }
;             LDS_BAR();
;             {
;                 const float kr[8] = {lo_bf(kw.x), hi_bf(kw.x), lo_bf(kw.y), hi_bf(kw.y), lo_bf(kw.z), hi_bf(kw.z), lo_bf(kw.w), hi_bf(kw.w)};
;                 const float rr[8] = {lo_bf(rw.x), hi_bf(rw.x), lo_bf(rw.y), hi_bf(rw.y), lo_bf(rw.z), hi_bf(rw.z), lo_bf(rw.w), hi_bf(rw.w)};
;                 float kq[8]; float ss = 0.f, bon = 0.f;
; #pragma unroll
;                 for (int i = 0; i < 8; ++i) { kq[i] = kr[i] * kkc[i]; ss += kq[i] * kq[i]; bon += rr[i] * kr[i] * rkc[i]; }
;                 ss += dppf<0xB1>(ss); ss += dppf<0x4E>(ss); ss += dppf<0x141>(ss); bon += dppf<0xB1>(bon); bon += dppf<0x4E>(bon); bon += dppf<0x141>(bon);
;                 if (s == 0 && half == 0 && j8 == 0) Bon[((size_t)b * TB + tokof(s, chunk * 64 + p2)) * 16 + h] = bon;
	v_mfma_f32_16x16x32_bf16 v[136:139], v[0:3], v[88:91], 0
	v_mfma_f32_16x16x32_bf16 v[136:139], v[4:7], v[92:95], v[136:139]
	v_mfma_f32_16x16x32_bf16 v[140:143], v[8:11], v[88:91], 0
	v_mfma_f32_16x16x32_bf16 v[140:143], v[12:15], v[92:95], v[140:143]
	v_mfma_f32_16x16x32_bf16 v[144:147], v[16:19], v[96:99], 0
	v_mfma_f32_16x16x32_bf16 v[144:147], v[20:23], v[100:103], v[144:147]
	v_mfma_f32_16x16x32_bf16 v[148:151], v[24:27], v[96:99], 0
	v_mfma_f32_16x16x32_bf16 v[148:151], v[28:31], v[100:103], v[148:151]
	v_lshlrev_b32_e32 v152, 16, v104
	v_and_b32_e32 v153, 0xffff0000, v104
	v_lshlrev_b32_e32 v154, 16, v105
	v_and_b32_e32 v155, 0xffff0000, v105
	v_lshlrev_b32_e32 v156, 16, v106
	v_and_b32_e32 v157, 0xffff0000, v106
	v_lshlrev_b32_e32 v158, 16, v107
	v_and_b32_e32 v159, 0xffff0000, v107
	v_lshlrev_b32_e32 v160, 16, v108
	v_and_b32_e32 v161, 0xffff0000, v108
	v_lshlrev_b32_e32 v162, 16, v109
	v_and_b32_e32 v163, 0xffff0000, v109
	v_lshlrev_b32_e32 v164, 16, v110
	v_and_b32_e32 v165, 0xffff0000, v110
	v_lshlrev_b32_e32 v166, 16, v111
	v_and_b32_e32 v167, 0xffff0000, v111
	v_lshlrev_b32_e32 v168, 16, v112
	v_and_b32_e32 v169, 0xffff0000, v112
	v_lshlrev_b32_e32 v170, 16, v113
	v_and_b32_e32 v171, 0xffff0000, v113
	v_lshlrev_b32_e32 v172, 16, v114
	v_and_b32_e32 v173, 0xffff0000, v114
	v_lshlrev_b32_e32 v174, 16, v115
	v_and_b32_e32 v175, 0xffff0000, v115
	v_lshlrev_b32_e32 v192, 16, v120
	v_and_b32_e32 v193, 0xffff0000, v120
	v_lshlrev_b32_e32 v194, 16, v121
	v_and_b32_e32 v195, 0xffff0000, v121
	v_pk_mul_f32 v[176:177], v[152:153], v[48:49]
	v_pk_mul_f32 v[178:179], v[154:155], v[50:51]
	v_pk_mul_f32 v[180:181], v[156:157], v[52:53]
	v_pk_mul_f32 v[182:183], v[158:159], v[54:55]
	v_pk_mul_f32 v[184:185], v[160:161], v[56:57]
	v_pk_mul_f32 v[186:187], v[162:163], v[58:59]
	v_pk_mul_f32 v[188:189], v[164:165], v[60:61]
	v_pk_mul_f32 v[190:191], v[166:167], v[62:63]
	v_pk_mul_f32 v[196:197], v[176:177], v[176:177]
	v_pk_mul_f32 v[198:199], v[178:179], v[178:179]
	v_pk_fma_f32 v[196:197], v[180:181], v[180:181], v[196:197]
	v_pk_fma_f32 v[198:199], v[182:183], v[182:183], v[198:199]
	v_pk_fma_f32 v[196:197], v[184:185], v[184:185], v[196:197]
	v_pk_fma_f32 v[198:199], v[186:187], v[186:187], v[198:199]
	v_pk_fma_f32 v[196:197], v[188:189], v[188:189], v[196:197]
	v_pk_fma_f32 v[198:199], v[190:191], v[190:191], v[198:199]
	s_nop 0
	v_pk_add_f32 v[196:197], v[196:197], v[198:199]
	s_cmp_eq_u32 s32, 0
	s_cbranch_scc1 .Lrw3_hnbc0
	v_mul_f32_e32 v208, v168, v152
	v_mul_f32_e32 v209, v169, v153
	v_mul_f32_e32 v210, v170, v154
	v_mul_f32_e32 v211, v171, v155
	v_mul_f32_e32 v234, v72, v208
	v_fmac_f32_e32 v234, v73, v209
	v_fmac_f32_e32 v234, v74, v210
	v_fmac_f32_e32 v234, v75, v211
	v_mul_f32_e32 v208, v172, v156
	v_mul_f32_e32 v209, v173, v157
	v_mul_f32_e32 v210, v174, v158
	v_mul_f32_e32 v211, v175, v159
	v_fmac_f32_e32 v234, v76, v208
	v_fmac_f32_e32 v234, v77, v209
	v_fmac_f32_e32 v234, v78, v210
	v_fmac_f32_e32 v234, v79, v211
	v_lshlrev_b32_e32 v204, 16, v116
	v_and_b32_e32 v205, 0xffff0000, v116
	v_lshlrev_b32_e32 v206, 16, v117
	v_and_b32_e32 v207, 0xffff0000, v117
	v_mul_f32_e32 v208, v204, v160
	v_mul_f32_e32 v209, v205, v161
	v_mul_f32_e32 v210, v206, v162
	v_mul_f32_e32 v211, v207, v163
	v_fmac_f32_e32 v234, v80, v208
	v_fmac_f32_e32 v234, v81, v209
	v_fmac_f32_e32 v234, v82, v210
	v_fmac_f32_e32 v234, v83, v211
	v_lshlrev_b32_e32 v204, 16, v118
	v_and_b32_e32 v205, 0xffff0000, v118
	v_lshlrev_b32_e32 v206, 16, v119
	v_and_b32_e32 v207, 0xffff0000, v119
	v_mul_f32_e32 v208, v204, v164
	v_mul_f32_e32 v209, v205, v165
	v_mul_f32_e32 v210, v206, v166
	v_mul_f32_e32 v211, v207, v167
	v_fmac_f32_e32 v234, v84, v208
	v_fmac_f32_e32 v234, v85, v209
	v_fmac_f32_e32 v234, v86, v210
	v_fmac_f32_e32 v234, v87, v211
